# v76 + SwiGLU epilogue leading vmcnt(0)->vmcnt(8) and layer-0 P4 norm loop-bottom vmcnt(0)->vmcnt(4) (stop waiting for stores / next-unit DMA prefetch)
# speedup vs baseline: 1.0080x; 1.0080x over previous
; #define G_STAGE(bufoff, gbase, voff) do { _Pragma("unroll") for (int _i = 0; _i < 2; ++_i) \
;         __builtin_amdgcn_global_load_lds((const unsigned*)((const char*)(gbase) + (voff)[_i]), (LAS unsigned*)(lds + (bufoff) + ldsw + _i * 8192), 16, 0, 0); } while (0)
; #define G_LDA(dst, b, h) do { _Pragma("unroll") for (int m = 0; m < 4; ++m) { const i32x4 _p0 = *(const LAS i32x4*)(lds + G_SA(b, h) + aoff + m * 2048), _p1 = *(const LAS i32x4*)(lds + G_SA(b, h) + aoff + m * 2048 + 1024); \
;         dst[m] = __builtin_shufflevector(_p0, _p1, 0, 1, 2, 3, 4, 5, 6, 7); } } while (0)
; #define G_LDB(dst, b, h) do { _Pragma("unroll") for (int n = 0; n < 2; ++n) { const i32x4 _p0 = *(const LAS i32x4*)(lds + G_SB(b, h) + boff + n * 2048), _p1 = *(const LAS i32x4*)(lds + G_SB(b, h) + boff + n * 2048 + 1024); \
;         dst[n] = __builtin_shufflevector(_p0, _p1, 0, 1, 2, 3, 4, 5, 6, 7); } } while (0)
; #define G_WAIT_V(n) asm volatile("s_waitcnt vmcnt(" #n ")" ::: "memory")
; #define G_WAIT_L(n) asm volatile("s_waitcnt lgkmcnt(" #n ")" ::: "memory")
; #define G_BAR __builtin_amdgcn_s_barrier()
; #define G_SCHED __builtin_amdgcn_sched_barrier(0)
; template <int NS, int MODE  , class Epi>
; __device__ __forceinline__ void gemm_phase(LAS unsigned char* lds, const Gemm g, const StaticOrder& S, const Epi& E) {
;     ...
;             if (G_SP2) {
;             G_LDB(B0, 0, 0); G_LDB(B1, 0, 1); G_SCHED; G_LDA(At, 0, 0); G_STAGE(G_SA(1, 1), a1 + hstep, voffA);
;             G_WAIT_V(8); G_WAIT_L(0); G_BAR; G_MMA(0, 0, At, B0); G_MMA(0, 1, At, B1); G_BAR; G_SCHED;
;             G_LDA(At, 0, 1); G_STAGE(G_SB(0, 0), b2, voffB); G_STAGE(G_SB(0, 1), b2 + hstep, voffB); G_STAGE(G_SA(0, 0), a2, voffA);
;             G_WAIT_V(8); G_WAIT_L(0); G_BAR; G_MMA(1, 0, At, B0); G_MMA(1, 1, At, B1); G_BAR; G_SCHED;
.LBB0_444:
	s_add_i32 s21, 0, 0x10000
	s_add_i32 s30, 0, 0x14000
	v_add_u32_e32 v132, s21, v190
	v_add_u32_e32 v136, s30, v190
	ds_read_b128 v[160:163], v132
	ds_read_b128 v[148:151], v132 offset:1024
	ds_read_b128 v[156:159], v132 offset:2048
	ds_read_b128 v[152:155], v132 offset:3072
	ds_read_b128 v[144:147], v136
	ds_read_b128 v[132:135], v136 offset:1024
	ds_read_b128 v[140:143], v136 offset:2048
	ds_read_b128 v[136:139], v136 offset:3072
	v_lshl_add_u64 v[176:177], v[174:175], 0, s[60:61]
	s_add_i32 m0, s19, 0xc000
	ds_read_b128 v[202:205], v193
	ds_read_b128 v[206:209], v193 offset:1024
	ds_read_b128 v[210:213], v193 offset:2048
	ds_read_b128 v[214:217], v193 offset:3072
	ds_read_b128 v[218:221], v193 offset:4096
	ds_read_b128 v[222:225], v193 offset:5120
	ds_read_b128 v[226:229], v193 offset:6144
	ds_read_b128 v[242:245], v193 offset:7168
	global_load_lds_dwordx4 v[176:177], off
	v_lshl_add_u64 v[176:177], v[186:187], 0, s[60:61]
	s_add_i32 m0, s19, 0xe000
	s_nop 0
	global_load_lds_dwordx4 v[176:177], off
	s_waitcnt vmcnt(8)
	s_waitcnt lgkmcnt(0)
	s_barrier
	s_nop 0
	s_waitcnt lgkmcnt(0)
	v_mfma_i32_16x16x64_i8 v[128:131], v[160:163], v[202:205], v[128:131]
	v_mfma_i32_16x16x64_i8 v[120:123], v[156:159], v[202:205], v[120:123]
	v_mfma_i32_16x16x64_i8 v[112:115], v[160:163], v[210:213], v[112:115]
	v_mfma_i32_16x16x64_i8 v[104:107], v[156:159], v[210:213], v[104:107]
	v_mfma_i32_16x16x64_i8 v[96:99], v[160:163], v[218:221], v[96:99]
	v_mfma_i32_16x16x64_i8 v[88:91], v[156:159], v[218:221], v[88:91]
	v_mfma_i32_16x16x64_i8 v[80:83], v[160:163], v[226:229], v[80:83]
	v_mfma_i32_16x16x64_i8 v[72:75], v[156:159], v[226:229], v[72:75]
	s_nop 0
	v_mfma_i32_16x16x64_i8 v[128:131], v[148:151], v[206:209], v[128:131]
	v_mfma_i32_16x16x64_i8 v[120:123], v[152:155], v[206:209], v[120:123]
	v_mfma_i32_16x16x64_i8 v[112:115], v[148:151], v[214:217], v[112:115]
	v_mfma_i32_16x16x64_i8 v[104:107], v[152:155], v[214:217], v[104:107]
	v_mfma_i32_16x16x64_i8 v[96:99], v[148:151], v[222:225], v[96:99]
	v_mfma_i32_16x16x64_i8 v[88:91], v[152:155], v[222:225], v[88:91]
	v_mfma_i32_16x16x64_i8 v[80:83], v[148:151], v[242:245], v[80:83]
	v_mfma_i32_16x16x64_i8 v[72:75], v[152:155], v[242:245], v[72:75]
	s_nop 0
	s_nop 0
	v_mfma_i32_16x16x64_i8 v[124:127], v[144:147], v[202:205], v[124:127]
	v_mfma_i32_16x16x64_i8 v[116:119], v[140:143], v[202:205], v[116:119]
	v_mfma_i32_16x16x64_i8 v[108:111], v[144:147], v[210:213], v[108:111]
	v_mfma_i32_16x16x64_i8 v[100:103], v[140:143], v[210:213], v[100:103]
	v_mfma_i32_16x16x64_i8 v[92:95], v[144:147], v[218:221], v[92:95]
	v_mfma_i32_16x16x64_i8 v[84:87], v[140:143], v[218:221], v[84:87]
	v_mfma_i32_16x16x64_i8 v[76:79], v[144:147], v[226:229], v[76:79]
	v_mfma_i32_16x16x64_i8 v[68:71], v[140:143], v[226:229], v[68:71]
	s_nop 0
	v_mfma_i32_16x16x64_i8 v[124:127], v[132:135], v[206:209], v[124:127]
	v_mfma_i32_16x16x64_i8 v[116:119], v[136:139], v[206:209], v[116:119]
	v_mfma_i32_16x16x64_i8 v[108:111], v[132:135], v[214:217], v[108:111]
	v_mfma_i32_16x16x64_i8 v[100:103], v[136:139], v[214:217], v[100:103]
	v_mfma_i32_16x16x64_i8 v[92:95], v[132:135], v[222:225], v[92:95]
	v_mfma_i32_16x16x64_i8 v[84:87], v[136:139], v[222:225], v[84:87]
	v_mfma_i32_16x16x64_i8 v[76:79], v[132:135], v[242:245], v[76:79]
	v_mfma_i32_16x16x64_i8 v[68:71], v[136:139], v[242:245], v[68:71]
	s_nop 0
	s_barrier
	s_add_i32 s21, s21, s18
	v_lshl_add_u64 v[176:177], s[68:69], 0, v[2:3]
	s_mov_b32 m0, s21
	ds_read_b128 v[202:205], v193 offset:16384
	ds_read_b128 v[206:209], v193 offset:17408
	ds_read_b128 v[210:213], v193 offset:18432
	ds_read_b128 v[214:217], v193 offset:19456
	ds_read_b128 v[218:221], v193 offset:20480
	ds_read_b128 v[222:225], v193 offset:21504
	ds_read_b128 v[226:229], v193 offset:22528
	ds_read_b128 v[242:245], v193 offset:23552
	global_load_lds_dwordx4 v[176:177], off
	s_add_i32 m0, s21, 0x2000
	s_add_u32 s24, s68, 0x40000
	v_lshl_add_u64 v[176:177], s[68:69], 0, v[164:165]
	s_addc_u32 s25, s69, 0
	s_add_i32 s21, s30, s18
	global_load_lds_dwordx4 v[176:177], off
	v_lshl_add_u64 v[176:177], s[24:25], 0, v[2:3]
	s_mov_b32 m0, s21
	s_nop 0
	global_load_lds_dwordx4 v[176:177], off
	v_lshl_add_u64 v[176:177], s[24:25], 0, v[164:165]
	s_add_i32 m0, s21, 0x2000
	s_nop 0
	global_load_lds_dwordx4 v[176:177], off
	v_lshl_add_u64 v[176:177], s[66:67], 0, v[168:169]
	s_mov_b32 m0, s19
	s_nop 0
	global_load_lds_dwordx4 v[176:177], off
	v_lshl_add_u64 v[176:177], s[66:67], 0, v[166:167]
	s_mov_b32 m0, s29
	s_nop 0
	global_load_lds_dwordx4 v[176:177], off
	s_waitcnt vmcnt(8)
	s_waitcnt lgkmcnt(0)
	s_barrier
; #define G_STAGE(bufoff, gbase, voff) do { _Pragma("unroll") for (int _i = 0; _i < 2; ++_i) \
;         __builtin_amdgcn_global_load_lds((const unsigned*)((const char*)(gbase) + (voff)[_i]), (LAS unsigned*)(lds + (bufoff) + ldsw + _i * 8192), 16, 0, 0); } while (0)
; #define G_LDA(dst, b, h) do { _Pragma("unroll") for (int m = 0; m < 4; ++m) { const i32x4 _p0 = *(const LAS i32x4*)(lds + G_SA(b, h) + aoff + m * 2048), _p1 = *(const LAS i32x4*)(lds + G_SA(b, h) + aoff + m * 2048 + 1024); \
;         dst[m] = __builtin_shufflevector(_p0, _p1, 0, 1, 2, 3, 4, 5, 6, 7); } } while (0)
; #define G_LDB(dst, b, h) do { _Pragma("unroll") for (int n = 0; n < 2; ++n) { const i32x4 _p0 = *(const LAS i32x4*)(lds + G_SB(b, h) + boff + n * 2048), _p1 = *(const LAS i32x4*)(lds + G_SB(b, h) + boff + n * 2048 + 1024); \
;         dst[n] = __builtin_shufflevector(_p0, _p1, 0, 1, 2, 3, 4, 5, 6, 7); } } while (0)
; #define G_WAIT_V(n) asm volatile("s_waitcnt vmcnt(" #n ")" ::: "memory")
; #define G_WAIT_L(n) asm volatile("s_waitcnt lgkmcnt(" #n ")" ::: "memory")
; #define G_BAR __builtin_amdgcn_s_barrier()
; #define G_SCHED __builtin_amdgcn_sched_barrier(0)
; template <int NS, int MODE  , class Epi>
; __device__ __forceinline__ void gemm_phase(LAS unsigned char* lds, const Gemm g, const StaticOrder& S, const Epi& E) {
;     ...
;             G_WAIT_V(8); G_WAIT_L(0); G_BAR; G_MMA(1, 0, At, B0); G_MMA(1, 1, At, B1); G_BAR; G_SCHED;
;             G_LDB(B0, 1, 0); G_LDB(B1, 1, 1); G_SCHED; G_LDA(At, 1, 0); G_STAGE(G_SA(0, 1), a2 + hstep, voffA);
;             G_WAIT_V(8); G_WAIT_L(0); G_BAR; G_MMA(0, 0, At, B0); G_MMA(0, 1, At, B1); G_BAR; G_SCHED;
;             G_LDA(At, 1, 1); G_STAGE(G_SB(1, 0), b3, voffB); G_STAGE(G_SB(1, 1), b3 + hstep, voffB); G_STAGE(G_SA(1, 0), a3, voffA);
	s_nop 0
	s_waitcnt lgkmcnt(0)
	v_mfma_i32_16x16x64_i8 v[64:67], v[160:163], v[202:205], v[64:67]
	v_mfma_i32_16x16x64_i8 v[56:59], v[156:159], v[202:205], v[56:59]
	v_mfma_i32_16x16x64_i8 v[48:51], v[160:163], v[210:213], v[48:51]
	v_mfma_i32_16x16x64_i8 v[40:43], v[156:159], v[210:213], v[40:43]
	v_mfma_i32_16x16x64_i8 v[32:35], v[160:163], v[218:221], v[32:35]
	v_mfma_i32_16x16x64_i8 v[24:27], v[156:159], v[218:221], v[24:27]
	v_mfma_i32_16x16x64_i8 v[16:19], v[160:163], v[226:229], v[16:19]
	v_mfma_i32_16x16x64_i8 v[8:11], v[156:159], v[226:229], v[8:11]
	s_nop 0
	v_mfma_i32_16x16x64_i8 v[64:67], v[148:151], v[206:209], v[64:67]
	v_mfma_i32_16x16x64_i8 v[56:59], v[152:155], v[206:209], v[56:59]
	v_mfma_i32_16x16x64_i8 v[48:51], v[148:151], v[214:217], v[48:51]
	v_mfma_i32_16x16x64_i8 v[40:43], v[152:155], v[214:217], v[40:43]
	v_mfma_i32_16x16x64_i8 v[32:35], v[148:151], v[222:225], v[32:35]
	v_mfma_i32_16x16x64_i8 v[24:27], v[152:155], v[222:225], v[24:27]
	v_mfma_i32_16x16x64_i8 v[16:19], v[148:151], v[242:245], v[16:19]
	v_mfma_i32_16x16x64_i8 v[8:11], v[152:155], v[242:245], v[8:11]
	s_nop 0
	s_nop 0
	v_mfma_i32_16x16x64_i8 v[60:63], v[144:147], v[202:205], v[60:63]
	v_mfma_i32_16x16x64_i8 v[52:55], v[140:143], v[202:205], v[52:55]
	v_mfma_i32_16x16x64_i8 v[44:47], v[144:147], v[210:213], v[44:47]
	v_mfma_i32_16x16x64_i8 v[36:39], v[140:143], v[210:213], v[36:39]
	v_mfma_i32_16x16x64_i8 v[28:31], v[144:147], v[218:221], v[28:31]
	v_mfma_i32_16x16x64_i8 v[20:23], v[140:143], v[218:221], v[20:23]
	v_mfma_i32_16x16x64_i8 v[12:15], v[144:147], v[226:229], v[12:15]
	v_mfma_i32_16x16x64_i8 v[4:7], v[140:143], v[226:229], v[4:7]
	s_nop 0
	v_mfma_i32_16x16x64_i8 v[60:63], v[132:135], v[206:209], v[60:63]
	v_mfma_i32_16x16x64_i8 v[52:55], v[136:139], v[206:209], v[52:55]
	v_mfma_i32_16x16x64_i8 v[44:47], v[132:135], v[214:217], v[44:47]
	v_mfma_i32_16x16x64_i8 v[36:39], v[136:139], v[214:217], v[36:39]
	v_mfma_i32_16x16x64_i8 v[28:31], v[132:135], v[222:225], v[28:31]
	v_mfma_i32_16x16x64_i8 v[20:23], v[136:139], v[222:225], v[20:23]
	v_mfma_i32_16x16x64_i8 v[12:15], v[132:135], v[242:245], v[12:15]
	v_mfma_i32_16x16x64_i8 v[4:7], v[136:139], v[242:245], v[4:7]
	s_nop 0
	s_barrier
	s_add_i32 s21, 0, 0x18000
	s_add_i32 s30, 0, 0x1c000
	v_add_u32_e32 v144, s21, v190
	v_add_u32_e32 v160, s30, v190
	ds_read_b128 v[132:135], v144
	ds_read_b128 v[136:139], v144 offset:1024
	ds_read_b128 v[140:143], v144 offset:2048
	ds_read_b128 v[144:147], v144 offset:3072
	ds_read_b128 v[148:151], v160
	ds_read_b128 v[152:155], v160 offset:1024
	ds_read_b128 v[156:159], v160 offset:2048
	ds_read_b128 v[160:163], v160 offset:3072
	s_add_u32 s24, s66, 0x40000
	s_addc_u32 s25, s67, 0
	s_mov_b32 m0, s56
	v_lshl_add_u64 v[176:177], s[24:25], 0, v[168:169]
	ds_read_b128 v[202:205], v193 offset:32768
	ds_read_b128 v[206:209], v193 offset:33792
	ds_read_b128 v[210:213], v193 offset:34816
	ds_read_b128 v[214:217], v193 offset:35840
	ds_read_b128 v[218:221], v193 offset:36864
	ds_read_b128 v[222:225], v193 offset:37888
	ds_read_b128 v[226:229], v193 offset:38912
	ds_read_b128 v[242:245], v193 offset:39936
	global_load_lds_dwordx4 v[176:177], off
	v_lshl_add_u64 v[176:177], s[24:25], 0, v[166:167]
	s_mov_b32 m0, s70
	s_nop 0
	global_load_lds_dwordx4 v[176:177], off
	s_waitcnt vmcnt(8)
	s_waitcnt lgkmcnt(0)
	s_barrier
	s_nop 0
	s_waitcnt lgkmcnt(0)
	v_mfma_i32_16x16x64_i8 v[128:131], v[132:135], v[202:205], v[128:131]
	v_mfma_i32_16x16x64_i8 v[120:123], v[140:143], v[202:205], v[120:123]
	v_mfma_i32_16x16x64_i8 v[112:115], v[132:135], v[210:213], v[112:115]
	v_mfma_i32_16x16x64_i8 v[104:107], v[140:143], v[210:213], v[104:107]
	v_mfma_i32_16x16x64_i8 v[96:99], v[132:135], v[218:221], v[96:99]
	v_mfma_i32_16x16x64_i8 v[88:91], v[140:143], v[218:221], v[88:91]
	v_mfma_i32_16x16x64_i8 v[80:83], v[132:135], v[226:229], v[80:83]
	v_mfma_i32_16x16x64_i8 v[72:75], v[140:143], v[226:229], v[72:75]
	s_nop 0
	v_mfma_i32_16x16x64_i8 v[128:131], v[136:139], v[206:209], v[128:131]
	v_mfma_i32_16x16x64_i8 v[120:123], v[144:147], v[206:209], v[120:123]
	v_mfma_i32_16x16x64_i8 v[112:115], v[136:139], v[214:217], v[112:115]
	v_mfma_i32_16x16x64_i8 v[104:107], v[144:147], v[214:217], v[104:107]
	v_mfma_i32_16x16x64_i8 v[96:99], v[136:139], v[222:225], v[96:99]
	v_mfma_i32_16x16x64_i8 v[88:91], v[144:147], v[222:225], v[88:91]
	v_mfma_i32_16x16x64_i8 v[80:83], v[136:139], v[242:245], v[80:83]
	v_mfma_i32_16x16x64_i8 v[72:75], v[144:147], v[242:245], v[72:75]
	s_nop 0
	s_nop 0
	v_mfma_i32_16x16x64_i8 v[124:127], v[148:151], v[202:205], v[124:127]
	v_mfma_i32_16x16x64_i8 v[116:119], v[156:159], v[202:205], v[116:119]
	v_mfma_i32_16x16x64_i8 v[108:111], v[148:151], v[210:213], v[108:111]
	v_mfma_i32_16x16x64_i8 v[100:103], v[156:159], v[210:213], v[100:103]
	v_mfma_i32_16x16x64_i8 v[92:95], v[148:151], v[218:221], v[92:95]
	v_mfma_i32_16x16x64_i8 v[84:87], v[156:159], v[218:221], v[84:87]
	v_mfma_i32_16x16x64_i8 v[76:79], v[148:151], v[226:229], v[76:79]
	v_mfma_i32_16x16x64_i8 v[68:71], v[156:159], v[226:229], v[68:71]
	s_nop 0
	v_mfma_i32_16x16x64_i8 v[124:127], v[152:155], v[206:209], v[124:127]
	v_mfma_i32_16x16x64_i8 v[116:119], v[160:163], v[206:209], v[116:119]
	v_mfma_i32_16x16x64_i8 v[108:111], v[152:155], v[214:217], v[108:111]
	v_mfma_i32_16x16x64_i8 v[100:103], v[160:163], v[214:217], v[100:103]
	v_mfma_i32_16x16x64_i8 v[92:95], v[152:155], v[222:225], v[92:95]
	v_mfma_i32_16x16x64_i8 v[84:87], v[160:163], v[222:225], v[84:87]
	v_mfma_i32_16x16x64_i8 v[76:79], v[152:155], v[242:245], v[76:79]
	v_mfma_i32_16x16x64_i8 v[68:71], v[160:163], v[242:245], v[68:71]
	s_nop 0
	s_barrier
; #define G_STAGE(bufoff, gbase, voff) do { _Pragma("unroll") for (int _i = 0; _i < 2; ++_i) \
;         __builtin_amdgcn_global_load_lds((const unsigned*)((const char*)(gbase) + (voff)[_i]), (LAS unsigned*)(lds + (bufoff) + ldsw + _i * 8192), 16, 0, 0); } while (0)
; #define G_LDA(dst, b, h) do { _Pragma("unroll") for (int m = 0; m < 4; ++m) { const i32x4 _p0 = *(const LAS i32x4*)(lds + G_SA(b, h) + aoff + m * 2048), _p1 = *(const LAS i32x4*)(lds + G_SA(b, h) + aoff + m * 2048 + 1024); \
;         dst[m] = __builtin_shufflevector(_p0, _p1, 0, 1, 2, 3, 4, 5, 6, 7); } } while (0)
; #define G_WAIT_V(n) asm volatile("s_waitcnt vmcnt(" #n ")" ::: "memory")
; #define G_WAIT_L(n) asm volatile("s_waitcnt lgkmcnt(" #n ")" ::: "memory")
; #define G_BAR __builtin_amdgcn_s_barrier()
; #define G_SCHED __builtin_amdgcn_sched_barrier(0)
; template <int NS, int MODE  , class Epi>
; __device__ __forceinline__ void gemm_phase(LAS unsigned char* lds, const Gemm g, const StaticOrder& S, const Epi& E) {
;     ...
;             G_LDA(At, 1, 1); G_STAGE(G_SB(1, 0), b3, voffB); G_STAGE(G_SB(1, 1), b3 + hstep, voffB); G_STAGE(G_SA(1, 0), a3, voffA);
;             G_WAIT_V(8); G_WAIT_L(0); G_BAR; G_MMA(1, 0, At, B0); G_MMA(1, 1, At, B1); G_BAR; G_SCHED;
	s_add_i32 s21, s21, s18
	v_lshl_add_u64 v[176:177], s[64:65], 0, v[2:3]
	s_mov_b32 m0, s21
	ds_read_b128 v[202:205], v193 offset:49152
	ds_read_b128 v[206:209], v193 offset:50176
	ds_read_b128 v[210:213], v193 offset:51200
	ds_read_b128 v[214:217], v193 offset:52224
	ds_read_b128 v[218:221], v193 offset:53248
	ds_read_b128 v[222:225], v193 offset:54272
	ds_read_b128 v[226:229], v193 offset:55296
	ds_read_b128 v[242:245], v193 offset:56320
	global_load_lds_dwordx4 v[176:177], off
	s_add_i32 m0, s21, 0x2000
	s_add_u32 s24, s64, 0x40000
	v_lshl_add_u64 v[176:177], s[64:65], 0, v[164:165]
	s_addc_u32 s25, s65, 0
	s_add_i32 s21, s30, s18
	global_load_lds_dwordx4 v[176:177], off
	v_lshl_add_u64 v[176:177], s[24:25], 0, v[2:3]
	s_mov_b32 m0, s21
	s_nop 0
	global_load_lds_dwordx4 v[176:177], off
	v_lshl_add_u64 v[176:177], s[24:25], 0, v[164:165]
	s_add_i32 m0, s21, 0x2000
	s_nop 0
	global_load_lds_dwordx4 v[176:177], off
	v_lshl_add_u64 v[176:177], s[62:63], 0, v[168:169]
	s_mov_b32 m0, s71
	s_nop 0
	global_load_lds_dwordx4 v[176:177], off
	v_lshl_add_u64 v[176:177], s[62:63], 0, v[166:167]
	s_mov_b32 m0, s72
	s_nop 0
	global_load_lds_dwordx4 v[176:177], off
	s_waitcnt vmcnt(8)
	s_waitcnt lgkmcnt(0)
	s_barrier
	s_nop 0
	s_waitcnt lgkmcnt(0)
	v_mfma_i32_16x16x64_i8 v[64:67], v[132:135], v[202:205], v[64:67]
	v_mfma_i32_16x16x64_i8 v[56:59], v[140:143], v[202:205], v[56:59]
	v_mfma_i32_16x16x64_i8 v[48:51], v[132:135], v[210:213], v[48:51]
	v_mfma_i32_16x16x64_i8 v[40:43], v[140:143], v[210:213], v[40:43]
	v_mfma_i32_16x16x64_i8 v[32:35], v[132:135], v[218:221], v[32:35]
	v_mfma_i32_16x16x64_i8 v[24:27], v[140:143], v[218:221], v[24:27]
	v_mfma_i32_16x16x64_i8 v[16:19], v[132:135], v[226:229], v[16:19]
	v_mfma_i32_16x16x64_i8 v[8:11], v[140:143], v[226:229], v[8:11]
	s_nop 0
	v_mfma_i32_16x16x64_i8 v[64:67], v[136:139], v[206:209], v[64:67]
	v_mfma_i32_16x16x64_i8 v[56:59], v[144:147], v[206:209], v[56:59]
	v_mfma_i32_16x16x64_i8 v[48:51], v[136:139], v[214:217], v[48:51]
	v_mfma_i32_16x16x64_i8 v[40:43], v[144:147], v[214:217], v[40:43]
	v_mfma_i32_16x16x64_i8 v[32:35], v[136:139], v[222:225], v[32:35]
	v_mfma_i32_16x16x64_i8 v[24:27], v[144:147], v[222:225], v[24:27]
	v_mfma_i32_16x16x64_i8 v[16:19], v[136:139], v[242:245], v[16:19]
	v_mfma_i32_16x16x64_i8 v[8:11], v[144:147], v[242:245], v[8:11]
	s_nop 0
	s_nop 0
	v_mfma_i32_16x16x64_i8 v[60:63], v[148:151], v[202:205], v[60:63]
	v_mfma_i32_16x16x64_i8 v[52:55], v[156:159], v[202:205], v[52:55]
	v_mfma_i32_16x16x64_i8 v[44:47], v[148:151], v[210:213], v[44:47]
	v_mfma_i32_16x16x64_i8 v[36:39], v[156:159], v[210:213], v[36:39]
	v_mfma_i32_16x16x64_i8 v[28:31], v[148:151], v[218:221], v[28:31]
	v_mfma_i32_16x16x64_i8 v[20:23], v[156:159], v[218:221], v[20:23]
	v_mfma_i32_16x16x64_i8 v[12:15], v[148:151], v[226:229], v[12:15]
	v_mfma_i32_16x16x64_i8 v[4:7], v[156:159], v[226:229], v[4:7]
	s_nop 0
	v_mfma_i32_16x16x64_i8 v[60:63], v[152:155], v[206:209], v[60:63]
	v_mfma_i32_16x16x64_i8 v[52:55], v[160:163], v[206:209], v[52:55]
	v_mfma_i32_16x16x64_i8 v[44:47], v[152:155], v[214:217], v[44:47]
	v_mfma_i32_16x16x64_i8 v[36:39], v[160:163], v[214:217], v[36:39]
	v_mfma_i32_16x16x64_i8 v[28:31], v[152:155], v[222:225], v[28:31]
	v_mfma_i32_16x16x64_i8 v[20:23], v[160:163], v[222:225], v[20:23]
	v_mfma_i32_16x16x64_i8 v[12:15], v[152:155], v[242:245], v[12:15]
	v_mfma_i32_16x16x64_i8 v[4:7], v[160:163], v[242:245], v[4:7]
	s_nop 0
	s_barrier
	s_add_i32 s13, s13, 2
	s_add_u32 s60, s60, 0x100
	s_addc_u32 s61, s61, 0
	s_cmp_gt_u32 s13, 13
	s_cbranch_scc1 .LBB0_447

;     __device__ __forceinline__ void operator()(const f32x4 (&acc)[2][2][4][2], const Unit& u, int wr, int wc, int fr, int fq, const float (&pre)[8]) const {
;         const int row0 = u.pm * BM + wr * 64 + fr, col0 = u.pn * 128 + wc * 32 + 8 * fq;
; #pragma unroll
;         for (int ai = 0; ai < 2; ++ai)
; #pragma unroll
;             for (int m = 0; m < 4; ++m) {
;                 const size_t off = (size_t)(row0 + ai * HALF + m * 16) * DFF + col0;
;                 const float rsc = pre[ai * 4 + m];
;                 const float ka = us * rsc * (1.0f / KREP), ke = ka * -1.4426950408889634f, K = ka * ka * (h8 ? SH8 : SA);
;                 f32x2 hv[4];
; #pragma unroll
;                 for (int n = 0; n < 2; ++n)
; #pragma unroll
;                     for (int jp = 0; jp < 2; ++jp) {
;                         const float fa0 = acc[ai][0][m][n][2 * jp], fa1 = acc[ai][0][m][n][2 * jp + 1], fb0 = acc[ai][1][m][n][2 * jp], fb1 = acc[ai][1][m][n][2 * jp + 1];
;                         const f32x2 A = iacc ? (f32x2){(float)__float_as_int(fa0), (float)__float_as_int(fa1)} : (f32x2){fa0, fa1};
;                         const f32x2 B = iacc ? (f32x2){(float)__float_as_int(fb0), (float)__float_as_int(fb1)} : (f32x2){fb0, fb1};
;                         const f32x2 X = A * ke;
;                         const f32x2 D = (f32x2){__builtin_amdgcn_exp2f(X[0]), __builtin_amdgcn_exp2f(X[1])} + 1.0f;
;                         const f32x2 R = {__builtin_amdgcn_rcpf(D[0]), __builtin_amdgcn_rcpf(D[1])};
;                         hv[n * 2 + jp] = ((A * B) * R) * K;
;                     }
;                 f16x8 hi, lo;
;                 if (h8) {
;                     int p0 = __builtin_amdgcn_cvt_pk_fp8_f32(hv[0][0], hv[0][1], 0, false); p0 = __builtin_amdgcn_cvt_pk_fp8_f32(hv[1][0], hv[1][1], p0, true);
;                     int p1 = __builtin_amdgcn_cvt_pk_fp8_f32(hv[2][0], hv[2][1], 0, false); p1 = __builtin_amdgcn_cvt_pk_fp8_f32(hv[3][0], hv[3][1], p1, true);
;                     *(u32x2v*)((unsigned char*)Hh + off) = (u32x2v){(unsigned)p0, (unsigned)p1}; }
; template <int NS, int MODE  , class Epi>
; __device__ __forceinline__ void gemm_phase(LAS unsigned char* lds, const Gemm g, const StaticOrder& S, const Epi& E) {
;     ...
;         if constexpr (MODE != 0) asm volatile("s_nop 7\n\ts_nop 7\n\ts_nop 7" ::: "memory");
.LBB0_449:
	v_cvt_f32_i32_e32 v129, v129
	v_cvt_f32_i32_e32 v128, v128
	v_cvt_f32_i32_e32 v125, v125
	v_cvt_f32_i32_e32 v124, v124
	v_cvt_f32_i32_e32 v131, v131
	v_cvt_f32_i32_e32 v130, v130
	s_waitcnt vmcnt(8)
	v_mul_f32_e32 v135, v188, v200
	v_mul_f32_e32 v136, 0xbfb8aa3b, v135
	v_pk_mul_f32 v[138:139], v[136:137], v[128:129] op_sel_hi:[0,1]
	v_pk_mul_f32 v[124:125], v[128:129], v[124:125]
	v_pk_mul_f32 v[128:129], v[136:137], v[130:131] op_sel_hi:[0,1]
	v_exp_f32_e32 v128, v128
	v_exp_f32_e32 v129, v129
	v_cvt_f32_i32_e32 v127, v127
	v_cvt_f32_i32_e32 v126, v126
	v_cvt_f32_i32_e32 v121, v121
	v_cvt_f32_i32_e32 v120, v120
	v_pk_add_f32 v[128:129], v[128:129], 1.0 op_sel_hi:[1,0]
	v_pk_mul_f32 v[126:127], v[130:131], v[126:127]
	v_cvt_f32_i32_e32 v117, v117
	v_pk_mul_f32 v[130:131], v[136:137], v[120:121] op_sel_hi:[0,1]
	v_cvt_f32_i32_e32 v116, v116
	v_cvt_f32_i32_e32 v123, v123
	v_cvt_f32_i32_e32 v122, v122
	v_exp_f32_e32 v138, v138
	v_exp_f32_e32 v139, v139
	v_rcp_f32_e32 v128, v128
	v_rcp_f32_e32 v129, v129
	v_exp_f32_e32 v130, v130
	v_exp_f32_e32 v131, v131
	v_pk_mul_f32 v[116:117], v[120:121], v[116:117]
	v_pk_mul_f32 v[120:121], v[136:137], v[122:123] op_sel_hi:[0,1]
	v_pk_add_f32 v[138:139], v[138:139], 1.0 op_sel_hi:[1,0]
	v_pk_mul_f32 v[126:127], v[128:129], v[126:127]
	v_pk_add_f32 v[128:129], v[130:131], 1.0 op_sel_hi:[1,0]
	v_exp_f32_e32 v120, v120
	v_exp_f32_e32 v121, v121
	v_rcp_f32_e32 v138, v138
	v_rcp_f32_e32 v139, v139
	v_rcp_f32_e32 v128, v128
	v_rcp_f32_e32 v129, v129
	v_cvt_f32_i32_e32 v119, v119
	v_cvt_f32_i32_e32 v118, v118
	v_mul_f32_e32 v135, v135, v135
	v_pk_add_f32 v[120:121], v[120:121], 1.0 op_sel_hi:[1,0]
	v_mul_f32_e32 v140, 4.0, v135
	v_pk_mul_f32 v[124:125], v[138:139], v[124:125]
	v_pk_mul_f32 v[116:117], v[128:129], v[116:117]
	v_rcp_f32_e32 v120, v120
	v_rcp_f32_e32 v121, v121
	v_pk_mul_f32 v[124:125], v[140:141], v[124:125] op_sel_hi:[0,1]
	v_pk_mul_f32 v[116:117], v[140:141], v[116:117] op_sel_hi:[0,1]
	v_pk_mul_f32 v[118:119], v[122:123], v[118:119]
	v_mov_b32_e32 v122, v3
	v_mov_b32_e32 v123, v3
	v_cvt_pk_fp8_f32 v122, v124, v125
	v_cvt_pk_fp8_f32 v123, v116, v117
	v_pk_mul_f32 v[116:117], v[120:121], v[118:119]
	v_lshl_add_u32 v134, s3, 8, v189
	v_lshl_or_b32 v132, s2, 7, v191
	v_pk_mul_f32 v[126:127], v[140:141], v[126:127] op_sel_hi:[0,1]
	v_pk_mul_f32 v[116:117], v[140:141], v[116:117] op_sel_hi:[0,1]
	v_readlane_b32 s2, v247, 14
	v_cvt_pk_fp8_f32 v122, v126, v127 op_sel:[0,0,1]
	v_cvt_pk_fp8_f32 v123, v116, v117 op_sel:[0,0,1]
	v_readlane_b32 s3, v247, 15
	s_movk_i32 s4, 0x1600
	v_ashrrev_i32_e32 v133, 31, v132
	v_mov_b64_e32 v[116:117], s[2:3]
	v_mad_i64_i32 v[118:119], s[2:3], v134, s4, v[116:117]
	v_cvt_f32_i32_e32 v113, v113
	v_cvt_f32_i32_e32 v112, v112
	v_cvt_f32_i32_e32 v109, v109
	v_cvt_f32_i32_e32 v108, v108
	v_cvt_f32_i32_e32 v115, v115
	v_cvt_f32_i32_e32 v114, v114
	v_lshl_add_u64 v[118:119], v[118:119], 0, v[132:133]
	s_nop 7
	s_nop 7
	s_nop 7
	global_store_dwordx2 v[118:119], v[122:123], off
	v_mul_f32_e32 v122, v188, v199
	v_or_b32_e32 v119, 16, v134
	v_mul_f32_e32 v118, 0xbfb8aa3b, v122
	v_pk_mul_f32 v[120:121], v[118:119], v[112:113] op_sel_hi:[0,1]
	v_pk_mul_f32 v[108:109], v[112:113], v[108:109]
	v_pk_mul_f32 v[112:113], v[118:119], v[114:115] op_sel_hi:[0,1]
	v_exp_f32_e32 v112, v112
	v_exp_f32_e32 v113, v113
	v_cvt_f32_i32_e32 v111, v111
	v_cvt_f32_i32_e32 v110, v110
	v_cvt_f32_i32_e32 v105, v105
	v_cvt_f32_i32_e32 v104, v104
	v_pk_add_f32 v[112:113], v[112:113], 1.0 op_sel_hi:[1,0]
	v_pk_mul_f32 v[110:111], v[114:115], v[110:111]
	v_cvt_f32_i32_e32 v101, v101
	v_pk_mul_f32 v[114:115], v[118:119], v[104:105] op_sel_hi:[0,1]
	v_cvt_f32_i32_e32 v100, v100
	v_cvt_f32_i32_e32 v107, v107
	v_cvt_f32_i32_e32 v106, v106
	v_exp_f32_e32 v120, v120
	v_exp_f32_e32 v121, v121
	v_rcp_f32_e32 v112, v112
	v_rcp_f32_e32 v113, v113
	v_exp_f32_e32 v114, v114
	v_exp_f32_e32 v115, v115
	v_pk_mul_f32 v[100:101], v[104:105], v[100:101]
	v_pk_mul_f32 v[104:105], v[118:119], v[106:107] op_sel_hi:[0,1]
	v_pk_add_f32 v[120:121], v[120:121], 1.0 op_sel_hi:[1,0]
	v_pk_mul_f32 v[110:111], v[112:113], v[110:111]
	v_pk_add_f32 v[112:113], v[114:115], 1.0 op_sel_hi:[1,0]
	v_exp_f32_e32 v104, v104
	v_exp_f32_e32 v105, v105
	v_rcp_f32_e32 v120, v120
	v_rcp_f32_e32 v121, v121
	v_rcp_f32_e32 v112, v112
	v_rcp_f32_e32 v113, v113
	v_cvt_f32_i32_e32 v103, v103
	v_cvt_f32_i32_e32 v102, v102
	v_mul_f32_e32 v122, v122, v122
	v_pk_add_f32 v[104:105], v[104:105], 1.0 op_sel_hi:[1,0]
	v_mul_f32_e32 v122, 4.0, v122
	v_pk_mul_f32 v[108:109], v[120:121], v[108:109]
	v_pk_mul_f32 v[100:101], v[112:113], v[100:101]
	v_rcp_f32_e32 v104, v104
	v_rcp_f32_e32 v105, v105
	v_pk_mul_f32 v[108:109], v[122:123], v[108:109] op_sel_hi:[0,1]
	v_pk_mul_f32 v[100:101], v[122:123], v[100:101] op_sel_hi:[0,1]
	v_pk_mul_f32 v[102:103], v[106:107], v[102:103]
	v_mov_b32_e32 v106, v3
	v_mov_b32_e32 v107, v3
	v_cvt_pk_fp8_f32 v106, v108, v109
	v_cvt_pk_fp8_f32 v107, v100, v101
	v_pk_mul_f32 v[100:101], v[104:105], v[102:103]
	v_pk_mul_f32 v[110:111], v[122:123], v[110:111] op_sel_hi:[0,1]
	v_pk_mul_f32 v[100:101], v[122:123], v[100:101] op_sel_hi:[0,1]
	v_cvt_pk_fp8_f32 v106, v110, v111 op_sel:[0,0,1]
	v_cvt_pk_fp8_f32 v107, v100, v101 op_sel:[0,0,1]
	v_cvt_f32_i32_e32 v97, v97
	v_cvt_f32_i32_e32 v96, v96
	v_cvt_f32_i32_e32 v93, v93
	v_cvt_f32_i32_e32 v92, v92
	v_cvt_f32_i32_e32 v99, v99
	v_cvt_f32_i32_e32 v98, v98
	v_mad_i64_i32 v[100:101], s[2:3], v119, s4, v[116:117]
	v_lshl_add_u64 v[100:101], v[100:101], 0, v[132:133]
	v_mul_f32_e32 v104, v188, v198
	global_store_dwordx2 v[100:101], v[106:107], off
	v_or_b32_e32 v101, 32, v134
;     __device__ __forceinline__ void operator()(const f32x4 (&acc)[2][2][4][2], const Unit& u, int wr, int wc, int fr, int fq, const float (&pre)[8]) const {
;     ...
;                         const float fa0 = acc[ai][0][m][n][2 * jp], fa1 = acc[ai][0][m][n][2 * jp + 1], fb0 = acc[ai][1][m][n][2 * jp], fb1 = acc[ai][1][m][n][2 * jp + 1];
;                         const f32x2 A = iacc ? (f32x2){(float)__float_as_int(fa0), (float)__float_as_int(fa1)} : (f32x2){fa0, fa1};
;                         const f32x2 B = iacc ? (f32x2){(float)__float_as_int(fb0), (float)__float_as_int(fb1)} : (f32x2){fb0, fb1};
;                         const f32x2 X = A * ke;
;                         const f32x2 D = (f32x2){__builtin_amdgcn_exp2f(X[0]), __builtin_amdgcn_exp2f(X[1])} + 1.0f;
;                         const f32x2 R = {__builtin_amdgcn_rcpf(D[0]), __builtin_amdgcn_rcpf(D[1])};
;                         hv[n * 2 + jp] = ((A * B) * R) * K;
;                     }
;                 f16x8 hi, lo;
;                 if (h8) {
;                     int p0 = __builtin_amdgcn_cvt_pk_fp8_f32(hv[0][0], hv[0][1], 0, false); p0 = __builtin_amdgcn_cvt_pk_fp8_f32(hv[1][0], hv[1][1], p0, true);
;                     int p1 = __builtin_amdgcn_cvt_pk_fp8_f32(hv[2][0], hv[2][1], 0, false); p1 = __builtin_amdgcn_cvt_pk_fp8_f32(hv[3][0], hv[3][1], p1, true);
;                     *(u32x2v*)((unsigned char*)Hh + off) = (u32x2v){(unsigned)p0, (unsigned)p1}; }
	v_mul_f32_e32 v100, 0xbfb8aa3b, v104
	v_pk_mul_f32 v[102:103], v[100:101], v[96:97] op_sel_hi:[0,1]
	v_pk_mul_f32 v[92:93], v[96:97], v[92:93]
	v_pk_mul_f32 v[96:97], v[100:101], v[98:99] op_sel_hi:[0,1]
	v_exp_f32_e32 v96, v96
	v_exp_f32_e32 v97, v97
	v_cvt_f32_i32_e32 v95, v95
	v_cvt_f32_i32_e32 v94, v94
	v_cvt_f32_i32_e32 v89, v89
	v_cvt_f32_i32_e32 v88, v88
	v_pk_add_f32 v[96:97], v[96:97], 1.0 op_sel_hi:[1,0]
	v_pk_mul_f32 v[94:95], v[98:99], v[94:95]
	v_cvt_f32_i32_e32 v85, v85
	v_pk_mul_f32 v[98:99], v[100:101], v[88:89] op_sel_hi:[0,1]
	v_cvt_f32_i32_e32 v84, v84
	v_cvt_f32_i32_e32 v91, v91
	v_cvt_f32_i32_e32 v90, v90
	v_exp_f32_e32 v102, v102
	v_exp_f32_e32 v103, v103
	v_rcp_f32_e32 v96, v96
	v_rcp_f32_e32 v97, v97
	v_exp_f32_e32 v98, v98
	v_exp_f32_e32 v99, v99
	v_pk_mul_f32 v[84:85], v[88:89], v[84:85]
	v_pk_mul_f32 v[88:89], v[100:101], v[90:91] op_sel_hi:[0,1]
	v_pk_add_f32 v[102:103], v[102:103], 1.0 op_sel_hi:[1,0]
	v_pk_mul_f32 v[94:95], v[96:97], v[94:95]
	v_pk_add_f32 v[96:97], v[98:99], 1.0 op_sel_hi:[1,0]
	v_exp_f32_e32 v88, v88
	v_exp_f32_e32 v89, v89
	v_rcp_f32_e32 v102, v102
	v_rcp_f32_e32 v103, v103
	v_rcp_f32_e32 v96, v96
	v_rcp_f32_e32 v97, v97
	v_cvt_f32_i32_e32 v87, v87
	v_cvt_f32_i32_e32 v86, v86
	v_mul_f32_e32 v104, v104, v104
	v_pk_add_f32 v[88:89], v[88:89], 1.0 op_sel_hi:[1,0]
	v_mul_f32_e32 v104, 4.0, v104
	v_pk_mul_f32 v[92:93], v[102:103], v[92:93]
	v_pk_mul_f32 v[84:85], v[96:97], v[84:85]
	v_rcp_f32_e32 v88, v88
	v_rcp_f32_e32 v89, v89
	v_pk_mul_f32 v[92:93], v[104:105], v[92:93] op_sel_hi:[0,1]
	v_pk_mul_f32 v[84:85], v[104:105], v[84:85] op_sel_hi:[0,1]
	v_pk_mul_f32 v[86:87], v[90:91], v[86:87]
	v_mov_b32_e32 v90, v3
	v_mov_b32_e32 v91, v3
	v_cvt_pk_fp8_f32 v90, v92, v93
	v_cvt_pk_fp8_f32 v91, v84, v85
	v_pk_mul_f32 v[84:85], v[88:89], v[86:87]
	v_pk_mul_f32 v[94:95], v[104:105], v[94:95] op_sel_hi:[0,1]
	v_pk_mul_f32 v[84:85], v[104:105], v[84:85] op_sel_hi:[0,1]
	v_cvt_pk_fp8_f32 v90, v94, v95 op_sel:[0,0,1]
	v_cvt_pk_fp8_f32 v91, v84, v85 op_sel:[0,0,1]
	v_cvt_f32_i32_e32 v81, v81
	v_cvt_f32_i32_e32 v80, v80
	v_cvt_f32_i32_e32 v77, v77
	v_cvt_f32_i32_e32 v76, v76
	v_cvt_f32_i32_e32 v83, v83
	v_cvt_f32_i32_e32 v82, v82
	v_mad_i64_i32 v[84:85], s[2:3], v101, s4, v[116:117]
	v_lshl_add_u64 v[84:85], v[84:85], 0, v[132:133]
	v_mul_f32_e32 v88, v188, v197
	global_store_dwordx2 v[84:85], v[90:91], off
	v_or_b32_e32 v85, 48, v134
	v_mul_f32_e32 v84, 0xbfb8aa3b, v88
	v_pk_mul_f32 v[86:87], v[84:85], v[80:81] op_sel_hi:[0,1]
	v_pk_mul_f32 v[76:77], v[80:81], v[76:77]
	v_pk_mul_f32 v[80:81], v[84:85], v[82:83] op_sel_hi:[0,1]
	v_exp_f32_e32 v80, v80
	v_exp_f32_e32 v81, v81
	v_cvt_f32_i32_e32 v79, v79
	v_cvt_f32_i32_e32 v78, v78
	v_cvt_f32_i32_e32 v73, v73
	v_cvt_f32_i32_e32 v72, v72
	v_pk_add_f32 v[80:81], v[80:81], 1.0 op_sel_hi:[1,0]
	v_pk_mul_f32 v[78:79], v[82:83], v[78:79]
	v_cvt_f32_i32_e32 v69, v69
	v_pk_mul_f32 v[82:83], v[84:85], v[72:73] op_sel_hi:[0,1]
	v_cvt_f32_i32_e32 v68, v68
	v_cvt_f32_i32_e32 v75, v75
	v_cvt_f32_i32_e32 v74, v74
	v_exp_f32_e32 v86, v86
	v_exp_f32_e32 v87, v87
	v_rcp_f32_e32 v80, v80
	v_rcp_f32_e32 v81, v81
	v_exp_f32_e32 v82, v82
	v_exp_f32_e32 v83, v83
	v_pk_mul_f32 v[68:69], v[72:73], v[68:69]
	v_pk_mul_f32 v[72:73], v[84:85], v[74:75] op_sel_hi:[0,1]
	v_pk_add_f32 v[86:87], v[86:87], 1.0 op_sel_hi:[1,0]
	v_pk_mul_f32 v[78:79], v[80:81], v[78:79]
	v_pk_add_f32 v[80:81], v[82:83], 1.0 op_sel_hi:[1,0]
	v_exp_f32_e32 v72, v72
	v_exp_f32_e32 v73, v73
	v_rcp_f32_e32 v86, v86
	v_rcp_f32_e32 v87, v87
	v_rcp_f32_e32 v80, v80
	v_rcp_f32_e32 v81, v81
	v_cvt_f32_i32_e32 v71, v71
	v_cvt_f32_i32_e32 v70, v70
	v_mul_f32_e32 v88, v88, v88
	v_pk_add_f32 v[72:73], v[72:73], 1.0 op_sel_hi:[1,0]
	v_mul_f32_e32 v88, 4.0, v88
	v_pk_mul_f32 v[76:77], v[86:87], v[76:77]
	v_pk_mul_f32 v[68:69], v[80:81], v[68:69]
	v_rcp_f32_e32 v72, v72
	v_rcp_f32_e32 v73, v73
	v_pk_mul_f32 v[76:77], v[88:89], v[76:77] op_sel_hi:[0,1]
	v_pk_mul_f32 v[68:69], v[88:89], v[68:69] op_sel_hi:[0,1]
	v_pk_mul_f32 v[70:71], v[74:75], v[70:71]
	v_mov_b32_e32 v74, v3
	v_mov_b32_e32 v75, v3
	v_cvt_pk_fp8_f32 v74, v76, v77
	v_cvt_pk_fp8_f32 v75, v68, v69
	v_pk_mul_f32 v[68:69], v[72:73], v[70:71]
	v_pk_mul_f32 v[78:79], v[88:89], v[78:79] op_sel_hi:[0,1]
	v_pk_mul_f32 v[68:69], v[88:89], v[68:69] op_sel_hi:[0,1]
	v_cvt_pk_fp8_f32 v74, v78, v79 op_sel:[0,0,1]
	v_cvt_pk_fp8_f32 v75, v68, v69 op_sel:[0,0,1]
	v_cvt_f32_i32_e32 v65, v65
	v_cvt_f32_i32_e32 v64, v64
	v_cvt_f32_i32_e32 v61, v61
	v_cvt_f32_i32_e32 v60, v60
	v_cvt_f32_i32_e32 v67, v67
	v_cvt_f32_i32_e32 v66, v66
	v_mad_i64_i32 v[68:69], s[2:3], v85, s4, v[116:117]
	v_lshl_add_u64 v[68:69], v[68:69], 0, v[132:133]
	v_mul_f32_e32 v72, v188, v196
	global_store_dwordx2 v[68:69], v[74:75], off
	v_add_u32_e32 v69, 0x80, v134
	v_mul_f32_e32 v68, 0xbfb8aa3b, v72
	v_pk_mul_f32 v[70:71], v[68:69], v[64:65] op_sel_hi:[0,1]
	v_pk_mul_f32 v[60:61], v[64:65], v[60:61]
	v_pk_mul_f32 v[64:65], v[68:69], v[66:67] op_sel_hi:[0,1]
	v_exp_f32_e32 v64, v64
	v_exp_f32_e32 v65, v65
	v_cvt_f32_i32_e32 v63, v63
	v_cvt_f32_i32_e32 v62, v62
	v_cvt_f32_i32_e32 v57, v57
	v_cvt_f32_i32_e32 v56, v56
	v_pk_add_f32 v[64:65], v[64:65], 1.0 op_sel_hi:[1,0]
	v_pk_mul_f32 v[62:63], v[66:67], v[62:63]
	v_cvt_f32_i32_e32 v53, v53
	v_pk_mul_f32 v[66:67], v[68:69], v[56:57] op_sel_hi:[0,1]
	v_cvt_f32_i32_e32 v52, v52
	v_cvt_f32_i32_e32 v59, v59
	v_cvt_f32_i32_e32 v58, v58
	v_exp_f32_e32 v70, v70
	v_exp_f32_e32 v71, v71
	v_rcp_f32_e32 v64, v64
	v_rcp_f32_e32 v65, v65
	v_exp_f32_e32 v66, v66
	v_exp_f32_e32 v67, v67
	v_pk_mul_f32 v[52:53], v[56:57], v[52:53]
	v_pk_mul_f32 v[56:57], v[68:69], v[58:59] op_sel_hi:[0,1]
;     __device__ __forceinline__ void operator()(const f32x4 (&acc)[2][2][4][2], const Unit& u, int wr, int wc, int fr, int fq, const float (&pre)[8]) const {
;     ...
;                         const float fa0 = acc[ai][0][m][n][2 * jp], fa1 = acc[ai][0][m][n][2 * jp + 1], fb0 = acc[ai][1][m][n][2 * jp], fb1 = acc[ai][1][m][n][2 * jp + 1];
;                         const f32x2 A = iacc ? (f32x2){(float)__float_as_int(fa0), (float)__float_as_int(fa1)} : (f32x2){fa0, fa1};
;                         const f32x2 B = iacc ? (f32x2){(float)__float_as_int(fb0), (float)__float_as_int(fb1)} : (f32x2){fb0, fb1};
;                         const f32x2 X = A * ke;
;                         const f32x2 D = (f32x2){__builtin_amdgcn_exp2f(X[0]), __builtin_amdgcn_exp2f(X[1])} + 1.0f;
;                         const f32x2 R = {__builtin_amdgcn_rcpf(D[0]), __builtin_amdgcn_rcpf(D[1])};
;                         hv[n * 2 + jp] = ((A * B) * R) * K;
;                     }
;                 f16x8 hi, lo;
;                 if (h8) {
;                     int p0 = __builtin_amdgcn_cvt_pk_fp8_f32(hv[0][0], hv[0][1], 0, false); p0 = __builtin_amdgcn_cvt_pk_fp8_f32(hv[1][0], hv[1][1], p0, true);
;                     int p1 = __builtin_amdgcn_cvt_pk_fp8_f32(hv[2][0], hv[2][1], 0, false); p1 = __builtin_amdgcn_cvt_pk_fp8_f32(hv[3][0], hv[3][1], p1, true);
;                     *(u32x2v*)((unsigned char*)Hh + off) = (u32x2v){(unsigned)p0, (unsigned)p1}; }
	v_pk_add_f32 v[70:71], v[70:71], 1.0 op_sel_hi:[1,0]
	v_pk_mul_f32 v[62:63], v[64:65], v[62:63]
	v_pk_add_f32 v[64:65], v[66:67], 1.0 op_sel_hi:[1,0]
	v_exp_f32_e32 v56, v56
	v_exp_f32_e32 v57, v57
	v_rcp_f32_e32 v70, v70
	v_rcp_f32_e32 v71, v71
	v_rcp_f32_e32 v64, v64
	v_rcp_f32_e32 v65, v65
	v_cvt_f32_i32_e32 v55, v55
	v_cvt_f32_i32_e32 v54, v54
	v_mul_f32_e32 v72, v72, v72
	v_pk_add_f32 v[56:57], v[56:57], 1.0 op_sel_hi:[1,0]
	v_mul_f32_e32 v72, 4.0, v72
	v_pk_mul_f32 v[60:61], v[70:71], v[60:61]
	v_pk_mul_f32 v[52:53], v[64:65], v[52:53]
	v_rcp_f32_e32 v56, v56
	v_rcp_f32_e32 v57, v57
	v_pk_mul_f32 v[60:61], v[72:73], v[60:61] op_sel_hi:[0,1]
	v_pk_mul_f32 v[52:53], v[72:73], v[52:53] op_sel_hi:[0,1]
	v_pk_mul_f32 v[54:55], v[58:59], v[54:55]
	v_mov_b32_e32 v58, v3
	v_mov_b32_e32 v59, v3
	v_cvt_pk_fp8_f32 v58, v60, v61
	v_cvt_pk_fp8_f32 v59, v52, v53
	v_pk_mul_f32 v[52:53], v[56:57], v[54:55]
	v_pk_mul_f32 v[62:63], v[72:73], v[62:63] op_sel_hi:[0,1]
	v_pk_mul_f32 v[52:53], v[72:73], v[52:53] op_sel_hi:[0,1]
	v_cvt_pk_fp8_f32 v58, v62, v63 op_sel:[0,0,1]
	v_cvt_pk_fp8_f32 v59, v52, v53 op_sel:[0,0,1]
	v_cvt_f32_i32_e32 v49, v49
	v_cvt_f32_i32_e32 v48, v48
	v_cvt_f32_i32_e32 v45, v45
	v_cvt_f32_i32_e32 v44, v44
	v_cvt_f32_i32_e32 v51, v51
	v_cvt_f32_i32_e32 v50, v50
	v_mad_i64_i32 v[52:53], s[2:3], v69, s4, v[116:117]
	v_lshl_add_u64 v[52:53], v[52:53], 0, v[132:133]
	v_mul_f32_e32 v56, v188, v195
	global_store_dwordx2 v[52:53], v[58:59], off
	v_add_u32_e32 v53, 0x90, v134
	v_mul_f32_e32 v52, 0xbfb8aa3b, v56
	v_pk_mul_f32 v[54:55], v[52:53], v[48:49] op_sel_hi:[0,1]
	v_pk_mul_f32 v[44:45], v[48:49], v[44:45]
	v_pk_mul_f32 v[48:49], v[52:53], v[50:51] op_sel_hi:[0,1]
	v_exp_f32_e32 v48, v48
	v_exp_f32_e32 v49, v49
	v_cvt_f32_i32_e32 v47, v47
	v_cvt_f32_i32_e32 v46, v46
	v_cvt_f32_i32_e32 v41, v41
	v_cvt_f32_i32_e32 v40, v40
	v_pk_add_f32 v[48:49], v[48:49], 1.0 op_sel_hi:[1,0]
	v_pk_mul_f32 v[46:47], v[50:51], v[46:47]
	v_cvt_f32_i32_e32 v37, v37
	v_pk_mul_f32 v[50:51], v[52:53], v[40:41] op_sel_hi:[0,1]
	v_cvt_f32_i32_e32 v36, v36
	v_cvt_f32_i32_e32 v43, v43
	v_cvt_f32_i32_e32 v42, v42
	v_exp_f32_e32 v54, v54
	v_exp_f32_e32 v55, v55
	v_rcp_f32_e32 v48, v48
	v_rcp_f32_e32 v49, v49
	v_exp_f32_e32 v50, v50
	v_exp_f32_e32 v51, v51
	v_pk_mul_f32 v[36:37], v[40:41], v[36:37]
	v_pk_mul_f32 v[40:41], v[52:53], v[42:43] op_sel_hi:[0,1]
	v_pk_add_f32 v[54:55], v[54:55], 1.0 op_sel_hi:[1,0]
	v_pk_mul_f32 v[46:47], v[48:49], v[46:47]
	v_pk_add_f32 v[48:49], v[50:51], 1.0 op_sel_hi:[1,0]
	v_exp_f32_e32 v40, v40
	v_exp_f32_e32 v41, v41
	v_rcp_f32_e32 v54, v54
	v_rcp_f32_e32 v55, v55
	v_rcp_f32_e32 v48, v48
	v_rcp_f32_e32 v49, v49
	v_cvt_f32_i32_e32 v39, v39
	v_cvt_f32_i32_e32 v38, v38
	v_mul_f32_e32 v56, v56, v56
	v_pk_add_f32 v[40:41], v[40:41], 1.0 op_sel_hi:[1,0]
	v_mul_f32_e32 v56, 4.0, v56
	v_pk_mul_f32 v[44:45], v[54:55], v[44:45]
	v_pk_mul_f32 v[36:37], v[48:49], v[36:37]
	v_rcp_f32_e32 v40, v40
	v_rcp_f32_e32 v41, v41
	v_pk_mul_f32 v[44:45], v[56:57], v[44:45] op_sel_hi:[0,1]
	v_pk_mul_f32 v[36:37], v[56:57], v[36:37] op_sel_hi:[0,1]
	v_pk_mul_f32 v[38:39], v[42:43], v[38:39]
	v_mov_b32_e32 v42, v3
	v_mov_b32_e32 v43, v3
	v_cvt_pk_fp8_f32 v42, v44, v45
	v_cvt_pk_fp8_f32 v43, v36, v37
	v_pk_mul_f32 v[36:37], v[40:41], v[38:39]
	v_pk_mul_f32 v[46:47], v[56:57], v[46:47] op_sel_hi:[0,1]
	v_pk_mul_f32 v[36:37], v[56:57], v[36:37] op_sel_hi:[0,1]
	v_cvt_pk_fp8_f32 v42, v46, v47 op_sel:[0,0,1]
	v_cvt_pk_fp8_f32 v43, v36, v37 op_sel:[0,0,1]
	v_cvt_f32_i32_e32 v33, v33
	v_cvt_f32_i32_e32 v32, v32
	v_cvt_f32_i32_e32 v29, v29
	v_cvt_f32_i32_e32 v28, v28
	v_cvt_f32_i32_e32 v35, v35
	v_cvt_f32_i32_e32 v34, v34
	v_mad_i64_i32 v[36:37], s[2:3], v53, s4, v[116:117]
	v_lshl_add_u64 v[36:37], v[36:37], 0, v[132:133]
	v_mul_f32_e32 v40, v188, v194
	global_store_dwordx2 v[36:37], v[42:43], off
	v_add_u32_e32 v37, 0xa0, v134
	v_mul_f32_e32 v36, 0xbfb8aa3b, v40
	v_pk_mul_f32 v[38:39], v[36:37], v[32:33] op_sel_hi:[0,1]
	v_pk_mul_f32 v[28:29], v[32:33], v[28:29]
	v_pk_mul_f32 v[32:33], v[36:37], v[34:35] op_sel_hi:[0,1]
	v_exp_f32_e32 v32, v32
	v_exp_f32_e32 v33, v33
	v_cvt_f32_i32_e32 v31, v31
	v_cvt_f32_i32_e32 v30, v30
	v_cvt_f32_i32_e32 v25, v25
	v_cvt_f32_i32_e32 v24, v24
	v_pk_add_f32 v[32:33], v[32:33], 1.0 op_sel_hi:[1,0]
	v_pk_mul_f32 v[30:31], v[34:35], v[30:31]
	v_cvt_f32_i32_e32 v21, v21
	v_pk_mul_f32 v[34:35], v[36:37], v[24:25] op_sel_hi:[0,1]
	v_cvt_f32_i32_e32 v20, v20
	v_cvt_f32_i32_e32 v27, v27
	v_cvt_f32_i32_e32 v26, v26
; #define G_BAR __builtin_amdgcn_s_barrier()
;     __device__ __forceinline__ void operator()(const f32x4 (&acc)[2][2][4][2], const Unit& u, int wr, int wc, int fr, int fq, const float (&pre)[8]) const {
;     ...
;                         const float fa0 = acc[ai][0][m][n][2 * jp], fa1 = acc[ai][0][m][n][2 * jp + 1], fb0 = acc[ai][1][m][n][2 * jp], fb1 = acc[ai][1][m][n][2 * jp + 1];
;                         const f32x2 A = iacc ? (f32x2){(float)__float_as_int(fa0), (float)__float_as_int(fa1)} : (f32x2){fa0, fa1};
;                         const f32x2 B = iacc ? (f32x2){(float)__float_as_int(fb0), (float)__float_as_int(fb1)} : (f32x2){fb0, fb1};
;                         const f32x2 X = A * ke;
;                         const f32x2 D = (f32x2){__builtin_amdgcn_exp2f(X[0]), __builtin_amdgcn_exp2f(X[1])} + 1.0f;
;                         const f32x2 R = {__builtin_amdgcn_rcpf(D[0]), __builtin_amdgcn_rcpf(D[1])};
;                         hv[n * 2 + jp] = ((A * B) * R) * K;
;                     }
;                 f16x8 hi, lo;
;                 if (h8) {
;                     int p0 = __builtin_amdgcn_cvt_pk_fp8_f32(hv[0][0], hv[0][1], 0, false); p0 = __builtin_amdgcn_cvt_pk_fp8_f32(hv[1][0], hv[1][1], p0, true);
;                     int p1 = __builtin_amdgcn_cvt_pk_fp8_f32(hv[2][0], hv[2][1], 0, false); p1 = __builtin_amdgcn_cvt_pk_fp8_f32(hv[3][0], hv[3][1], p1, true);
;                     *(u32x2v*)((unsigned char*)Hh + off) = (u32x2v){(unsigned)p0, (unsigned)p1}; }
; template <int NS, int MODE  , class Epi>
; __device__ __forceinline__ void gemm_phase(LAS unsigned char* lds, const Gemm g, const StaticOrder& S, const Epi& E) {
;     ...
;         if (has_next) E.preload(pre, nxt, wr, fr);
;         if (!has_next) break;
; #pragma unroll
;         for (int a = 0; a < 2; ++a)
; #pragma unroll
;             for (int b = 0; b < 2; ++b)
; #pragma unroll
;                 for (int m = 0; m < 4; ++m)
; #pragma unroll
;                     for (int n = 0; n < 2; ++n) acc[a][b][m][n] = (f32x4){0.f, 0.f, 0.f, 0.f};
;         cur = nxt; cA = nA; cB = nB; ++ui;
;         if (G_ALIGN) { if (wr == 1) G_BAR; }
	v_exp_f32_e32 v38, v38
	v_exp_f32_e32 v39, v39
	v_rcp_f32_e32 v32, v32
	v_rcp_f32_e32 v33, v33
	v_exp_f32_e32 v34, v34
	v_exp_f32_e32 v35, v35
	v_pk_mul_f32 v[20:21], v[24:25], v[20:21]
	v_pk_mul_f32 v[24:25], v[36:37], v[26:27] op_sel_hi:[0,1]
	v_pk_add_f32 v[38:39], v[38:39], 1.0 op_sel_hi:[1,0]
	v_pk_mul_f32 v[30:31], v[32:33], v[30:31]
	v_pk_add_f32 v[32:33], v[34:35], 1.0 op_sel_hi:[1,0]
	v_exp_f32_e32 v24, v24
	v_exp_f32_e32 v25, v25
	v_rcp_f32_e32 v38, v38
	v_rcp_f32_e32 v39, v39
	v_rcp_f32_e32 v32, v32
	v_rcp_f32_e32 v33, v33
	v_cvt_f32_i32_e32 v23, v23
	v_cvt_f32_i32_e32 v22, v22
	v_mul_f32_e32 v40, v40, v40
	v_pk_add_f32 v[24:25], v[24:25], 1.0 op_sel_hi:[1,0]
	v_mul_f32_e32 v40, 4.0, v40
	v_pk_mul_f32 v[28:29], v[38:39], v[28:29]
	v_pk_mul_f32 v[20:21], v[32:33], v[20:21]
	v_rcp_f32_e32 v24, v24
	v_rcp_f32_e32 v25, v25
	v_pk_mul_f32 v[28:29], v[40:41], v[28:29] op_sel_hi:[0,1]
	v_pk_mul_f32 v[20:21], v[40:41], v[20:21] op_sel_hi:[0,1]
	v_pk_mul_f32 v[22:23], v[26:27], v[22:23]
	v_mov_b32_e32 v26, v3
	v_mov_b32_e32 v27, v3
	v_cvt_pk_fp8_f32 v26, v28, v29
	v_cvt_pk_fp8_f32 v27, v20, v21
	v_pk_mul_f32 v[20:21], v[24:25], v[22:23]
	v_pk_mul_f32 v[30:31], v[40:41], v[30:31] op_sel_hi:[0,1]
	v_pk_mul_f32 v[20:21], v[40:41], v[20:21] op_sel_hi:[0,1]
	v_cvt_pk_fp8_f32 v26, v30, v31 op_sel:[0,0,1]
	v_cvt_pk_fp8_f32 v27, v20, v21 op_sel:[0,0,1]
	v_cvt_f32_i32_e32 v17, v17
	v_cvt_f32_i32_e32 v16, v16
	v_cvt_f32_i32_e32 v13, v13
	v_cvt_f32_i32_e32 v12, v12
	v_cvt_f32_i32_e32 v19, v19
	v_cvt_f32_i32_e32 v18, v18
	v_mad_i64_i32 v[20:21], s[2:3], v37, s4, v[116:117]
	v_lshl_add_u64 v[20:21], v[20:21], 0, v[132:133]
	v_mul_f32_e32 v24, v188, v192
	global_store_dwordx2 v[20:21], v[26:27], off
	v_add_u32_e32 v21, 0xb0, v134
	v_mul_f32_e32 v20, 0xbfb8aa3b, v24
	v_pk_mul_f32 v[22:23], v[20:21], v[16:17] op_sel_hi:[0,1]
	v_pk_mul_f32 v[12:13], v[16:17], v[12:13]
	v_pk_mul_f32 v[16:17], v[20:21], v[18:19] op_sel_hi:[0,1]
	v_exp_f32_e32 v16, v16
	v_exp_f32_e32 v17, v17
	v_cvt_f32_i32_e32 v15, v15
	v_cvt_f32_i32_e32 v14, v14
	v_cvt_f32_i32_e32 v9, v9
	v_cvt_f32_i32_e32 v8, v8
	v_pk_add_f32 v[16:17], v[16:17], 1.0 op_sel_hi:[1,0]
	v_pk_mul_f32 v[14:15], v[18:19], v[14:15]
	v_cvt_f32_i32_e32 v5, v5
	v_pk_mul_f32 v[18:19], v[20:21], v[8:9] op_sel_hi:[0,1]
	v_cvt_f32_i32_e32 v4, v4
	v_cvt_f32_i32_e32 v11, v11
	v_cvt_f32_i32_e32 v10, v10
	v_exp_f32_e32 v22, v22
	v_exp_f32_e32 v23, v23
	v_rcp_f32_e32 v16, v16
	v_rcp_f32_e32 v17, v17
	v_exp_f32_e32 v18, v18
	v_exp_f32_e32 v19, v19
	v_pk_mul_f32 v[4:5], v[8:9], v[4:5]
	v_pk_mul_f32 v[8:9], v[20:21], v[10:11] op_sel_hi:[0,1]
	v_pk_add_f32 v[22:23], v[22:23], 1.0 op_sel_hi:[1,0]
	v_pk_mul_f32 v[14:15], v[16:17], v[14:15]
	v_pk_add_f32 v[16:17], v[18:19], 1.0 op_sel_hi:[1,0]
	v_exp_f32_e32 v8, v8
	v_exp_f32_e32 v9, v9
	v_rcp_f32_e32 v22, v22
	v_rcp_f32_e32 v23, v23
	v_rcp_f32_e32 v16, v16
	v_rcp_f32_e32 v17, v17
	v_cvt_f32_i32_e32 v7, v7
	v_cvt_f32_i32_e32 v6, v6
	v_mul_f32_e32 v24, v24, v24
	v_pk_add_f32 v[8:9], v[8:9], 1.0 op_sel_hi:[1,0]
	v_mul_f32_e32 v24, 4.0, v24
	v_pk_mul_f32 v[12:13], v[22:23], v[12:13]
	v_pk_mul_f32 v[4:5], v[16:17], v[4:5]
	v_rcp_f32_e32 v8, v8
	v_rcp_f32_e32 v9, v9
	v_pk_mul_f32 v[12:13], v[24:25], v[12:13] op_sel_hi:[0,1]
	v_pk_mul_f32 v[4:5], v[24:25], v[4:5] op_sel_hi:[0,1]
	v_pk_mul_f32 v[6:7], v[10:11], v[6:7]
	v_mov_b32_e32 v10, v3
	v_mov_b32_e32 v11, v3
	v_cvt_pk_fp8_f32 v10, v12, v13
	v_cvt_pk_fp8_f32 v11, v4, v5
	v_pk_mul_f32 v[4:5], v[8:9], v[6:7]
	v_pk_mul_f32 v[14:15], v[24:25], v[14:15] op_sel_hi:[0,1]
	v_pk_mul_f32 v[4:5], v[24:25], v[4:5] op_sel_hi:[0,1]
	v_cvt_pk_fp8_f32 v10, v14, v15 op_sel:[0,0,1]
	v_cvt_pk_fp8_f32 v11, v4, v5 op_sel:[0,0,1]
	v_mad_i64_i32 v[4:5], s[2:3], v21, s4, v[116:117]
	v_lshl_add_u64 v[4:5], v[4:5], 0, v[132:133]
	s_andn2_b64 vcc, exec, s[38:39]
	s_mov_b64 s[38:39], -1
	global_store_dwordx2 v[4:5], v[10:11], off
	s_cbranch_vccnz .LBB0_440
	v_lshl_add_u32 v4, s20, 8, v189
	v_ashrrev_i32_e32 v5, 31, v4
	v_lshl_add_u64 v[4:5], v[4:5], 2, s[16:17]
	global_load_dword v200, v[4:5], off
	global_load_dword v199, v[4:5], off offset:64
	global_load_dword v198, v[4:5], off offset:128
	global_load_dword v197, v[4:5], off offset:192
	global_load_dword v196, v[4:5], off offset:512
	global_load_dword v195, v[4:5], off offset:576
	global_load_dword v194, v[4:5], off offset:640
	global_load_dword v192, v[4:5], off offset:704
	s_andn2_b64 vcc, exec, s[0:1]
	s_cbranch_vccnz .LBB0_439
	s_barrier
	s_branch .LBB0_439

; #define G_STAGE(bufoff, gbase, voff) do { _Pragma("unroll") for (int _i = 0; _i < 2; ++_i) \
;         __builtin_amdgcn_global_load_lds((const unsigned*)((const char*)(gbase) + (voff)[_i]), (LAS unsigned*)(lds + (bufoff) + ldsw + _i * 8192), 16, 0, 0); } while (0)
; #define G_LDA(dst, b, h) do { _Pragma("unroll") for (int m = 0; m < 4; ++m) { const i32x4 _p0 = *(const LAS i32x4*)(lds + G_SA(b, h) + aoff + m * 2048), _p1 = *(const LAS i32x4*)(lds + G_SA(b, h) + aoff + m * 2048 + 1024); \
;         dst[m] = __builtin_shufflevector(_p0, _p1, 0, 1, 2, 3, 4, 5, 6, 7); } } while (0)
; #define G_LDB(dst, b, h) do { _Pragma("unroll") for (int n = 0; n < 2; ++n) { const i32x4 _p0 = *(const LAS i32x4*)(lds + G_SB(b, h) + boff + n * 2048), _p1 = *(const LAS i32x4*)(lds + G_SB(b, h) + boff + n * 2048 + 1024); \
;         dst[n] = __builtin_shufflevector(_p0, _p1, 0, 1, 2, 3, 4, 5, 6, 7); } } while (0)
; #define G_WAIT_V(n) asm volatile("s_waitcnt vmcnt(" #n ")" ::: "memory")
; #define G_WAIT_L(n) asm volatile("s_waitcnt lgkmcnt(" #n ")" ::: "memory")
; #define G_BAR __builtin_amdgcn_s_barrier()
; #define G_SCHED __builtin_amdgcn_sched_barrier(0)
; template <int NS, int MODE  , class Epi>
; __device__ __forceinline__ void gemm_phase(LAS unsigned char* lds, const Gemm g, const StaticOrder& S, const Epi& E) {
;     ...
;             if (G_SP2) {
;             G_LDB(B0, 0, 0); G_LDB(B1, 0, 1); G_SCHED; G_LDA(At, 0, 0); G_STAGE(G_SA(1, 1), a1 + hstep, voffA);
;             G_WAIT_V(8); G_WAIT_L(0); G_BAR; G_MMA(0, 0, At, B0); G_MMA(0, 1, At, B1); G_BAR; G_SCHED;
;             G_LDA(At, 0, 1); G_STAGE(G_SB(0, 0), b2, voffB); G_STAGE(G_SB(0, 1), b2 + hstep, voffB); G_STAGE(G_SA(0, 0), a2, voffA);
;             G_WAIT_V(8); G_WAIT_L(0); G_BAR; G_MMA(1, 0, At, B0); G_MMA(1, 1, At, B1); G_BAR; G_SCHED;
.LBB0_525:
	s_add_i32 s25, 0, 0x10000
	s_add_i32 s30, 0, 0x14000
	v_add_u32_e32 v4, s25, v244
	v_add_u32_e32 v16, s30, v244
	ds_read_b128 v[20:23], v4
	ds_read_b128 v[24:27], v4 offset:1024
	ds_read_b128 v[28:31], v4 offset:2048
	ds_read_b128 v[32:35], v4 offset:3072
	ds_read_b128 v[4:7], v16
	ds_read_b128 v[8:11], v16 offset:1024
	ds_read_b128 v[12:15], v16 offset:2048
	ds_read_b128 v[16:19], v16 offset:3072
	v_lshl_add_u64 v[176:177], v[164:165], 0, s[46:47]
	s_add_i32 m0, s19, 0xc000
	ds_read_b128 v[168:171], v246
	ds_read_b128 v[172:175], v246 offset:1024
	ds_read_b128 v[196:199], v246 offset:2048
	ds_read_b128 v[200:203], v246 offset:3072
	ds_read_b128 v[204:207], v246 offset:4096
	ds_read_b128 v[208:211], v246 offset:5120
	ds_read_b128 v[212:215], v246 offset:6144
	ds_read_b128 v[216:219], v246 offset:7168
	global_load_lds_dwordx4 v[176:177], off
	v_lshl_add_u64 v[176:177], v[166:167], 0, s[46:47]
	s_add_i32 m0, s19, 0xe000
	s_nop 0
	global_load_lds_dwordx4 v[176:177], off
	s_waitcnt vmcnt(8)
	s_waitcnt lgkmcnt(0)
	s_barrier
	s_nop 0
	s_waitcnt lgkmcnt(0)
	v_mfma_scale_f32_16x16x128_f8f6f4 v[160:163], v[20:27], v[168:175], v[160:163], v242, v242 op_sel_hi:[0,0,0]
	v_mfma_scale_f32_16x16x128_f8f6f4 v[156:159], v[28:35], v[168:175], v[156:159], v242, v242 op_sel_hi:[0,0,0]
	v_mfma_scale_f32_16x16x128_f8f6f4 v[148:151], v[20:27], v[196:203], v[148:151], v242, v242 op_sel_hi:[0,0,0]
	v_mfma_scale_f32_16x16x128_f8f6f4 v[144:147], v[28:35], v[196:203], v[144:147], v242, v242 op_sel_hi:[0,0,0]
	v_mfma_scale_f32_16x16x128_f8f6f4 v[128:131], v[20:27], v[204:211], v[128:131], v242, v242 op_sel_hi:[0,0,0]
	v_mfma_scale_f32_16x16x128_f8f6f4 v[124:127], v[28:35], v[204:211], v[124:127], v242, v242 op_sel_hi:[0,0,0]
	v_mfma_scale_f32_16x16x128_f8f6f4 v[120:123], v[20:27], v[212:219], v[120:123], v242, v242 op_sel_hi:[0,0,0]
	v_mfma_scale_f32_16x16x128_f8f6f4 v[116:119], v[28:35], v[212:219], v[116:119], v242, v242 op_sel_hi:[0,0,0]
	s_nop 0
	s_nop 0
	v_mfma_scale_f32_16x16x128_f8f6f4 v[152:155], v[4:11], v[168:175], v[152:155], v242, v242 op_sel_hi:[0,0,0]
	v_mfma_scale_f32_16x16x128_f8f6f4 v[140:143], v[12:19], v[168:175], v[140:143], v242, v242 op_sel_hi:[0,0,0]
	v_mfma_scale_f32_16x16x128_f8f6f4 v[136:139], v[4:11], v[196:203], v[136:139], v242, v242 op_sel_hi:[0,0,0]
	v_mfma_scale_f32_16x16x128_f8f6f4 v[132:135], v[12:19], v[196:203], v[132:135], v242, v242 op_sel_hi:[0,0,0]
	v_mfma_scale_f32_16x16x128_f8f6f4 v[112:115], v[4:11], v[204:211], v[112:115], v242, v242 op_sel_hi:[0,0,0]
	v_mfma_scale_f32_16x16x128_f8f6f4 v[108:111], v[12:19], v[204:211], v[108:111], v242, v242 op_sel_hi:[0,0,0]
	v_mfma_scale_f32_16x16x128_f8f6f4 v[104:107], v[4:11], v[212:219], v[104:107], v242, v242 op_sel_hi:[0,0,0]
	v_mfma_scale_f32_16x16x128_f8f6f4 v[100:103], v[12:19], v[212:219], v[100:103], v242, v242 op_sel_hi:[0,0,0]
	s_nop 0
	s_barrier
	s_add_i32 s25, s25, s18
	v_lshl_add_u64 v[176:177], s[60:61], 0, v[2:3]
	s_mov_b32 m0, s25
	ds_read_b128 v[168:171], v246 offset:16384
	ds_read_b128 v[172:175], v246 offset:17408
	ds_read_b128 v[196:199], v246 offset:18432
	ds_read_b128 v[200:203], v246 offset:19456
	ds_read_b128 v[204:207], v246 offset:20480
	ds_read_b128 v[208:211], v246 offset:21504
	ds_read_b128 v[212:215], v246 offset:22528
	ds_read_b128 v[216:219], v246 offset:23552
	global_load_lds_dwordx4 v[176:177], off
	s_add_i32 m0, s25, 0x2000
	v_lshl_add_u64 v[176:177], s[60:61], 0, v[186:187]
	s_add_u32 s60, s60, 0xb0000
	s_addc_u32 s61, s61, 0
	s_add_i32 s25, s30, s18
	global_load_lds_dwordx4 v[176:177], off
	v_lshl_add_u64 v[176:177], s[60:61], 0, v[2:3]
	s_mov_b32 m0, s25
	s_nop 0
	global_load_lds_dwordx4 v[176:177], off
	v_lshl_add_u64 v[176:177], s[60:61], 0, v[186:187]
	s_add_i32 m0, s25, 0x2000
	s_nop 0
	global_load_lds_dwordx4 v[176:177], off
	v_lshl_add_u64 v[176:177], s[58:59], 0, v[190:191]
	s_mov_b32 m0, s19
	s_nop 0
	global_load_lds_dwordx4 v[176:177], off
	v_lshl_add_u64 v[176:177], s[58:59], 0, v[188:189]
	s_mov_b32 m0, s29
	s_nop 0
	global_load_lds_dwordx4 v[176:177], off
	s_waitcnt vmcnt(8)
	s_waitcnt lgkmcnt(0)
	s_barrier
	s_nop 0
	s_waitcnt lgkmcnt(0)
	v_mfma_scale_f32_16x16x128_f8f6f4 v[96:99], v[20:27], v[168:175], v[96:99], v242, v242 op_sel_hi:[0,0,0]
	v_mfma_scale_f32_16x16x128_f8f6f4 v[92:95], v[28:35], v[168:175], v[92:95], v242, v242 op_sel_hi:[0,0,0]
	v_mfma_scale_f32_16x16x128_f8f6f4 v[88:91], v[20:27], v[196:203], v[88:91], v242, v242 op_sel_hi:[0,0,0]
	v_mfma_scale_f32_16x16x128_f8f6f4 v[84:87], v[28:35], v[196:203], v[84:87], v242, v242 op_sel_hi:[0,0,0]
	v_mfma_scale_f32_16x16x128_f8f6f4 v[64:67], v[20:27], v[204:211], v[64:67], v242, v242 op_sel_hi:[0,0,0]
	v_mfma_scale_f32_16x16x128_f8f6f4 v[60:63], v[28:35], v[204:211], v[60:63], v242, v242 op_sel_hi:[0,0,0]
	v_mfma_scale_f32_16x16x128_f8f6f4 v[56:59], v[20:27], v[212:219], v[56:59], v242, v242 op_sel_hi:[0,0,0]
	v_mfma_scale_f32_16x16x128_f8f6f4 v[52:55], v[28:35], v[212:219], v[52:55], v242, v242 op_sel_hi:[0,0,0]
	s_nop 0
	s_nop 0
	v_mfma_scale_f32_16x16x128_f8f6f4 v[80:83], v[4:11], v[168:175], v[80:83], v242, v242 op_sel_hi:[0,0,0]
	v_mfma_scale_f32_16x16x128_f8f6f4 v[76:79], v[12:19], v[168:175], v[76:79], v242, v242 op_sel_hi:[0,0,0]
	v_mfma_scale_f32_16x16x128_f8f6f4 v[72:75], v[4:11], v[196:203], v[72:75], v242, v242 op_sel_hi:[0,0,0]
	v_mfma_scale_f32_16x16x128_f8f6f4 v[68:71], v[12:19], v[196:203], v[68:71], v242, v242 op_sel_hi:[0,0,0]
	v_mfma_scale_f32_16x16x128_f8f6f4 v[48:51], v[4:11], v[204:211], v[48:51], v242, v242 op_sel_hi:[0,0,0]
	v_mfma_scale_f32_16x16x128_f8f6f4 v[44:47], v[12:19], v[204:211], v[44:47], v242, v242 op_sel_hi:[0,0,0]
	v_mfma_scale_f32_16x16x128_f8f6f4 v[40:43], v[4:11], v[212:219], v[40:43], v242, v242 op_sel_hi:[0,0,0]
	v_mfma_scale_f32_16x16x128_f8f6f4 v[36:39], v[12:19], v[212:219], v[36:39], v242, v242 op_sel_hi:[0,0,0]
	s_nop 0
	s_barrier
; #define G_STAGE(bufoff, gbase, voff) do { _Pragma("unroll") for (int _i = 0; _i < 2; ++_i) \
;         __builtin_amdgcn_global_load_lds((const unsigned*)((const char*)(gbase) + (voff)[_i]), (LAS unsigned*)(lds + (bufoff) + ldsw + _i * 8192), 16, 0, 0); } while (0)
; #define G_LDA(dst, b, h) do { _Pragma("unroll") for (int m = 0; m < 4; ++m) { const i32x4 _p0 = *(const LAS i32x4*)(lds + G_SA(b, h) + aoff + m * 2048), _p1 = *(const LAS i32x4*)(lds + G_SA(b, h) + aoff + m * 2048 + 1024); \
;         dst[m] = __builtin_shufflevector(_p0, _p1, 0, 1, 2, 3, 4, 5, 6, 7); } } while (0)
; #define G_LDB(dst, b, h) do { _Pragma("unroll") for (int n = 0; n < 2; ++n) { const i32x4 _p0 = *(const LAS i32x4*)(lds + G_SB(b, h) + boff + n * 2048), _p1 = *(const LAS i32x4*)(lds + G_SB(b, h) + boff + n * 2048 + 1024); \
;         dst[n] = __builtin_shufflevector(_p0, _p1, 0, 1, 2, 3, 4, 5, 6, 7); } } while (0)
; #define G_WAIT_V(n) asm volatile("s_waitcnt vmcnt(" #n ")" ::: "memory")
; #define G_WAIT_L(n) asm volatile("s_waitcnt lgkmcnt(" #n ")" ::: "memory")
; #define G_BAR __builtin_amdgcn_s_barrier()
; #define G_SCHED __builtin_amdgcn_sched_barrier(0)
; template <int NS, int MODE  , class Epi>
; __device__ __forceinline__ void gemm_phase(LAS unsigned char* lds, const Gemm g, const StaticOrder& S, const Epi& E) {
;     ...
;             G_LDB(B0, 1, 0); G_LDB(B1, 1, 1); G_SCHED; G_LDA(At, 1, 0); G_STAGE(G_SA(0, 1), a2 + hstep, voffA);
;             G_WAIT_V(8); G_WAIT_L(0); G_BAR; G_MMA(0, 0, At, B0); G_MMA(0, 1, At, B1); G_BAR; G_SCHED;
;             G_LDA(At, 1, 1); G_STAGE(G_SB(1, 0), b3, voffB); G_STAGE(G_SB(1, 1), b3 + hstep, voffB); G_STAGE(G_SA(1, 0), a3, voffA);
;             G_WAIT_V(8); G_WAIT_L(0); G_BAR; G_MMA(1, 0, At, B0); G_MMA(1, 1, At, B1); G_BAR; G_SCHED;
	s_add_i32 s25, 0, 0x18000
	s_add_i32 s35, 0, 0x1c000
	v_add_u32_e32 v16, s25, v244
	v_add_u32_e32 v32, s35, v244
	ds_read_b128 v[4:7], v16
	ds_read_b128 v[8:11], v16 offset:1024
	ds_read_b128 v[12:15], v16 offset:2048
	ds_read_b128 v[16:19], v16 offset:3072
	ds_read_b128 v[20:23], v32
	ds_read_b128 v[24:27], v32 offset:1024
	ds_read_b128 v[28:31], v32 offset:2048
	ds_read_b128 v[32:35], v32 offset:3072
	s_add_u32 s30, s58, 0xb0000
	s_addc_u32 s31, s59, 0
	s_mov_b32 m0, s56
	v_lshl_add_u64 v[176:177], s[30:31], 0, v[190:191]
	ds_read_b128 v[168:171], v246 offset:32768
	ds_read_b128 v[172:175], v246 offset:33792
	ds_read_b128 v[196:199], v246 offset:34816
	ds_read_b128 v[200:203], v246 offset:35840
	ds_read_b128 v[204:207], v246 offset:36864
	ds_read_b128 v[208:211], v246 offset:37888
	ds_read_b128 v[212:215], v246 offset:38912
	ds_read_b128 v[216:219], v246 offset:39936
	global_load_lds_dwordx4 v[176:177], off
	v_lshl_add_u64 v[176:177], s[30:31], 0, v[188:189]
	s_mov_b32 m0, s62
	s_nop 0
	global_load_lds_dwordx4 v[176:177], off
	s_waitcnt vmcnt(8)
	s_waitcnt lgkmcnt(0)
	s_barrier
	s_nop 0
	s_waitcnt lgkmcnt(0)
	v_mfma_scale_f32_16x16x128_f8f6f4 v[160:163], v[4:11], v[168:175], v[160:163], v242, v242 op_sel_hi:[0,0,0]
	v_mfma_scale_f32_16x16x128_f8f6f4 v[156:159], v[12:19], v[168:175], v[156:159], v242, v242 op_sel_hi:[0,0,0]
	v_mfma_scale_f32_16x16x128_f8f6f4 v[148:151], v[4:11], v[196:203], v[148:151], v242, v242 op_sel_hi:[0,0,0]
	v_mfma_scale_f32_16x16x128_f8f6f4 v[144:147], v[12:19], v[196:203], v[144:147], v242, v242 op_sel_hi:[0,0,0]
	v_mfma_scale_f32_16x16x128_f8f6f4 v[128:131], v[4:11], v[204:211], v[128:131], v242, v242 op_sel_hi:[0,0,0]
	v_mfma_scale_f32_16x16x128_f8f6f4 v[124:127], v[12:19], v[204:211], v[124:127], v242, v242 op_sel_hi:[0,0,0]
	v_mfma_scale_f32_16x16x128_f8f6f4 v[120:123], v[4:11], v[212:219], v[120:123], v242, v242 op_sel_hi:[0,0,0]
	v_mfma_scale_f32_16x16x128_f8f6f4 v[116:119], v[12:19], v[212:219], v[116:119], v242, v242 op_sel_hi:[0,0,0]
	s_nop 0
	s_nop 0
	v_mfma_scale_f32_16x16x128_f8f6f4 v[152:155], v[20:27], v[168:175], v[152:155], v242, v242 op_sel_hi:[0,0,0]
	v_mfma_scale_f32_16x16x128_f8f6f4 v[140:143], v[28:35], v[168:175], v[140:143], v242, v242 op_sel_hi:[0,0,0]
	v_mfma_scale_f32_16x16x128_f8f6f4 v[136:139], v[20:27], v[196:203], v[136:139], v242, v242 op_sel_hi:[0,0,0]
	v_mfma_scale_f32_16x16x128_f8f6f4 v[132:135], v[28:35], v[196:203], v[132:135], v242, v242 op_sel_hi:[0,0,0]
	v_mfma_scale_f32_16x16x128_f8f6f4 v[112:115], v[20:27], v[204:211], v[112:115], v242, v242 op_sel_hi:[0,0,0]
	v_mfma_scale_f32_16x16x128_f8f6f4 v[108:111], v[28:35], v[204:211], v[108:111], v242, v242 op_sel_hi:[0,0,0]
	v_mfma_scale_f32_16x16x128_f8f6f4 v[104:107], v[20:27], v[212:219], v[104:107], v242, v242 op_sel_hi:[0,0,0]
	v_mfma_scale_f32_16x16x128_f8f6f4 v[100:103], v[28:35], v[212:219], v[100:103], v242, v242 op_sel_hi:[0,0,0]
	s_nop 0
	s_barrier
	s_add_i32 s25, s25, s18
	v_lshl_add_u64 v[176:177], s[54:55], 0, v[2:3]
	s_mov_b32 m0, s25
	ds_read_b128 v[168:171], v246 offset:49152
	ds_read_b128 v[172:175], v246 offset:50176
	ds_read_b128 v[196:199], v246 offset:51200
	ds_read_b128 v[200:203], v246 offset:52224
	ds_read_b128 v[204:207], v246 offset:53248
	ds_read_b128 v[208:211], v246 offset:54272
	ds_read_b128 v[212:215], v246 offset:55296
	ds_read_b128 v[216:219], v246 offset:56320
	global_load_lds_dwordx4 v[176:177], off
	s_add_i32 m0, s25, 0x2000
	s_add_u32 s30, s54, 0xb0000
	v_lshl_add_u64 v[176:177], s[54:55], 0, v[186:187]
	s_addc_u32 s31, s55, 0
	s_add_i32 s25, s35, s18
	global_load_lds_dwordx4 v[176:177], off
	v_lshl_add_u64 v[176:177], s[30:31], 0, v[2:3]
	s_mov_b32 m0, s25
	s_nop 0
	global_load_lds_dwordx4 v[176:177], off
	v_lshl_add_u64 v[176:177], s[30:31], 0, v[186:187]
	s_add_i32 m0, s25, 0x2000
	s_nop 0
	global_load_lds_dwordx4 v[176:177], off
	v_lshl_add_u64 v[176:177], s[52:53], 0, v[190:191]
	s_mov_b32 m0, s65
	s_nop 0
	global_load_lds_dwordx4 v[176:177], off
	v_lshl_add_u64 v[176:177], s[52:53], 0, v[188:189]
	s_mov_b32 m0, s66
	s_nop 0
	global_load_lds_dwordx4 v[176:177], off
	s_waitcnt vmcnt(8)
	s_waitcnt lgkmcnt(0)
	s_barrier
	s_nop 0
	s_waitcnt lgkmcnt(0)
	v_mfma_scale_f32_16x16x128_f8f6f4 v[96:99], v[4:11], v[168:175], v[96:99], v242, v242 op_sel_hi:[0,0,0]
	v_mfma_scale_f32_16x16x128_f8f6f4 v[92:95], v[12:19], v[168:175], v[92:95], v242, v242 op_sel_hi:[0,0,0]
	v_mfma_scale_f32_16x16x128_f8f6f4 v[88:91], v[4:11], v[196:203], v[88:91], v242, v242 op_sel_hi:[0,0,0]
	v_mfma_scale_f32_16x16x128_f8f6f4 v[84:87], v[12:19], v[196:203], v[84:87], v242, v242 op_sel_hi:[0,0,0]
	v_mfma_scale_f32_16x16x128_f8f6f4 v[64:67], v[4:11], v[204:211], v[64:67], v242, v242 op_sel_hi:[0,0,0]
	v_mfma_scale_f32_16x16x128_f8f6f4 v[60:63], v[12:19], v[204:211], v[60:63], v242, v242 op_sel_hi:[0,0,0]
	v_mfma_scale_f32_16x16x128_f8f6f4 v[56:59], v[4:11], v[212:219], v[56:59], v242, v242 op_sel_hi:[0,0,0]
	v_mfma_scale_f32_16x16x128_f8f6f4 v[52:55], v[12:19], v[212:219], v[52:55], v242, v242 op_sel_hi:[0,0,0]
	s_nop 0
	s_nop 0
	v_mfma_scale_f32_16x16x128_f8f6f4 v[80:83], v[20:27], v[168:175], v[80:83], v242, v242 op_sel_hi:[0,0,0]
	v_mfma_scale_f32_16x16x128_f8f6f4 v[76:79], v[28:35], v[168:175], v[76:79], v242, v242 op_sel_hi:[0,0,0]
	v_mfma_scale_f32_16x16x128_f8f6f4 v[72:75], v[20:27], v[196:203], v[72:75], v242, v242 op_sel_hi:[0,0,0]
	v_mfma_scale_f32_16x16x128_f8f6f4 v[68:71], v[28:35], v[196:203], v[68:71], v242, v242 op_sel_hi:[0,0,0]
	v_mfma_scale_f32_16x16x128_f8f6f4 v[48:51], v[20:27], v[204:211], v[48:51], v242, v242 op_sel_hi:[0,0,0]
	v_mfma_scale_f32_16x16x128_f8f6f4 v[44:47], v[28:35], v[204:211], v[44:47], v242, v242 op_sel_hi:[0,0,0]
	v_mfma_scale_f32_16x16x128_f8f6f4 v[40:43], v[20:27], v[212:219], v[40:43], v242, v242 op_sel_hi:[0,0,0]
	v_mfma_scale_f32_16x16x128_f8f6f4 v[36:39], v[28:35], v[212:219], v[36:39], v242, v242 op_sel_hi:[0,0,0]
	s_nop 0
	s_barrier
	s_add_i32 s24, s24, 2
	s_add_u32 s46, s46, 0x100
	s_addc_u32 s47, s47, 0
	s_cmp_gt_u32 s24, 41
	s_cbranch_scc1 .LBB0_528

; #define LAS __attribute__((address_space(3)))
; __device__ __forceinline__ void phase_norm(const Params& P, LAS unsigned char* lds, int l, int i, const void* xsrc, int src16, int out8) {
;     ...
;     for (int row = r0x; row < rex; row += rsx) {
;         const int b = row >> 12;
;         f32x4 v[8]; float ss = 0.f;
; #pragma unroll
;         for (int j = 0; j < 8; ++j) { if (src16) { if ((j & 1) == 0) { const f16x8 t = __builtin_bit_cast(f16x8, nx[j >> 1]); v[j] = cvt4(t, 0); v[j + 1] = cvt4(t, 1); } } else v[j] = nx[j]; }
;         if (row + rsx < rex) NRM_LOAD(nx, row + rsx);
; #pragma unroll
;         for (int j = 0; j < 8; ++j) { ss += v[j][0] * v[j][0] + v[j][1] * v[j][1] + v[j][2] * v[j][2] + v[j][3] * v[j][3]; }
;         ss = wave_sum(ss);
;         const float rstd = 1.0f / sqrtf(ss * (1.0f / DM) + EPS);
; #pragma unroll
;         for (int j = 0; j < 8; ++j) { const int c = src16 ? (8 * (lane + 64 * (j >> 1)) + 4 * (j & 1)) : 4 * (lane + 64 * j);
;             const f32x4 gg = *(const LAS f32x4*)(gs + b * DM + c), s0 = *(const LAS f32x4*)(shl + b * DM + c);
;             f32x4 y = (v[j] * rstd) * gg + s0;
;             if (out8 == 2) v[j] = y;
;             else if (out8 == 1) { int pk = __builtin_amdgcn_cvt_pk_fp8_f32(y[0] * SA8, y[1] * SA8, 0, false); pk = __builtin_amdgcn_cvt_pk_fp8_f32(y[2] * SA8, y[3] * SA8, pk, true);
;                 *(int*)((unsigned char*)xh + (size_t)row * DM + c) = pk; }
;             else split_store4(xh, xl, (size_t)row * DM + c, y * SA, true); }
;         if (out8 == 2) {
;             float mx = 1e-20f;
; #pragma unroll
;             for (int j = 0; j < 8; ++j) mx = fmaxf(mx, fmaxf(fmaxf(fabsf(v[j][0]), fabsf(v[j][1])), fmaxf(fabsf(v[j][2]), fabsf(v[j][3]))));
;             mx = wave_max(mx);
;             const float qs = 127.0f / mx;
;             if (lane == 0) ((float*)(P.ws + WS_RS))[row] = mx * (1.0f / 127.0f);
; #pragma unroll
;             for (int j = 0; j < 8; ++j) { const int c = src16 ? (8 * (lane + 64 * (j >> 1)) + 4 * (j & 1)) : 4 * (lane + 64 * j);
;                 const int q0 = (int)rintf(v[j][0] * qs), q1 = (int)rintf(v[j][1] * qs), q2 = (int)rintf(v[j][2] * qs), q3 = (int)rintf(v[j][3] * qs);
;                 *(int*)((unsigned char*)xh + (size_t)row * DM + c) = (q0 & 255) | ((q1 & 255) << 8) | ((q2 & 255) << 16) | ((q3 & 255) << 24); }
;         }
.LBB0_603:
	s_and_b64 s[18:19], exec, s[42:43]
	s_waitcnt vmcnt(4)
	v_mov_b64_e32 v[10:11], v[6:7]
	v_mov_b64_e32 v[14:15], v[94:95]
	v_mov_b64_e32 v[18:19], v[98:99]
	v_mov_b64_e32 v[22:23], v[102:103]
	s_or_b64 s[38:39], s[18:19], s[38:39]
	v_lshl_add_u64 v[106:107], v[106:107], 0, s[12:13]
	v_lshl_add_u64 v[108:109], v[108:109], 0, s[20:21]
	v_lshl_add_u64 v[110:111], v[110:111], 0, s[26:27]
	v_lshl_add_u64 v[112:113], v[112:113], 0, s[20:21]
	v_mov_b64_e32 v[8:9], v[4:5]
	v_mov_b64_e32 v[16:17], v[96:97]
	v_mov_b64_e32 v[20:21], v[100:101]
	v_mov_b64_e32 v[24:25], v[104:105]
	v_mov_b32_e32 v30, v140
	s_andn2_b64 exec, exec, s[38:39]
	s_cbranch_execz .LBB0_641

; #define G_STAGE(bufoff, gbase, voff) do { _Pragma("unroll") for (int _i = 0; _i < 2; ++_i) \
;         __builtin_amdgcn_global_load_lds((const unsigned*)((const char*)(gbase) + (voff)[_i]), (LAS unsigned*)(lds + (bufoff) + ldsw + _i * 8192), 16, 0, 0); } while (0)
; #define G_LDA(dst, b, h) do { _Pragma("unroll") for (int m = 0; m < 4; ++m) { const i32x4 _p0 = *(const LAS i32x4*)(lds + G_SA(b, h) + aoff + m * 2048), _p1 = *(const LAS i32x4*)(lds + G_SA(b, h) + aoff + m * 2048 + 1024); \
;         dst[m] = __builtin_shufflevector(_p0, _p1, 0, 1, 2, 3, 4, 5, 6, 7); } } while (0)
; #define G_LDB(dst, b, h) do { _Pragma("unroll") for (int n = 0; n < 2; ++n) { const i32x4 _p0 = *(const LAS i32x4*)(lds + G_SB(b, h) + boff + n * 2048), _p1 = *(const LAS i32x4*)(lds + G_SB(b, h) + boff + n * 2048 + 1024); \
;         dst[n] = __builtin_shufflevector(_p0, _p1, 0, 1, 2, 3, 4, 5, 6, 7); } } while (0)
; #define G_WAIT_V(n) asm volatile("s_waitcnt vmcnt(" #n ")" ::: "memory")
; #define G_WAIT_L(n) asm volatile("s_waitcnt lgkmcnt(" #n ")" ::: "memory")
; #define G_BAR __builtin_amdgcn_s_barrier()
; #define G_SCHED __builtin_amdgcn_sched_barrier(0)
; template <int NS, int MODE  , class Epi>
; __device__ __forceinline__ void gemm_phase(LAS unsigned char* lds, const Gemm g, const StaticOrder& S, const Epi& E) {
;     ...
;             if (G_SP2) {
;             G_LDB(B0, 0, 0); G_LDB(B1, 0, 1); G_SCHED; G_LDA(At, 0, 0); G_STAGE(G_SA(1, 1), a1 + hstep, voffA);
;             G_WAIT_V(8); G_WAIT_L(0); G_BAR; G_MMA(0, 0, At, B0); G_MMA(0, 1, At, B1); G_BAR; G_SCHED;
;             G_LDA(At, 0, 1); G_STAGE(G_SB(0, 0), b2, voffB); G_STAGE(G_SB(0, 1), b2 + hstep, voffB); G_STAGE(G_SA(0, 0), a2, voffA);
;             G_WAIT_V(8); G_WAIT_L(0); G_BAR; G_MMA(1, 0, At, B0); G_MMA(1, 1, At, B1); G_BAR; G_SCHED;
.LBB0_733:
	s_add_i32 s25, 0, 0x10000
	s_add_i32 s27, 0, 0x14000
	v_add_u32_e32 v132, s25, v191
	v_add_u32_e32 v136, s27, v191
	ds_read_b128 v[160:163], v132
	ds_read_b128 v[148:151], v132 offset:1024
	ds_read_b128 v[156:159], v132 offset:2048
	ds_read_b128 v[152:155], v132 offset:3072
	ds_read_b128 v[144:147], v136
	ds_read_b128 v[132:135], v136 offset:1024
	ds_read_b128 v[140:143], v136 offset:2048
	ds_read_b128 v[136:139], v136 offset:3072
	v_lshl_add_u64 v[218:219], v[174:175], 0, s[72:73]
	s_add_i32 m0, s19, 0xc000
	ds_read_b128 v[176:179], v193
	ds_read_b128 v[180:183], v193 offset:1024
	ds_read_b128 v[194:197], v193 offset:2048
	ds_read_b128 v[198:201], v193 offset:3072
	ds_read_b128 v[202:205], v193 offset:4096
	ds_read_b128 v[206:209], v193 offset:5120
	ds_read_b128 v[210:213], v193 offset:6144
	ds_read_b128 v[214:217], v193 offset:7168
	global_load_lds_dwordx4 v[218:219], off
	v_lshl_add_u64 v[218:219], v[186:187], 0, s[72:73]
	s_add_i32 m0, s19, 0xe000
	s_nop 0
	global_load_lds_dwordx4 v[218:219], off
	s_waitcnt vmcnt(8)
	s_waitcnt lgkmcnt(0)
	s_barrier
	s_nop 0
	s_waitcnt lgkmcnt(0)
	v_mfma_i32_16x16x64_i8 v[128:131], v[160:163], v[176:179], v[128:131]
	v_mfma_i32_16x16x64_i8 v[124:127], v[156:159], v[176:179], v[124:127]
	v_mfma_i32_16x16x64_i8 v[116:119], v[160:163], v[194:197], v[116:119]
	v_mfma_i32_16x16x64_i8 v[108:111], v[156:159], v[194:197], v[108:111]
	v_mfma_i32_16x16x64_i8 v[100:103], v[160:163], v[202:205], v[100:103]
	v_mfma_i32_16x16x64_i8 v[92:95], v[156:159], v[202:205], v[92:95]
	v_mfma_i32_16x16x64_i8 v[84:87], v[160:163], v[210:213], v[84:87]
	v_mfma_i32_16x16x64_i8 v[76:79], v[156:159], v[210:213], v[76:79]
	s_nop 0
	v_mfma_i32_16x16x64_i8 v[128:131], v[148:151], v[180:183], v[128:131]
	v_mfma_i32_16x16x64_i8 v[124:127], v[152:155], v[180:183], v[124:127]
	v_mfma_i32_16x16x64_i8 v[116:119], v[148:151], v[198:201], v[116:119]
	v_mfma_i32_16x16x64_i8 v[108:111], v[152:155], v[198:201], v[108:111]
	v_mfma_i32_16x16x64_i8 v[100:103], v[148:151], v[206:209], v[100:103]
	v_mfma_i32_16x16x64_i8 v[92:95], v[152:155], v[206:209], v[92:95]
	v_mfma_i32_16x16x64_i8 v[84:87], v[148:151], v[214:217], v[84:87]
	v_mfma_i32_16x16x64_i8 v[76:79], v[152:155], v[214:217], v[76:79]
	s_nop 0
	s_nop 0
	v_mfma_i32_16x16x64_i8 v[120:123], v[144:147], v[176:179], v[120:123]
	v_mfma_i32_16x16x64_i8 v[112:115], v[140:143], v[176:179], v[112:115]
	v_mfma_i32_16x16x64_i8 v[104:107], v[144:147], v[194:197], v[104:107]
	v_mfma_i32_16x16x64_i8 v[96:99], v[140:143], v[194:197], v[96:99]
	v_mfma_i32_16x16x64_i8 v[88:91], v[144:147], v[202:205], v[88:91]
	v_mfma_i32_16x16x64_i8 v[80:83], v[140:143], v[202:205], v[80:83]
	v_mfma_i32_16x16x64_i8 v[72:75], v[144:147], v[210:213], v[72:75]
	v_mfma_i32_16x16x64_i8 v[68:71], v[140:143], v[210:213], v[68:71]
	s_nop 0
	v_mfma_i32_16x16x64_i8 v[120:123], v[132:135], v[180:183], v[120:123]
	v_mfma_i32_16x16x64_i8 v[112:115], v[136:139], v[180:183], v[112:115]
	v_mfma_i32_16x16x64_i8 v[104:107], v[132:135], v[198:201], v[104:107]
	v_mfma_i32_16x16x64_i8 v[96:99], v[136:139], v[198:201], v[96:99]
	v_mfma_i32_16x16x64_i8 v[88:91], v[132:135], v[206:209], v[88:91]
	v_mfma_i32_16x16x64_i8 v[80:83], v[136:139], v[206:209], v[80:83]
	v_mfma_i32_16x16x64_i8 v[72:75], v[132:135], v[214:217], v[72:75]
	v_mfma_i32_16x16x64_i8 v[68:71], v[136:139], v[214:217], v[68:71]
	s_nop 0
	s_barrier
	s_add_i32 s25, s25, s3
	v_lshl_add_u64 v[218:219], s[90:91], 0, v[2:3]
	s_mov_b32 m0, s25
	ds_read_b128 v[176:179], v193 offset:16384
	ds_read_b128 v[180:183], v193 offset:17408
	ds_read_b128 v[194:197], v193 offset:18432
	ds_read_b128 v[198:201], v193 offset:19456
	ds_read_b128 v[202:205], v193 offset:20480
	ds_read_b128 v[206:209], v193 offset:21504
	ds_read_b128 v[210:213], v193 offset:22528
	ds_read_b128 v[214:217], v193 offset:23552
	global_load_lds_dwordx4 v[218:219], off
	s_add_i32 m0, s25, 0x2000
	s_add_u32 s30, s90, 0x40000
	v_lshl_add_u64 v[218:219], s[90:91], 0, v[164:165]
	s_addc_u32 s31, s91, 0
	s_add_i32 s25, s27, s3
	global_load_lds_dwordx4 v[218:219], off
	v_lshl_add_u64 v[218:219], s[30:31], 0, v[2:3]
	s_mov_b32 m0, s25
	s_nop 0
	global_load_lds_dwordx4 v[218:219], off
	v_lshl_add_u64 v[218:219], s[30:31], 0, v[164:165]
	s_add_i32 m0, s25, 0x2000
	s_nop 0
	global_load_lds_dwordx4 v[218:219], off
	v_lshl_add_u64 v[218:219], s[80:81], 0, v[168:169]
	s_mov_b32 m0, s19
	s_nop 0
	global_load_lds_dwordx4 v[218:219], off
	v_lshl_add_u64 v[218:219], s[80:81], 0, v[166:167]
	s_mov_b32 m0, s29
	s_nop 0
	global_load_lds_dwordx4 v[218:219], off
	s_waitcnt vmcnt(8)
	s_waitcnt lgkmcnt(0)
	s_barrier
; #define G_STAGE(bufoff, gbase, voff) do { _Pragma("unroll") for (int _i = 0; _i < 2; ++_i) \
;         __builtin_amdgcn_global_load_lds((const unsigned*)((const char*)(gbase) + (voff)[_i]), (LAS unsigned*)(lds + (bufoff) + ldsw + _i * 8192), 16, 0, 0); } while (0)
; #define G_LDA(dst, b, h) do { _Pragma("unroll") for (int m = 0; m < 4; ++m) { const i32x4 _p0 = *(const LAS i32x4*)(lds + G_SA(b, h) + aoff + m * 2048), _p1 = *(const LAS i32x4*)(lds + G_SA(b, h) + aoff + m * 2048 + 1024); \
;         dst[m] = __builtin_shufflevector(_p0, _p1, 0, 1, 2, 3, 4, 5, 6, 7); } } while (0)
; #define G_LDB(dst, b, h) do { _Pragma("unroll") for (int n = 0; n < 2; ++n) { const i32x4 _p0 = *(const LAS i32x4*)(lds + G_SB(b, h) + boff + n * 2048), _p1 = *(const LAS i32x4*)(lds + G_SB(b, h) + boff + n * 2048 + 1024); \
;         dst[n] = __builtin_shufflevector(_p0, _p1, 0, 1, 2, 3, 4, 5, 6, 7); } } while (0)
; #define G_WAIT_V(n) asm volatile("s_waitcnt vmcnt(" #n ")" ::: "memory")
; #define G_WAIT_L(n) asm volatile("s_waitcnt lgkmcnt(" #n ")" ::: "memory")
; #define G_BAR __builtin_amdgcn_s_barrier()
; #define G_SCHED __builtin_amdgcn_sched_barrier(0)
; template <int NS, int MODE  , class Epi>
; __device__ __forceinline__ void gemm_phase(LAS unsigned char* lds, const Gemm g, const StaticOrder& S, const Epi& E) {
;     ...
;             G_WAIT_V(8); G_WAIT_L(0); G_BAR; G_MMA(1, 0, At, B0); G_MMA(1, 1, At, B1); G_BAR; G_SCHED;
;             G_LDB(B0, 1, 0); G_LDB(B1, 1, 1); G_SCHED; G_LDA(At, 1, 0); G_STAGE(G_SA(0, 1), a2 + hstep, voffA);
;             G_WAIT_V(8); G_WAIT_L(0); G_BAR; G_MMA(0, 0, At, B0); G_MMA(0, 1, At, B1); G_BAR; G_SCHED;
;             G_LDA(At, 1, 1); G_STAGE(G_SB(1, 0), b3, voffB); G_STAGE(G_SB(1, 1), b3 + hstep, voffB); G_STAGE(G_SA(1, 0), a3, voffA);
	s_nop 0
	s_waitcnt lgkmcnt(0)
	v_mfma_i32_16x16x64_i8 v[64:67], v[160:163], v[176:179], v[64:67]
	v_mfma_i32_16x16x64_i8 v[60:63], v[156:159], v[176:179], v[60:63]
	v_mfma_i32_16x16x64_i8 v[52:55], v[160:163], v[194:197], v[52:55]
	v_mfma_i32_16x16x64_i8 v[44:47], v[156:159], v[194:197], v[44:47]
	v_mfma_i32_16x16x64_i8 v[36:39], v[160:163], v[202:205], v[36:39]
	v_mfma_i32_16x16x64_i8 v[28:31], v[156:159], v[202:205], v[28:31]
	v_mfma_i32_16x16x64_i8 v[20:23], v[160:163], v[210:213], v[20:23]
	v_mfma_i32_16x16x64_i8 v[12:15], v[156:159], v[210:213], v[12:15]
	s_nop 0
	v_mfma_i32_16x16x64_i8 v[64:67], v[148:151], v[180:183], v[64:67]
	v_mfma_i32_16x16x64_i8 v[60:63], v[152:155], v[180:183], v[60:63]
	v_mfma_i32_16x16x64_i8 v[52:55], v[148:151], v[198:201], v[52:55]
	v_mfma_i32_16x16x64_i8 v[44:47], v[152:155], v[198:201], v[44:47]
	v_mfma_i32_16x16x64_i8 v[36:39], v[148:151], v[206:209], v[36:39]
	v_mfma_i32_16x16x64_i8 v[28:31], v[152:155], v[206:209], v[28:31]
	v_mfma_i32_16x16x64_i8 v[20:23], v[148:151], v[214:217], v[20:23]
	v_mfma_i32_16x16x64_i8 v[12:15], v[152:155], v[214:217], v[12:15]
	s_nop 0
	s_nop 0
	v_mfma_i32_16x16x64_i8 v[56:59], v[144:147], v[176:179], v[56:59]
	v_mfma_i32_16x16x64_i8 v[48:51], v[140:143], v[176:179], v[48:51]
	v_mfma_i32_16x16x64_i8 v[40:43], v[144:147], v[194:197], v[40:43]
	v_mfma_i32_16x16x64_i8 v[32:35], v[140:143], v[194:197], v[32:35]
	v_mfma_i32_16x16x64_i8 v[24:27], v[144:147], v[202:205], v[24:27]
	v_mfma_i32_16x16x64_i8 v[16:19], v[140:143], v[202:205], v[16:19]
	v_mfma_i32_16x16x64_i8 v[8:11], v[144:147], v[210:213], v[8:11]
	v_mfma_i32_16x16x64_i8 v[4:7], v[140:143], v[210:213], v[4:7]
	s_nop 0
	v_mfma_i32_16x16x64_i8 v[56:59], v[132:135], v[180:183], v[56:59]
	v_mfma_i32_16x16x64_i8 v[48:51], v[136:139], v[180:183], v[48:51]
	v_mfma_i32_16x16x64_i8 v[40:43], v[132:135], v[198:201], v[40:43]
	v_mfma_i32_16x16x64_i8 v[32:35], v[136:139], v[198:201], v[32:35]
	v_mfma_i32_16x16x64_i8 v[24:27], v[132:135], v[206:209], v[24:27]
	v_mfma_i32_16x16x64_i8 v[16:19], v[136:139], v[206:209], v[16:19]
	v_mfma_i32_16x16x64_i8 v[8:11], v[132:135], v[214:217], v[8:11]
	v_mfma_i32_16x16x64_i8 v[4:7], v[136:139], v[214:217], v[4:7]
	s_nop 0
	s_barrier
	s_add_i32 s25, 0, 0x18000
	s_add_i32 s27, 0, 0x1c000
	v_add_u32_e32 v144, s25, v191
	v_add_u32_e32 v160, s27, v191
	ds_read_b128 v[132:135], v144
	ds_read_b128 v[136:139], v144 offset:1024
	ds_read_b128 v[140:143], v144 offset:2048
	ds_read_b128 v[144:147], v144 offset:3072
	ds_read_b128 v[148:151], v160
	ds_read_b128 v[152:155], v160 offset:1024
	ds_read_b128 v[156:159], v160 offset:2048
	ds_read_b128 v[160:163], v160 offset:3072
	s_add_u32 s30, s80, 0x40000
	s_addc_u32 s31, s81, 0
	s_mov_b32 m0, s35
	v_lshl_add_u64 v[218:219], s[30:31], 0, v[168:169]
	ds_read_b128 v[176:179], v193 offset:32768
	ds_read_b128 v[180:183], v193 offset:33792
	ds_read_b128 v[194:197], v193 offset:34816
	ds_read_b128 v[198:201], v193 offset:35840
	ds_read_b128 v[202:205], v193 offset:36864
	ds_read_b128 v[206:209], v193 offset:37888
	ds_read_b128 v[210:213], v193 offset:38912
	ds_read_b128 v[214:217], v193 offset:39936
	global_load_lds_dwordx4 v[218:219], off
	v_lshl_add_u64 v[218:219], s[30:31], 0, v[166:167]
	s_mov_b32 m0, s59
	s_nop 0
	global_load_lds_dwordx4 v[218:219], off
	s_waitcnt vmcnt(8)
	s_waitcnt lgkmcnt(0)
	s_barrier
	s_nop 0
	s_waitcnt lgkmcnt(0)
	v_mfma_i32_16x16x64_i8 v[128:131], v[132:135], v[176:179], v[128:131]
	v_mfma_i32_16x16x64_i8 v[124:127], v[140:143], v[176:179], v[124:127]
	v_mfma_i32_16x16x64_i8 v[116:119], v[132:135], v[194:197], v[116:119]
	v_mfma_i32_16x16x64_i8 v[108:111], v[140:143], v[194:197], v[108:111]
	v_mfma_i32_16x16x64_i8 v[100:103], v[132:135], v[202:205], v[100:103]
	v_mfma_i32_16x16x64_i8 v[92:95], v[140:143], v[202:205], v[92:95]
	v_mfma_i32_16x16x64_i8 v[84:87], v[132:135], v[210:213], v[84:87]
	v_mfma_i32_16x16x64_i8 v[76:79], v[140:143], v[210:213], v[76:79]
	s_nop 0
	v_mfma_i32_16x16x64_i8 v[128:131], v[136:139], v[180:183], v[128:131]
	v_mfma_i32_16x16x64_i8 v[124:127], v[144:147], v[180:183], v[124:127]
	v_mfma_i32_16x16x64_i8 v[116:119], v[136:139], v[198:201], v[116:119]
	v_mfma_i32_16x16x64_i8 v[108:111], v[144:147], v[198:201], v[108:111]
	v_mfma_i32_16x16x64_i8 v[100:103], v[136:139], v[206:209], v[100:103]
	v_mfma_i32_16x16x64_i8 v[92:95], v[144:147], v[206:209], v[92:95]
	v_mfma_i32_16x16x64_i8 v[84:87], v[136:139], v[214:217], v[84:87]
	v_mfma_i32_16x16x64_i8 v[76:79], v[144:147], v[214:217], v[76:79]
	s_nop 0
	s_nop 0
	v_mfma_i32_16x16x64_i8 v[120:123], v[148:151], v[176:179], v[120:123]
	v_mfma_i32_16x16x64_i8 v[112:115], v[156:159], v[176:179], v[112:115]
	v_mfma_i32_16x16x64_i8 v[104:107], v[148:151], v[194:197], v[104:107]
	v_mfma_i32_16x16x64_i8 v[96:99], v[156:159], v[194:197], v[96:99]
	v_mfma_i32_16x16x64_i8 v[88:91], v[148:151], v[202:205], v[88:91]
	v_mfma_i32_16x16x64_i8 v[80:83], v[156:159], v[202:205], v[80:83]
	v_mfma_i32_16x16x64_i8 v[72:75], v[148:151], v[210:213], v[72:75]
	v_mfma_i32_16x16x64_i8 v[68:71], v[156:159], v[210:213], v[68:71]
	s_nop 0
	v_mfma_i32_16x16x64_i8 v[120:123], v[152:155], v[180:183], v[120:123]
	v_mfma_i32_16x16x64_i8 v[112:115], v[160:163], v[180:183], v[112:115]
	v_mfma_i32_16x16x64_i8 v[104:107], v[152:155], v[198:201], v[104:107]
	v_mfma_i32_16x16x64_i8 v[96:99], v[160:163], v[198:201], v[96:99]
	v_mfma_i32_16x16x64_i8 v[88:91], v[152:155], v[206:209], v[88:91]
	v_mfma_i32_16x16x64_i8 v[80:83], v[160:163], v[206:209], v[80:83]
	v_mfma_i32_16x16x64_i8 v[72:75], v[152:155], v[214:217], v[72:75]
	v_mfma_i32_16x16x64_i8 v[68:71], v[160:163], v[214:217], v[68:71]
	s_nop 0
	s_barrier
; #define G_STAGE(bufoff, gbase, voff) do { _Pragma("unroll") for (int _i = 0; _i < 2; ++_i) \
;         __builtin_amdgcn_global_load_lds((const unsigned*)((const char*)(gbase) + (voff)[_i]), (LAS unsigned*)(lds + (bufoff) + ldsw + _i * 8192), 16, 0, 0); } while (0)
; #define G_LDA(dst, b, h) do { _Pragma("unroll") for (int m = 0; m < 4; ++m) { const i32x4 _p0 = *(const LAS i32x4*)(lds + G_SA(b, h) + aoff + m * 2048), _p1 = *(const LAS i32x4*)(lds + G_SA(b, h) + aoff + m * 2048 + 1024); \
;         dst[m] = __builtin_shufflevector(_p0, _p1, 0, 1, 2, 3, 4, 5, 6, 7); } } while (0)
; #define G_WAIT_V(n) asm volatile("s_waitcnt vmcnt(" #n ")" ::: "memory")
; #define G_WAIT_L(n) asm volatile("s_waitcnt lgkmcnt(" #n ")" ::: "memory")
; #define G_BAR __builtin_amdgcn_s_barrier()
; #define G_SCHED __builtin_amdgcn_sched_barrier(0)
; template <int NS, int MODE  , class Epi>
; __device__ __forceinline__ void gemm_phase(LAS unsigned char* lds, const Gemm g, const StaticOrder& S, const Epi& E) {
;     ...
;             G_LDA(At, 1, 1); G_STAGE(G_SB(1, 0), b3, voffB); G_STAGE(G_SB(1, 1), b3 + hstep, voffB); G_STAGE(G_SA(1, 0), a3, voffA);
;             G_WAIT_V(8); G_WAIT_L(0); G_BAR; G_MMA(1, 0, At, B0); G_MMA(1, 1, At, B1); G_BAR; G_SCHED;
	s_add_i32 s25, s25, s3
	v_lshl_add_u64 v[218:219], s[76:77], 0, v[2:3]
	s_mov_b32 m0, s25
	ds_read_b128 v[176:179], v193 offset:49152
	ds_read_b128 v[180:183], v193 offset:50176
	ds_read_b128 v[194:197], v193 offset:51200
	ds_read_b128 v[198:201], v193 offset:52224
	ds_read_b128 v[202:205], v193 offset:53248
	ds_read_b128 v[206:209], v193 offset:54272
	ds_read_b128 v[210:213], v193 offset:55296
	ds_read_b128 v[214:217], v193 offset:56320
	global_load_lds_dwordx4 v[218:219], off
	s_add_i32 m0, s25, 0x2000
	s_add_u32 s30, s76, 0x40000
	v_lshl_add_u64 v[218:219], s[76:77], 0, v[164:165]
	s_addc_u32 s31, s77, 0
	s_add_i32 s25, s27, s3
	global_load_lds_dwordx4 v[218:219], off
	v_lshl_add_u64 v[218:219], s[30:31], 0, v[2:3]
	s_mov_b32 m0, s25
	s_nop 0
	global_load_lds_dwordx4 v[218:219], off
	v_lshl_add_u64 v[218:219], s[30:31], 0, v[164:165]
	s_add_i32 m0, s25, 0x2000
	s_nop 0
	global_load_lds_dwordx4 v[218:219], off
	v_lshl_add_u64 v[218:219], s[74:75], 0, v[168:169]
	s_mov_b32 m0, s2
	s_nop 0
	global_load_lds_dwordx4 v[218:219], off
	v_lshl_add_u64 v[218:219], s[74:75], 0, v[166:167]
	s_mov_b32 m0, s86
	s_nop 0
	global_load_lds_dwordx4 v[218:219], off
	s_waitcnt vmcnt(8)
	s_waitcnt lgkmcnt(0)
	s_barrier
	s_nop 0
	s_waitcnt lgkmcnt(0)
	v_mfma_i32_16x16x64_i8 v[64:67], v[132:135], v[176:179], v[64:67]
	v_mfma_i32_16x16x64_i8 v[60:63], v[140:143], v[176:179], v[60:63]
	v_mfma_i32_16x16x64_i8 v[52:55], v[132:135], v[194:197], v[52:55]
	v_mfma_i32_16x16x64_i8 v[44:47], v[140:143], v[194:197], v[44:47]
	v_mfma_i32_16x16x64_i8 v[36:39], v[132:135], v[202:205], v[36:39]
	v_mfma_i32_16x16x64_i8 v[28:31], v[140:143], v[202:205], v[28:31]
	v_mfma_i32_16x16x64_i8 v[20:23], v[132:135], v[210:213], v[20:23]
	v_mfma_i32_16x16x64_i8 v[12:15], v[140:143], v[210:213], v[12:15]
	s_nop 0
	v_mfma_i32_16x16x64_i8 v[64:67], v[136:139], v[180:183], v[64:67]
	v_mfma_i32_16x16x64_i8 v[60:63], v[144:147], v[180:183], v[60:63]
	v_mfma_i32_16x16x64_i8 v[52:55], v[136:139], v[198:201], v[52:55]
	v_mfma_i32_16x16x64_i8 v[44:47], v[144:147], v[198:201], v[44:47]
	v_mfma_i32_16x16x64_i8 v[36:39], v[136:139], v[206:209], v[36:39]
	v_mfma_i32_16x16x64_i8 v[28:31], v[144:147], v[206:209], v[28:31]
	v_mfma_i32_16x16x64_i8 v[20:23], v[136:139], v[214:217], v[20:23]
	v_mfma_i32_16x16x64_i8 v[12:15], v[144:147], v[214:217], v[12:15]
	s_nop 0
	s_nop 0
	v_mfma_i32_16x16x64_i8 v[56:59], v[148:151], v[176:179], v[56:59]
	v_mfma_i32_16x16x64_i8 v[48:51], v[156:159], v[176:179], v[48:51]
	v_mfma_i32_16x16x64_i8 v[40:43], v[148:151], v[194:197], v[40:43]
	v_mfma_i32_16x16x64_i8 v[32:35], v[156:159], v[194:197], v[32:35]
	v_mfma_i32_16x16x64_i8 v[24:27], v[148:151], v[202:205], v[24:27]
	v_mfma_i32_16x16x64_i8 v[16:19], v[156:159], v[202:205], v[16:19]
	v_mfma_i32_16x16x64_i8 v[8:11], v[148:151], v[210:213], v[8:11]
	v_mfma_i32_16x16x64_i8 v[4:7], v[156:159], v[210:213], v[4:7]
	s_nop 0
	v_mfma_i32_16x16x64_i8 v[56:59], v[152:155], v[180:183], v[56:59]
	v_mfma_i32_16x16x64_i8 v[48:51], v[160:163], v[180:183], v[48:51]
	v_mfma_i32_16x16x64_i8 v[40:43], v[152:155], v[198:201], v[40:43]
	v_mfma_i32_16x16x64_i8 v[32:35], v[160:163], v[198:201], v[32:35]
	v_mfma_i32_16x16x64_i8 v[24:27], v[152:155], v[206:209], v[24:27]
	v_mfma_i32_16x16x64_i8 v[16:19], v[160:163], v[206:209], v[16:19]
	v_mfma_i32_16x16x64_i8 v[8:11], v[152:155], v[214:217], v[8:11]
	v_mfma_i32_16x16x64_i8 v[4:7], v[160:163], v[214:217], v[4:7]
	s_nop 0
	s_barrier
	s_add_i32 s21, s21, 2
	s_add_u32 s72, s72, 0x100
	s_addc_u32 s73, s73, 0
	s_cmp_gt_u32 s21, 13
	s_cbranch_scc1 .LBB0_736

; #define G_STAGE(bufoff, gbase, voff) do { _Pragma("unroll") for (int _i = 0; _i < 2; ++_i) \
;         __builtin_amdgcn_global_load_lds((const unsigned*)((const char*)(gbase) + (voff)[_i]), (LAS unsigned*)(lds + (bufoff) + ldsw + _i * 8192), 16, 0, 0); } while (0)
; #define G_LDA(dst, b, h) do { _Pragma("unroll") for (int m = 0; m < 4; ++m) { const i32x4 _p0 = *(const LAS i32x4*)(lds + G_SA(b, h) + aoff + m * 2048), _p1 = *(const LAS i32x4*)(lds + G_SA(b, h) + aoff + m * 2048 + 1024); \
;         dst[m] = __builtin_shufflevector(_p0, _p1, 0, 1, 2, 3, 4, 5, 6, 7); } } while (0)
; #define G_LDB(dst, b, h) do { _Pragma("unroll") for (int n = 0; n < 2; ++n) { const i32x4 _p0 = *(const LAS i32x4*)(lds + G_SB(b, h) + boff + n * 2048), _p1 = *(const LAS i32x4*)(lds + G_SB(b, h) + boff + n * 2048 + 1024); \
;         dst[n] = __builtin_shufflevector(_p0, _p1, 0, 1, 2, 3, 4, 5, 6, 7); } } while (0)
; #define G_WAIT_V(n) asm volatile("s_waitcnt vmcnt(" #n ")" ::: "memory")
; #define G_WAIT_L(n) asm volatile("s_waitcnt lgkmcnt(" #n ")" ::: "memory")
; #define G_BAR __builtin_amdgcn_s_barrier()
; #define G_SCHED __builtin_amdgcn_sched_barrier(0)
; template <int NS, int MODE  , class Epi>
; __device__ __forceinline__ void gemm_phase(LAS unsigned char* lds, const Gemm g, const StaticOrder& S, const Epi& E) {
;     ...
;             if (G_SP2) {
;             G_LDB(B0, 0, 0); G_LDB(B1, 0, 1); G_SCHED; G_LDA(At, 0, 0); G_STAGE(G_SA(1, 1), a1 + hstep, voffA);
;             G_WAIT_V(8); G_WAIT_L(0); G_BAR; G_MMA(0, 0, At, B0); G_MMA(0, 1, At, B1); G_BAR; G_SCHED;
;             G_LDA(At, 0, 1); G_STAGE(G_SB(0, 0), b2, voffB); G_STAGE(G_SB(0, 1), b2 + hstep, voffB); G_STAGE(G_SA(0, 0), a2, voffA);
;             G_WAIT_V(8); G_WAIT_L(0); G_BAR; G_MMA(1, 0, At, B0); G_MMA(1, 1, At, B1); G_BAR; G_SCHED;
.LBB0_753:
	s_add_i32 s25, 0, 0x10000
	s_add_i32 s27, 0, 0x14000
	v_add_u32_e32 v162, s25, v147
	v_add_u32_e32 v178, s27, v147
	ds_read_b128 v[150:153], v162
	ds_read_b128 v[154:157], v162 offset:1024
	ds_read_b128 v[158:161], v162 offset:2048
	ds_read_b128 v[162:165], v162 offset:3072
	ds_read_b128 v[166:169], v178
	ds_read_b128 v[170:173], v178 offset:1024
	ds_read_b128 v[174:177], v178 offset:2048
	ds_read_b128 v[178:181], v178 offset:3072
	v_lshl_add_u64 v[182:183], v[142:143], 0, s[72:73]
	s_add_i32 m0, s3, 0xc000
	ds_read_b128 v[190:193], v149
	ds_read_b128 v[194:197], v149 offset:1024
	ds_read_b128 v[198:201], v149 offset:2048
	ds_read_b128 v[202:205], v149 offset:3072
	ds_read_b128 v[206:209], v149 offset:4096
	ds_read_b128 v[210:213], v149 offset:5120
	ds_read_b128 v[214:217], v149 offset:6144
	ds_read_b128 v[218:221], v149 offset:7168
	global_load_lds_dwordx4 v[182:183], off
	v_lshl_add_u64 v[182:183], v[144:145], 0, s[72:73]
	s_add_i32 m0, s3, 0xe000
	s_nop 0
	global_load_lds_dwordx4 v[182:183], off
	s_waitcnt vmcnt(8)
	s_waitcnt lgkmcnt(0)
	s_barrier
	s_nop 0
	s_waitcnt lgkmcnt(0)
	v_mfma_f32_16x16x32_f16 v[128:131], v[150:153], v[190:193], v[128:131]
	v_mfma_f32_16x16x32_f16 v[124:127], v[158:161], v[190:193], v[124:127]
	v_mfma_f32_16x16x32_f16 v[116:119], v[150:153], v[198:201], v[116:119]
	v_mfma_f32_16x16x32_f16 v[108:111], v[158:161], v[198:201], v[108:111]
	v_mfma_f32_16x16x32_f16 v[100:103], v[150:153], v[206:209], v[100:103]
	v_mfma_f32_16x16x32_f16 v[92:95], v[158:161], v[206:209], v[92:95]
	v_mfma_f32_16x16x32_f16 v[84:87], v[150:153], v[214:217], v[84:87]
	v_mfma_f32_16x16x32_f16 v[76:79], v[158:161], v[214:217], v[76:79]
	v_mfma_f32_16x16x32_f16 v[128:131], v[154:157], v[194:197], v[128:131]
	v_mfma_f32_16x16x32_f16 v[124:127], v[162:165], v[194:197], v[124:127]
	v_mfma_f32_16x16x32_f16 v[116:119], v[154:157], v[202:205], v[116:119]
	v_mfma_f32_16x16x32_f16 v[108:111], v[162:165], v[202:205], v[108:111]
	v_mfma_f32_16x16x32_f16 v[100:103], v[154:157], v[210:213], v[100:103]
	v_mfma_f32_16x16x32_f16 v[92:95], v[162:165], v[210:213], v[92:95]
	v_mfma_f32_16x16x32_f16 v[84:87], v[154:157], v[218:221], v[84:87]
	v_mfma_f32_16x16x32_f16 v[76:79], v[162:165], v[218:221], v[76:79]
	s_nop 0
	s_nop 0
	v_mfma_f32_16x16x32_f16 v[120:123], v[166:169], v[190:193], v[120:123]
	v_mfma_f32_16x16x32_f16 v[112:115], v[174:177], v[190:193], v[112:115]
	v_mfma_f32_16x16x32_f16 v[104:107], v[166:169], v[198:201], v[104:107]
	v_mfma_f32_16x16x32_f16 v[96:99], v[174:177], v[198:201], v[96:99]
	v_mfma_f32_16x16x32_f16 v[88:91], v[166:169], v[206:209], v[88:91]
	v_mfma_f32_16x16x32_f16 v[80:83], v[174:177], v[206:209], v[80:83]
	v_mfma_f32_16x16x32_f16 v[72:75], v[166:169], v[214:217], v[72:75]
	v_mfma_f32_16x16x32_f16 v[68:71], v[174:177], v[214:217], v[68:71]
	v_mfma_f32_16x16x32_f16 v[120:123], v[170:173], v[194:197], v[120:123]
	v_mfma_f32_16x16x32_f16 v[112:115], v[178:181], v[194:197], v[112:115]
	v_mfma_f32_16x16x32_f16 v[104:107], v[170:173], v[202:205], v[104:107]
	v_mfma_f32_16x16x32_f16 v[96:99], v[178:181], v[202:205], v[96:99]
	v_mfma_f32_16x16x32_f16 v[88:91], v[170:173], v[210:213], v[88:91]
	v_mfma_f32_16x16x32_f16 v[80:83], v[178:181], v[210:213], v[80:83]
	v_mfma_f32_16x16x32_f16 v[72:75], v[170:173], v[218:221], v[72:75]
	v_mfma_f32_16x16x32_f16 v[68:71], v[178:181], v[218:221], v[68:71]
	s_nop 0
	s_barrier
	s_add_i32 s25, s25, s2
	v_lshl_add_u64 v[182:183], s[90:91], 0, v[2:3]
	s_mov_b32 m0, s25
	ds_read_b128 v[190:193], v149 offset:16384
	ds_read_b128 v[194:197], v149 offset:17408
	ds_read_b128 v[198:201], v149 offset:18432
	ds_read_b128 v[202:205], v149 offset:19456
	ds_read_b128 v[206:209], v149 offset:20480
	ds_read_b128 v[210:213], v149 offset:21504
	ds_read_b128 v[214:217], v149 offset:22528
	ds_read_b128 v[218:221], v149 offset:23552
	global_load_lds_dwordx4 v[182:183], off
	s_add_i32 m0, s25, 0x2000
	s_add_u32 s30, s90, 0x80000
	v_lshl_add_u64 v[182:183], s[90:91], 0, v[132:133]
	s_addc_u32 s31, s91, 0
	s_add_i32 s25, s27, s2
	global_load_lds_dwordx4 v[182:183], off
	v_lshl_add_u64 v[182:183], s[30:31], 0, v[2:3]
	s_mov_b32 m0, s25
	s_nop 0
	global_load_lds_dwordx4 v[182:183], off
	v_lshl_add_u64 v[182:183], s[30:31], 0, v[132:133]
	s_add_i32 m0, s25, 0x2000
	s_nop 0
	global_load_lds_dwordx4 v[182:183], off
	v_lshl_add_u64 v[182:183], s[80:81], 0, v[136:137]
	s_mov_b32 m0, s3
	s_nop 0
	global_load_lds_dwordx4 v[182:183], off
	v_lshl_add_u64 v[182:183], s[80:81], 0, v[134:135]
	s_mov_b32 m0, s18
	s_nop 0
	global_load_lds_dwordx4 v[182:183], off
	s_waitcnt vmcnt(8)
	s_waitcnt lgkmcnt(0)
	s_barrier
; #define G_STAGE(bufoff, gbase, voff) do { _Pragma("unroll") for (int _i = 0; _i < 2; ++_i) \
;         __builtin_amdgcn_global_load_lds((const unsigned*)((const char*)(gbase) + (voff)[_i]), (LAS unsigned*)(lds + (bufoff) + ldsw + _i * 8192), 16, 0, 0); } while (0)
; #define G_LDA(dst, b, h) do { _Pragma("unroll") for (int m = 0; m < 4; ++m) { const i32x4 _p0 = *(const LAS i32x4*)(lds + G_SA(b, h) + aoff + m * 2048), _p1 = *(const LAS i32x4*)(lds + G_SA(b, h) + aoff + m * 2048 + 1024); \
;         dst[m] = __builtin_shufflevector(_p0, _p1, 0, 1, 2, 3, 4, 5, 6, 7); } } while (0)
; #define G_LDB(dst, b, h) do { _Pragma("unroll") for (int n = 0; n < 2; ++n) { const i32x4 _p0 = *(const LAS i32x4*)(lds + G_SB(b, h) + boff + n * 2048), _p1 = *(const LAS i32x4*)(lds + G_SB(b, h) + boff + n * 2048 + 1024); \
;         dst[n] = __builtin_shufflevector(_p0, _p1, 0, 1, 2, 3, 4, 5, 6, 7); } } while (0)
; #define G_WAIT_V(n) asm volatile("s_waitcnt vmcnt(" #n ")" ::: "memory")
; #define G_WAIT_L(n) asm volatile("s_waitcnt lgkmcnt(" #n ")" ::: "memory")
; #define G_BAR __builtin_amdgcn_s_barrier()
; #define G_SCHED __builtin_amdgcn_sched_barrier(0)
; template <int NS, int MODE  , class Epi>
; __device__ __forceinline__ void gemm_phase(LAS unsigned char* lds, const Gemm g, const StaticOrder& S, const Epi& E) {
;     ...
;             G_WAIT_V(8); G_WAIT_L(0); G_BAR; G_MMA(1, 0, At, B0); G_MMA(1, 1, At, B1); G_BAR; G_SCHED;
;             G_LDB(B0, 1, 0); G_LDB(B1, 1, 1); G_SCHED; G_LDA(At, 1, 0); G_STAGE(G_SA(0, 1), a2 + hstep, voffA);
;             G_WAIT_V(8); G_WAIT_L(0); G_BAR; G_MMA(0, 0, At, B0); G_MMA(0, 1, At, B1); G_BAR; G_SCHED;
;             G_LDA(At, 1, 1); G_STAGE(G_SB(1, 0), b3, voffB); G_STAGE(G_SB(1, 1), b3 + hstep, voffB); G_STAGE(G_SA(1, 0), a3, voffA);
	s_nop 0
	s_waitcnt lgkmcnt(0)
	v_mfma_f32_16x16x32_f16 v[64:67], v[150:153], v[190:193], v[64:67]
	v_mfma_f32_16x16x32_f16 v[60:63], v[158:161], v[190:193], v[60:63]
	v_mfma_f32_16x16x32_f16 v[52:55], v[150:153], v[198:201], v[52:55]
	v_mfma_f32_16x16x32_f16 v[44:47], v[158:161], v[198:201], v[44:47]
	v_mfma_f32_16x16x32_f16 v[36:39], v[150:153], v[206:209], v[36:39]
	v_mfma_f32_16x16x32_f16 v[28:31], v[158:161], v[206:209], v[28:31]
	v_mfma_f32_16x16x32_f16 v[20:23], v[150:153], v[214:217], v[20:23]
	v_mfma_f32_16x16x32_f16 v[12:15], v[158:161], v[214:217], v[12:15]
	v_mfma_f32_16x16x32_f16 v[64:67], v[154:157], v[194:197], v[64:67]
	v_mfma_f32_16x16x32_f16 v[60:63], v[162:165], v[194:197], v[60:63]
	v_mfma_f32_16x16x32_f16 v[52:55], v[154:157], v[202:205], v[52:55]
	v_mfma_f32_16x16x32_f16 v[44:47], v[162:165], v[202:205], v[44:47]
	v_mfma_f32_16x16x32_f16 v[36:39], v[154:157], v[210:213], v[36:39]
	v_mfma_f32_16x16x32_f16 v[28:31], v[162:165], v[210:213], v[28:31]
	v_mfma_f32_16x16x32_f16 v[20:23], v[154:157], v[218:221], v[20:23]
	v_mfma_f32_16x16x32_f16 v[12:15], v[162:165], v[218:221], v[12:15]
	s_nop 0
	s_nop 0
	v_mfma_f32_16x16x32_f16 v[56:59], v[166:169], v[190:193], v[56:59]
	v_mfma_f32_16x16x32_f16 v[48:51], v[174:177], v[190:193], v[48:51]
	v_mfma_f32_16x16x32_f16 v[40:43], v[166:169], v[198:201], v[40:43]
	v_mfma_f32_16x16x32_f16 v[32:35], v[174:177], v[198:201], v[32:35]
	v_mfma_f32_16x16x32_f16 v[24:27], v[166:169], v[206:209], v[24:27]
	v_mfma_f32_16x16x32_f16 v[16:19], v[174:177], v[206:209], v[16:19]
	v_mfma_f32_16x16x32_f16 v[8:11], v[166:169], v[214:217], v[8:11]
	v_mfma_f32_16x16x32_f16 v[4:7], v[174:177], v[214:217], v[4:7]
	v_mfma_f32_16x16x32_f16 v[56:59], v[170:173], v[194:197], v[56:59]
	v_mfma_f32_16x16x32_f16 v[48:51], v[178:181], v[194:197], v[48:51]
	v_mfma_f32_16x16x32_f16 v[40:43], v[170:173], v[202:205], v[40:43]
	v_mfma_f32_16x16x32_f16 v[32:35], v[178:181], v[202:205], v[32:35]
	v_mfma_f32_16x16x32_f16 v[24:27], v[170:173], v[210:213], v[24:27]
	v_mfma_f32_16x16x32_f16 v[16:19], v[178:181], v[210:213], v[16:19]
	v_mfma_f32_16x16x32_f16 v[8:11], v[170:173], v[218:221], v[8:11]
	v_mfma_f32_16x16x32_f16 v[4:7], v[178:181], v[218:221], v[4:7]
	s_nop 0
	s_barrier
	s_add_i32 s25, 0, 0x18000
	s_add_i32 s27, 0, 0x1c000
	v_add_u32_e32 v162, s25, v147
	v_add_u32_e32 v178, s27, v147
	ds_read_b128 v[150:153], v162
	ds_read_b128 v[154:157], v162 offset:1024
	ds_read_b128 v[158:161], v162 offset:2048
	ds_read_b128 v[162:165], v162 offset:3072
	ds_read_b128 v[166:169], v178
	ds_read_b128 v[170:173], v178 offset:1024
	ds_read_b128 v[174:177], v178 offset:2048
	ds_read_b128 v[178:181], v178 offset:3072
	s_add_u32 s30, s80, 0x80000
	s_addc_u32 s31, s81, 0
	s_mov_b32 m0, s19
	v_lshl_add_u64 v[182:183], s[30:31], 0, v[136:137]
	ds_read_b128 v[190:193], v149 offset:32768
	ds_read_b128 v[194:197], v149 offset:33792
	ds_read_b128 v[198:201], v149 offset:34816
	ds_read_b128 v[202:205], v149 offset:35840
	ds_read_b128 v[206:209], v149 offset:36864
	ds_read_b128 v[210:213], v149 offset:37888
	ds_read_b128 v[214:217], v149 offset:38912
	ds_read_b128 v[218:221], v149 offset:39936
	global_load_lds_dwordx4 v[182:183], off
	v_lshl_add_u64 v[182:183], s[30:31], 0, v[134:135]
	s_mov_b32 m0, s29
	s_nop 0
	global_load_lds_dwordx4 v[182:183], off
	s_waitcnt vmcnt(8)
	s_waitcnt lgkmcnt(0)
	s_barrier
	s_nop 0
	s_waitcnt lgkmcnt(0)
	v_mfma_f32_16x16x32_f16 v[128:131], v[150:153], v[190:193], v[128:131]
	v_mfma_f32_16x16x32_f16 v[124:127], v[158:161], v[190:193], v[124:127]
	v_mfma_f32_16x16x32_f16 v[116:119], v[150:153], v[198:201], v[116:119]
	v_mfma_f32_16x16x32_f16 v[108:111], v[158:161], v[198:201], v[108:111]
	v_mfma_f32_16x16x32_f16 v[100:103], v[150:153], v[206:209], v[100:103]
	v_mfma_f32_16x16x32_f16 v[92:95], v[158:161], v[206:209], v[92:95]
	v_mfma_f32_16x16x32_f16 v[84:87], v[150:153], v[214:217], v[84:87]
	v_mfma_f32_16x16x32_f16 v[76:79], v[158:161], v[214:217], v[76:79]
	v_mfma_f32_16x16x32_f16 v[128:131], v[154:157], v[194:197], v[128:131]
	v_mfma_f32_16x16x32_f16 v[124:127], v[162:165], v[194:197], v[124:127]
	v_mfma_f32_16x16x32_f16 v[116:119], v[154:157], v[202:205], v[116:119]
	v_mfma_f32_16x16x32_f16 v[108:111], v[162:165], v[202:205], v[108:111]
	v_mfma_f32_16x16x32_f16 v[100:103], v[154:157], v[210:213], v[100:103]
	v_mfma_f32_16x16x32_f16 v[92:95], v[162:165], v[210:213], v[92:95]
	v_mfma_f32_16x16x32_f16 v[84:87], v[154:157], v[218:221], v[84:87]
	v_mfma_f32_16x16x32_f16 v[76:79], v[162:165], v[218:221], v[76:79]
	s_nop 0
	s_nop 0
	v_mfma_f32_16x16x32_f16 v[120:123], v[166:169], v[190:193], v[120:123]
	v_mfma_f32_16x16x32_f16 v[112:115], v[174:177], v[190:193], v[112:115]
	v_mfma_f32_16x16x32_f16 v[104:107], v[166:169], v[198:201], v[104:107]
	v_mfma_f32_16x16x32_f16 v[96:99], v[174:177], v[198:201], v[96:99]
	v_mfma_f32_16x16x32_f16 v[88:91], v[166:169], v[206:209], v[88:91]
	v_mfma_f32_16x16x32_f16 v[80:83], v[174:177], v[206:209], v[80:83]
	v_mfma_f32_16x16x32_f16 v[72:75], v[166:169], v[214:217], v[72:75]
	v_mfma_f32_16x16x32_f16 v[68:71], v[174:177], v[214:217], v[68:71]
	v_mfma_f32_16x16x32_f16 v[120:123], v[170:173], v[194:197], v[120:123]
	v_mfma_f32_16x16x32_f16 v[112:115], v[178:181], v[194:197], v[112:115]
	v_mfma_f32_16x16x32_f16 v[104:107], v[170:173], v[202:205], v[104:107]
	v_mfma_f32_16x16x32_f16 v[96:99], v[178:181], v[202:205], v[96:99]
	v_mfma_f32_16x16x32_f16 v[88:91], v[170:173], v[210:213], v[88:91]
	v_mfma_f32_16x16x32_f16 v[80:83], v[178:181], v[210:213], v[80:83]
	v_mfma_f32_16x16x32_f16 v[72:75], v[170:173], v[218:221], v[72:75]
	v_mfma_f32_16x16x32_f16 v[68:71], v[178:181], v[218:221], v[68:71]
	s_nop 0
	s_barrier
; #define G_STAGE(bufoff, gbase, voff) do { _Pragma("unroll") for (int _i = 0; _i < 2; ++_i) \
;         __builtin_amdgcn_global_load_lds((const unsigned*)((const char*)(gbase) + (voff)[_i]), (LAS unsigned*)(lds + (bufoff) + ldsw + _i * 8192), 16, 0, 0); } while (0)
; #define G_LDA(dst, b, h) do { _Pragma("unroll") for (int m = 0; m < 4; ++m) { const i32x4 _p0 = *(const LAS i32x4*)(lds + G_SA(b, h) + aoff + m * 2048), _p1 = *(const LAS i32x4*)(lds + G_SA(b, h) + aoff + m * 2048 + 1024); \
;         dst[m] = __builtin_shufflevector(_p0, _p1, 0, 1, 2, 3, 4, 5, 6, 7); } } while (0)
; #define G_WAIT_V(n) asm volatile("s_waitcnt vmcnt(" #n ")" ::: "memory")
; #define G_WAIT_L(n) asm volatile("s_waitcnt lgkmcnt(" #n ")" ::: "memory")
; #define G_BAR __builtin_amdgcn_s_barrier()
; #define G_SCHED __builtin_amdgcn_sched_barrier(0)
; template <int NS, int MODE  , class Epi>
; __device__ __forceinline__ void gemm_phase(LAS unsigned char* lds, const Gemm g, const StaticOrder& S, const Epi& E) {
;     ...
;             G_LDA(At, 1, 1); G_STAGE(G_SB(1, 0), b3, voffB); G_STAGE(G_SB(1, 1), b3 + hstep, voffB); G_STAGE(G_SA(1, 0), a3, voffA);
;             G_WAIT_V(8); G_WAIT_L(0); G_BAR; G_MMA(1, 0, At, B0); G_MMA(1, 1, At, B1); G_BAR; G_SCHED;
	s_add_i32 s25, s25, s2
	v_lshl_add_u64 v[182:183], s[76:77], 0, v[2:3]
	s_mov_b32 m0, s25
	ds_read_b128 v[190:193], v149 offset:49152
	ds_read_b128 v[194:197], v149 offset:50176
	ds_read_b128 v[198:201], v149 offset:51200
	ds_read_b128 v[202:205], v149 offset:52224
	ds_read_b128 v[206:209], v149 offset:53248
	ds_read_b128 v[210:213], v149 offset:54272
	ds_read_b128 v[214:217], v149 offset:55296
	ds_read_b128 v[218:221], v149 offset:56320
	global_load_lds_dwordx4 v[182:183], off
	s_add_i32 m0, s25, 0x2000
	s_add_u32 s30, s76, 0x80000
	v_lshl_add_u64 v[182:183], s[76:77], 0, v[132:133]
	s_addc_u32 s31, s77, 0
	s_add_i32 s25, s27, s2
	global_load_lds_dwordx4 v[182:183], off
	v_lshl_add_u64 v[182:183], s[30:31], 0, v[2:3]
	s_mov_b32 m0, s25
	s_nop 0
	global_load_lds_dwordx4 v[182:183], off
	v_lshl_add_u64 v[182:183], s[30:31], 0, v[132:133]
	s_add_i32 m0, s25, 0x2000
	s_nop 0
	global_load_lds_dwordx4 v[182:183], off
	v_lshl_add_u64 v[182:183], s[74:75], 0, v[136:137]
	s_mov_b32 m0, s35
	s_nop 0
	global_load_lds_dwordx4 v[182:183], off
	v_lshl_add_u64 v[182:183], s[74:75], 0, v[134:135]
	s_mov_b32 m0, s59
	s_nop 0
	global_load_lds_dwordx4 v[182:183], off
	s_waitcnt vmcnt(8)
	s_waitcnt lgkmcnt(0)
	s_barrier
	s_nop 0
	s_waitcnt lgkmcnt(0)
	v_mfma_f32_16x16x32_f16 v[64:67], v[150:153], v[190:193], v[64:67]
	v_mfma_f32_16x16x32_f16 v[60:63], v[158:161], v[190:193], v[60:63]
	v_mfma_f32_16x16x32_f16 v[52:55], v[150:153], v[198:201], v[52:55]
	v_mfma_f32_16x16x32_f16 v[44:47], v[158:161], v[198:201], v[44:47]
	v_mfma_f32_16x16x32_f16 v[36:39], v[150:153], v[206:209], v[36:39]
	v_mfma_f32_16x16x32_f16 v[28:31], v[158:161], v[206:209], v[28:31]
	v_mfma_f32_16x16x32_f16 v[20:23], v[150:153], v[214:217], v[20:23]
	v_mfma_f32_16x16x32_f16 v[12:15], v[158:161], v[214:217], v[12:15]
	v_mfma_f32_16x16x32_f16 v[64:67], v[154:157], v[194:197], v[64:67]
	v_mfma_f32_16x16x32_f16 v[60:63], v[162:165], v[194:197], v[60:63]
	v_mfma_f32_16x16x32_f16 v[52:55], v[154:157], v[202:205], v[52:55]
	v_mfma_f32_16x16x32_f16 v[44:47], v[162:165], v[202:205], v[44:47]
	v_mfma_f32_16x16x32_f16 v[36:39], v[154:157], v[210:213], v[36:39]
	v_mfma_f32_16x16x32_f16 v[28:31], v[162:165], v[210:213], v[28:31]
	v_mfma_f32_16x16x32_f16 v[20:23], v[154:157], v[218:221], v[20:23]
	v_mfma_f32_16x16x32_f16 v[12:15], v[162:165], v[218:221], v[12:15]
	s_nop 0
	s_nop 0
	v_mfma_f32_16x16x32_f16 v[56:59], v[166:169], v[190:193], v[56:59]
	v_mfma_f32_16x16x32_f16 v[48:51], v[174:177], v[190:193], v[48:51]
	v_mfma_f32_16x16x32_f16 v[40:43], v[166:169], v[198:201], v[40:43]
	v_mfma_f32_16x16x32_f16 v[32:35], v[174:177], v[198:201], v[32:35]
	v_mfma_f32_16x16x32_f16 v[24:27], v[166:169], v[206:209], v[24:27]
	v_mfma_f32_16x16x32_f16 v[16:19], v[174:177], v[206:209], v[16:19]
	v_mfma_f32_16x16x32_f16 v[8:11], v[166:169], v[214:217], v[8:11]
	v_mfma_f32_16x16x32_f16 v[4:7], v[174:177], v[214:217], v[4:7]
	v_mfma_f32_16x16x32_f16 v[56:59], v[170:173], v[194:197], v[56:59]
	v_mfma_f32_16x16x32_f16 v[48:51], v[178:181], v[194:197], v[48:51]
	v_mfma_f32_16x16x32_f16 v[40:43], v[170:173], v[202:205], v[40:43]
	v_mfma_f32_16x16x32_f16 v[32:35], v[178:181], v[202:205], v[32:35]
	v_mfma_f32_16x16x32_f16 v[24:27], v[170:173], v[210:213], v[24:27]
	v_mfma_f32_16x16x32_f16 v[16:19], v[178:181], v[210:213], v[16:19]
	v_mfma_f32_16x16x32_f16 v[8:11], v[170:173], v[218:221], v[8:11]
	v_mfma_f32_16x16x32_f16 v[4:7], v[178:181], v[218:221], v[4:7]
	s_nop 0
	s_barrier
	s_add_i32 s21, s21, 2
	s_add_u32 s72, s72, 0x100
	s_addc_u32 s73, s73, 0
	s_cmp_gt_u32 s21, 29
	s_cbranch_scc1 .LBB0_756

; #define G_STAGE(bufoff, gbase, voff) do { _Pragma("unroll") for (int _i = 0; _i < 2; ++_i) \
;         __builtin_amdgcn_global_load_lds((const unsigned*)((const char*)(gbase) + (voff)[_i]), (LAS unsigned*)(lds + (bufoff) + ldsw + _i * 8192), 16, 0, 0); } while (0)
; #define G_LDA(dst, b, h) do { _Pragma("unroll") for (int m = 0; m < 4; ++m) { const i32x4 _p0 = *(const LAS i32x4*)(lds + G_SA(b, h) + aoff + m * 2048), _p1 = *(const LAS i32x4*)(lds + G_SA(b, h) + aoff + m * 2048 + 1024); \
;         dst[m] = __builtin_shufflevector(_p0, _p1, 0, 1, 2, 3, 4, 5, 6, 7); } } while (0)
; #define G_LDB(dst, b, h) do { _Pragma("unroll") for (int n = 0; n < 2; ++n) { const i32x4 _p0 = *(const LAS i32x4*)(lds + G_SB(b, h) + boff + n * 2048), _p1 = *(const LAS i32x4*)(lds + G_SB(b, h) + boff + n * 2048 + 1024); \
;         dst[n] = __builtin_shufflevector(_p0, _p1, 0, 1, 2, 3, 4, 5, 6, 7); } } while (0)
; #define G_WAIT_V(n) asm volatile("s_waitcnt vmcnt(" #n ")" ::: "memory")
; #define G_WAIT_L(n) asm volatile("s_waitcnt lgkmcnt(" #n ")" ::: "memory")
; #define G_BAR __builtin_amdgcn_s_barrier()
; #define G_SCHED __builtin_amdgcn_sched_barrier(0)
; template <int NS, int MODE  , class Epi>
; __device__ __forceinline__ void gemm_phase(LAS unsigned char* lds, const Gemm g, const StaticOrder& S, const Epi& E) {
;     ...
;             if (G_SP2) {
;             G_LDB(B0, 0, 0); G_LDB(B1, 0, 1); G_SCHED; G_LDA(At, 0, 0); G_STAGE(G_SA(1, 1), a1 + hstep, voffA);
;             G_WAIT_V(8); G_WAIT_L(0); G_BAR; G_MMA(0, 0, At, B0); G_MMA(0, 1, At, B1); G_BAR; G_SCHED;
;             G_LDA(At, 0, 1); G_STAGE(G_SB(0, 0), b2, voffB); G_STAGE(G_SB(0, 1), b2 + hstep, voffB); G_STAGE(G_SA(0, 0), a2, voffA);
;             G_WAIT_V(8); G_WAIT_L(0); G_BAR; G_MMA(1, 0, At, B0); G_MMA(1, 1, At, B1); G_BAR; G_SCHED;
.LBB0_1126:
	s_add_i32 s21, 0, 0x10000
	s_add_i32 s30, 0, 0x14000
	v_add_u32_e32 v148, s21, v205
	v_add_u32_e32 v164, s30, v205
	ds_read_b128 v[136:139], v148
	ds_read_b128 v[140:143], v148 offset:1024
	ds_read_b128 v[144:147], v148 offset:2048
	ds_read_b128 v[148:151], v148 offset:3072
	ds_read_b128 v[152:155], v164
	ds_read_b128 v[156:159], v164 offset:1024
	ds_read_b128 v[160:163], v164 offset:2048
	ds_read_b128 v[164:167], v164 offset:3072
	v_lshl_add_u64 v[216:217], v[132:133], 0, s[60:61]
	s_add_i32 m0, s19, 0xc000
	ds_read_b128 v[176:179], v207
	ds_read_b128 v[180:183], v207 offset:1024
	ds_read_b128 v[188:191], v207 offset:2048
	ds_read_b128 v[192:195], v207 offset:3072
	ds_read_b128 v[196:199], v207 offset:4096
	ds_read_b128 v[200:203], v207 offset:5120
	ds_read_b128 v[208:211], v207 offset:6144
	ds_read_b128 v[212:215], v207 offset:7168
	global_load_lds_dwordx4 v[216:217], off
	v_lshl_add_u64 v[216:217], v[134:135], 0, s[60:61]
	s_add_i32 m0, s19, 0xe000
	s_nop 0
	global_load_lds_dwordx4 v[216:217], off
	s_waitcnt vmcnt(8)
	s_waitcnt lgkmcnt(0)
	s_barrier
	s_nop 0
	s_waitcnt lgkmcnt(0)
	v_mfma_f32_16x16x32_f16 v[128:131], v[136:139], v[176:179], v[128:131]
	v_mfma_f32_16x16x32_f16 v[124:127], v[144:147], v[176:179], v[124:127]
	v_mfma_f32_16x16x32_f16 v[112:115], v[136:139], v[188:191], v[112:115]
	v_mfma_f32_16x16x32_f16 v[108:111], v[144:147], v[188:191], v[108:111]
	v_mfma_f32_16x16x32_f16 v[100:103], v[136:139], v[196:199], v[100:103]
	v_mfma_f32_16x16x32_f16 v[92:95], v[144:147], v[196:199], v[92:95]
	v_mfma_f32_16x16x32_f16 v[88:91], v[136:139], v[208:211], v[88:91]
	v_mfma_f32_16x16x32_f16 v[80:83], v[144:147], v[208:211], v[80:83]
	v_mfma_f32_16x16x32_f16 v[128:131], v[140:143], v[180:183], v[128:131]
	v_mfma_f32_16x16x32_f16 v[124:127], v[148:151], v[180:183], v[124:127]
	v_mfma_f32_16x16x32_f16 v[112:115], v[140:143], v[192:195], v[112:115]
	v_mfma_f32_16x16x32_f16 v[108:111], v[148:151], v[192:195], v[108:111]
	v_mfma_f32_16x16x32_f16 v[100:103], v[140:143], v[200:203], v[100:103]
	v_mfma_f32_16x16x32_f16 v[92:95], v[148:151], v[200:203], v[92:95]
	v_mfma_f32_16x16x32_f16 v[88:91], v[140:143], v[212:215], v[88:91]
	v_mfma_f32_16x16x32_f16 v[80:83], v[148:151], v[212:215], v[80:83]
	s_nop 0
	s_nop 0
	v_mfma_f32_16x16x32_f16 v[120:123], v[152:155], v[176:179], v[120:123]
	v_mfma_f32_16x16x32_f16 v[116:119], v[160:163], v[176:179], v[116:119]
	v_mfma_f32_16x16x32_f16 v[104:107], v[152:155], v[188:191], v[104:107]
	v_mfma_f32_16x16x32_f16 v[96:99], v[160:163], v[188:191], v[96:99]
	v_mfma_f32_16x16x32_f16 v[84:87], v[152:155], v[196:199], v[84:87]
	v_mfma_f32_16x16x32_f16 v[76:79], v[160:163], v[196:199], v[76:79]
	v_mfma_f32_16x16x32_f16 v[72:75], v[152:155], v[208:211], v[72:75]
	v_mfma_f32_16x16x32_f16 v[68:71], v[160:163], v[208:211], v[68:71]
	v_mfma_f32_16x16x32_f16 v[120:123], v[156:159], v[180:183], v[120:123]
	v_mfma_f32_16x16x32_f16 v[116:119], v[164:167], v[180:183], v[116:119]
	v_mfma_f32_16x16x32_f16 v[104:107], v[156:159], v[192:195], v[104:107]
	v_mfma_f32_16x16x32_f16 v[96:99], v[164:167], v[192:195], v[96:99]
	v_mfma_f32_16x16x32_f16 v[84:87], v[156:159], v[200:203], v[84:87]
	v_mfma_f32_16x16x32_f16 v[76:79], v[164:167], v[200:203], v[76:79]
	v_mfma_f32_16x16x32_f16 v[72:75], v[156:159], v[212:215], v[72:75]
	v_mfma_f32_16x16x32_f16 v[68:71], v[164:167], v[212:215], v[68:71]
	s_nop 0
	s_barrier
	s_add_i32 s21, s21, s18
	v_lshl_add_u64 v[216:217], s[68:69], 0, v[2:3]
	s_mov_b32 m0, s21
	ds_read_b128 v[176:179], v207 offset:16384
	ds_read_b128 v[180:183], v207 offset:17408
	ds_read_b128 v[188:191], v207 offset:18432
	ds_read_b128 v[192:195], v207 offset:19456
	ds_read_b128 v[196:199], v207 offset:20480
	ds_read_b128 v[200:203], v207 offset:21504
	ds_read_b128 v[208:211], v207 offset:22528
	ds_read_b128 v[212:215], v207 offset:23552
	global_load_lds_dwordx4 v[216:217], off
	s_add_i32 m0, s21, 0x2000
	s_add_u32 s24, s68, 0x80000
	v_lshl_add_u64 v[216:217], s[68:69], 0, v[168:169]
	s_addc_u32 s25, s69, 0
	s_add_i32 s21, s30, s18
	global_load_lds_dwordx4 v[216:217], off
	v_lshl_add_u64 v[216:217], s[24:25], 0, v[2:3]
	s_mov_b32 m0, s21
	s_nop 0
	global_load_lds_dwordx4 v[216:217], off
	v_lshl_add_u64 v[216:217], s[24:25], 0, v[168:169]
	s_add_i32 m0, s21, 0x2000
	s_nop 0
	global_load_lds_dwordx4 v[216:217], off
	v_lshl_add_u64 v[216:217], s[66:67], 0, v[172:173]
	s_mov_b32 m0, s19
	s_nop 0
	global_load_lds_dwordx4 v[216:217], off
	v_lshl_add_u64 v[216:217], s[66:67], 0, v[170:171]
	s_mov_b32 m0, s29
	s_nop 0
	global_load_lds_dwordx4 v[216:217], off
	s_waitcnt vmcnt(8)
	s_waitcnt lgkmcnt(0)
	s_barrier
; #define G_STAGE(bufoff, gbase, voff) do { _Pragma("unroll") for (int _i = 0; _i < 2; ++_i) \
;         __builtin_amdgcn_global_load_lds((const unsigned*)((const char*)(gbase) + (voff)[_i]), (LAS unsigned*)(lds + (bufoff) + ldsw + _i * 8192), 16, 0, 0); } while (0)
; #define G_LDA(dst, b, h) do { _Pragma("unroll") for (int m = 0; m < 4; ++m) { const i32x4 _p0 = *(const LAS i32x4*)(lds + G_SA(b, h) + aoff + m * 2048), _p1 = *(const LAS i32x4*)(lds + G_SA(b, h) + aoff + m * 2048 + 1024); \
;         dst[m] = __builtin_shufflevector(_p0, _p1, 0, 1, 2, 3, 4, 5, 6, 7); } } while (0)
; #define G_LDB(dst, b, h) do { _Pragma("unroll") for (int n = 0; n < 2; ++n) { const i32x4 _p0 = *(const LAS i32x4*)(lds + G_SB(b, h) + boff + n * 2048), _p1 = *(const LAS i32x4*)(lds + G_SB(b, h) + boff + n * 2048 + 1024); \
;         dst[n] = __builtin_shufflevector(_p0, _p1, 0, 1, 2, 3, 4, 5, 6, 7); } } while (0)
; #define G_WAIT_V(n) asm volatile("s_waitcnt vmcnt(" #n ")" ::: "memory")
; #define G_WAIT_L(n) asm volatile("s_waitcnt lgkmcnt(" #n ")" ::: "memory")
; #define G_BAR __builtin_amdgcn_s_barrier()
; #define G_SCHED __builtin_amdgcn_sched_barrier(0)
; template <int NS, int MODE  , class Epi>
; __device__ __forceinline__ void gemm_phase(LAS unsigned char* lds, const Gemm g, const StaticOrder& S, const Epi& E) {
;     ...
;             G_WAIT_V(8); G_WAIT_L(0); G_BAR; G_MMA(1, 0, At, B0); G_MMA(1, 1, At, B1); G_BAR; G_SCHED;
;             G_LDB(B0, 1, 0); G_LDB(B1, 1, 1); G_SCHED; G_LDA(At, 1, 0); G_STAGE(G_SA(0, 1), a2 + hstep, voffA);
;             G_WAIT_V(8); G_WAIT_L(0); G_BAR; G_MMA(0, 0, At, B0); G_MMA(0, 1, At, B1); G_BAR; G_SCHED;
;             G_LDA(At, 1, 1); G_STAGE(G_SB(1, 0), b3, voffB); G_STAGE(G_SB(1, 1), b3 + hstep, voffB); G_STAGE(G_SA(1, 0), a3, voffA);
	s_nop 0
	s_waitcnt lgkmcnt(0)
	v_mfma_f32_16x16x32_f16 v[64:67], v[136:139], v[176:179], v[64:67]
	v_mfma_f32_16x16x32_f16 v[60:63], v[144:147], v[176:179], v[60:63]
	v_mfma_f32_16x16x32_f16 v[52:55], v[136:139], v[188:191], v[52:55]
	v_mfma_f32_16x16x32_f16 v[44:47], v[144:147], v[188:191], v[44:47]
	v_mfma_f32_16x16x32_f16 v[36:39], v[136:139], v[196:199], v[36:39]
	v_mfma_f32_16x16x32_f16 v[28:31], v[144:147], v[196:199], v[28:31]
	v_mfma_f32_16x16x32_f16 v[20:23], v[136:139], v[208:211], v[20:23]
	v_mfma_f32_16x16x32_f16 v[12:15], v[144:147], v[208:211], v[12:15]
	v_mfma_f32_16x16x32_f16 v[64:67], v[140:143], v[180:183], v[64:67]
	v_mfma_f32_16x16x32_f16 v[60:63], v[148:151], v[180:183], v[60:63]
	v_mfma_f32_16x16x32_f16 v[52:55], v[140:143], v[192:195], v[52:55]
	v_mfma_f32_16x16x32_f16 v[44:47], v[148:151], v[192:195], v[44:47]
	v_mfma_f32_16x16x32_f16 v[36:39], v[140:143], v[200:203], v[36:39]
	v_mfma_f32_16x16x32_f16 v[28:31], v[148:151], v[200:203], v[28:31]
	v_mfma_f32_16x16x32_f16 v[20:23], v[140:143], v[212:215], v[20:23]
	v_mfma_f32_16x16x32_f16 v[12:15], v[148:151], v[212:215], v[12:15]
	s_nop 0
	s_nop 0
	v_mfma_f32_16x16x32_f16 v[56:59], v[152:155], v[176:179], v[56:59]
	v_mfma_f32_16x16x32_f16 v[48:51], v[160:163], v[176:179], v[48:51]
	v_mfma_f32_16x16x32_f16 v[40:43], v[152:155], v[188:191], v[40:43]
	v_mfma_f32_16x16x32_f16 v[32:35], v[160:163], v[188:191], v[32:35]
	v_mfma_f32_16x16x32_f16 v[24:27], v[152:155], v[196:199], v[24:27]
	v_mfma_f32_16x16x32_f16 v[16:19], v[160:163], v[196:199], v[16:19]
	v_mfma_f32_16x16x32_f16 v[8:11], v[152:155], v[208:211], v[8:11]
	v_mfma_f32_16x16x32_f16 v[4:7], v[160:163], v[208:211], v[4:7]
	v_mfma_f32_16x16x32_f16 v[56:59], v[156:159], v[180:183], v[56:59]
	v_mfma_f32_16x16x32_f16 v[48:51], v[164:167], v[180:183], v[48:51]
	v_mfma_f32_16x16x32_f16 v[40:43], v[156:159], v[192:195], v[40:43]
	v_mfma_f32_16x16x32_f16 v[32:35], v[164:167], v[192:195], v[32:35]
	v_mfma_f32_16x16x32_f16 v[24:27], v[156:159], v[200:203], v[24:27]
	v_mfma_f32_16x16x32_f16 v[16:19], v[164:167], v[200:203], v[16:19]
	v_mfma_f32_16x16x32_f16 v[8:11], v[156:159], v[212:215], v[8:11]
	v_mfma_f32_16x16x32_f16 v[4:7], v[164:167], v[212:215], v[4:7]
	s_nop 0
	s_barrier
	s_add_i32 s21, 0, 0x18000
	s_add_i32 s30, 0, 0x1c000
	v_add_u32_e32 v148, s21, v205
	v_add_u32_e32 v164, s30, v205
	ds_read_b128 v[136:139], v148
	ds_read_b128 v[140:143], v148 offset:1024
	ds_read_b128 v[144:147], v148 offset:2048
	ds_read_b128 v[148:151], v148 offset:3072
	ds_read_b128 v[152:155], v164
	ds_read_b128 v[156:159], v164 offset:1024
	ds_read_b128 v[160:163], v164 offset:2048
	ds_read_b128 v[164:167], v164 offset:3072
	s_add_u32 s24, s66, 0x80000
	s_addc_u32 s25, s67, 0
	s_mov_b32 m0, s56
	v_lshl_add_u64 v[216:217], s[24:25], 0, v[172:173]
	ds_read_b128 v[176:179], v207 offset:32768
	ds_read_b128 v[180:183], v207 offset:33792
	ds_read_b128 v[188:191], v207 offset:34816
	ds_read_b128 v[192:195], v207 offset:35840
	ds_read_b128 v[196:199], v207 offset:36864
	ds_read_b128 v[200:203], v207 offset:37888
	ds_read_b128 v[208:211], v207 offset:38912
	ds_read_b128 v[212:215], v207 offset:39936
	global_load_lds_dwordx4 v[216:217], off
	v_lshl_add_u64 v[216:217], s[24:25], 0, v[170:171]
	s_mov_b32 m0, s70
	s_nop 0
	global_load_lds_dwordx4 v[216:217], off
	s_waitcnt vmcnt(8)
	s_waitcnt lgkmcnt(0)
	s_barrier
	s_nop 0
	s_waitcnt lgkmcnt(0)
	v_mfma_f32_16x16x32_f16 v[128:131], v[136:139], v[176:179], v[128:131]
	v_mfma_f32_16x16x32_f16 v[124:127], v[144:147], v[176:179], v[124:127]
	v_mfma_f32_16x16x32_f16 v[112:115], v[136:139], v[188:191], v[112:115]
	v_mfma_f32_16x16x32_f16 v[108:111], v[144:147], v[188:191], v[108:111]
	v_mfma_f32_16x16x32_f16 v[100:103], v[136:139], v[196:199], v[100:103]
	v_mfma_f32_16x16x32_f16 v[92:95], v[144:147], v[196:199], v[92:95]
	v_mfma_f32_16x16x32_f16 v[88:91], v[136:139], v[208:211], v[88:91]
	v_mfma_f32_16x16x32_f16 v[80:83], v[144:147], v[208:211], v[80:83]
	v_mfma_f32_16x16x32_f16 v[128:131], v[140:143], v[180:183], v[128:131]
	v_mfma_f32_16x16x32_f16 v[124:127], v[148:151], v[180:183], v[124:127]
	v_mfma_f32_16x16x32_f16 v[112:115], v[140:143], v[192:195], v[112:115]
	v_mfma_f32_16x16x32_f16 v[108:111], v[148:151], v[192:195], v[108:111]
	v_mfma_f32_16x16x32_f16 v[100:103], v[140:143], v[200:203], v[100:103]
	v_mfma_f32_16x16x32_f16 v[92:95], v[148:151], v[200:203], v[92:95]
	v_mfma_f32_16x16x32_f16 v[88:91], v[140:143], v[212:215], v[88:91]
	v_mfma_f32_16x16x32_f16 v[80:83], v[148:151], v[212:215], v[80:83]
	s_nop 0
	s_nop 0
	v_mfma_f32_16x16x32_f16 v[120:123], v[152:155], v[176:179], v[120:123]
	v_mfma_f32_16x16x32_f16 v[116:119], v[160:163], v[176:179], v[116:119]
	v_mfma_f32_16x16x32_f16 v[104:107], v[152:155], v[188:191], v[104:107]
	v_mfma_f32_16x16x32_f16 v[96:99], v[160:163], v[188:191], v[96:99]
	v_mfma_f32_16x16x32_f16 v[84:87], v[152:155], v[196:199], v[84:87]
	v_mfma_f32_16x16x32_f16 v[76:79], v[160:163], v[196:199], v[76:79]
	v_mfma_f32_16x16x32_f16 v[72:75], v[152:155], v[208:211], v[72:75]
	v_mfma_f32_16x16x32_f16 v[68:71], v[160:163], v[208:211], v[68:71]
	v_mfma_f32_16x16x32_f16 v[120:123], v[156:159], v[180:183], v[120:123]
	v_mfma_f32_16x16x32_f16 v[116:119], v[164:167], v[180:183], v[116:119]
	v_mfma_f32_16x16x32_f16 v[104:107], v[156:159], v[192:195], v[104:107]
	v_mfma_f32_16x16x32_f16 v[96:99], v[164:167], v[192:195], v[96:99]
	v_mfma_f32_16x16x32_f16 v[84:87], v[156:159], v[200:203], v[84:87]
	v_mfma_f32_16x16x32_f16 v[76:79], v[164:167], v[200:203], v[76:79]
	v_mfma_f32_16x16x32_f16 v[72:75], v[156:159], v[212:215], v[72:75]
	v_mfma_f32_16x16x32_f16 v[68:71], v[164:167], v[212:215], v[68:71]
	s_nop 0
	s_barrier
; #define G_STAGE(bufoff, gbase, voff) do { _Pragma("unroll") for (int _i = 0; _i < 2; ++_i) \
;         __builtin_amdgcn_global_load_lds((const unsigned*)((const char*)(gbase) + (voff)[_i]), (LAS unsigned*)(lds + (bufoff) + ldsw + _i * 8192), 16, 0, 0); } while (0)
; #define G_LDA(dst, b, h) do { _Pragma("unroll") for (int m = 0; m < 4; ++m) { const i32x4 _p0 = *(const LAS i32x4*)(lds + G_SA(b, h) + aoff + m * 2048), _p1 = *(const LAS i32x4*)(lds + G_SA(b, h) + aoff + m * 2048 + 1024); \
;         dst[m] = __builtin_shufflevector(_p0, _p1, 0, 1, 2, 3, 4, 5, 6, 7); } } while (0)
; #define G_WAIT_V(n) asm volatile("s_waitcnt vmcnt(" #n ")" ::: "memory")
; #define G_WAIT_L(n) asm volatile("s_waitcnt lgkmcnt(" #n ")" ::: "memory")
; #define G_BAR __builtin_amdgcn_s_barrier()
; #define G_SCHED __builtin_amdgcn_sched_barrier(0)
; template <int NS, int MODE  , class Epi>
; __device__ __forceinline__ void gemm_phase(LAS unsigned char* lds, const Gemm g, const StaticOrder& S, const Epi& E) {
;     ...
;             G_LDA(At, 1, 1); G_STAGE(G_SB(1, 0), b3, voffB); G_STAGE(G_SB(1, 1), b3 + hstep, voffB); G_STAGE(G_SA(1, 0), a3, voffA);
;             G_WAIT_V(8); G_WAIT_L(0); G_BAR; G_MMA(1, 0, At, B0); G_MMA(1, 1, At, B1); G_BAR; G_SCHED;
	s_add_i32 s21, s21, s18
	v_lshl_add_u64 v[216:217], s[64:65], 0, v[2:3]
	s_mov_b32 m0, s21
	ds_read_b128 v[176:179], v207 offset:49152
	ds_read_b128 v[180:183], v207 offset:50176
	ds_read_b128 v[188:191], v207 offset:51200
	ds_read_b128 v[192:195], v207 offset:52224
	ds_read_b128 v[196:199], v207 offset:53248
	ds_read_b128 v[200:203], v207 offset:54272
	ds_read_b128 v[208:211], v207 offset:55296
	ds_read_b128 v[212:215], v207 offset:56320
	global_load_lds_dwordx4 v[216:217], off
	s_add_i32 m0, s21, 0x2000
	s_add_u32 s24, s64, 0x80000
	v_lshl_add_u64 v[216:217], s[64:65], 0, v[168:169]
	s_addc_u32 s25, s65, 0
	s_add_i32 s21, s30, s18
	global_load_lds_dwordx4 v[216:217], off
	v_lshl_add_u64 v[216:217], s[24:25], 0, v[2:3]
	s_mov_b32 m0, s21
	s_nop 0
	global_load_lds_dwordx4 v[216:217], off
	v_lshl_add_u64 v[216:217], s[24:25], 0, v[168:169]
	s_add_i32 m0, s21, 0x2000
	s_nop 0
	global_load_lds_dwordx4 v[216:217], off
	v_lshl_add_u64 v[216:217], s[62:63], 0, v[172:173]
	s_mov_b32 m0, s73
	s_nop 0
	global_load_lds_dwordx4 v[216:217], off
	v_lshl_add_u64 v[216:217], s[62:63], 0, v[170:171]
	s_mov_b32 m0, s74
	s_nop 0
	global_load_lds_dwordx4 v[216:217], off
	s_waitcnt vmcnt(8)
	s_waitcnt lgkmcnt(0)
	s_barrier
	s_nop 0
	s_waitcnt lgkmcnt(0)
	v_mfma_f32_16x16x32_f16 v[64:67], v[136:139], v[176:179], v[64:67]
	v_mfma_f32_16x16x32_f16 v[60:63], v[144:147], v[176:179], v[60:63]
	v_mfma_f32_16x16x32_f16 v[52:55], v[136:139], v[188:191], v[52:55]
	v_mfma_f32_16x16x32_f16 v[44:47], v[144:147], v[188:191], v[44:47]
	v_mfma_f32_16x16x32_f16 v[36:39], v[136:139], v[196:199], v[36:39]
	v_mfma_f32_16x16x32_f16 v[28:31], v[144:147], v[196:199], v[28:31]
	v_mfma_f32_16x16x32_f16 v[20:23], v[136:139], v[208:211], v[20:23]
	v_mfma_f32_16x16x32_f16 v[12:15], v[144:147], v[208:211], v[12:15]
	v_mfma_f32_16x16x32_f16 v[64:67], v[140:143], v[180:183], v[64:67]
	v_mfma_f32_16x16x32_f16 v[60:63], v[148:151], v[180:183], v[60:63]
	v_mfma_f32_16x16x32_f16 v[52:55], v[140:143], v[192:195], v[52:55]
	v_mfma_f32_16x16x32_f16 v[44:47], v[148:151], v[192:195], v[44:47]
	v_mfma_f32_16x16x32_f16 v[36:39], v[140:143], v[200:203], v[36:39]
	v_mfma_f32_16x16x32_f16 v[28:31], v[148:151], v[200:203], v[28:31]
	v_mfma_f32_16x16x32_f16 v[20:23], v[140:143], v[212:215], v[20:23]
	v_mfma_f32_16x16x32_f16 v[12:15], v[148:151], v[212:215], v[12:15]
	s_nop 0
	s_nop 0
	v_mfma_f32_16x16x32_f16 v[56:59], v[152:155], v[176:179], v[56:59]
	v_mfma_f32_16x16x32_f16 v[48:51], v[160:163], v[176:179], v[48:51]
	v_mfma_f32_16x16x32_f16 v[40:43], v[152:155], v[188:191], v[40:43]
	v_mfma_f32_16x16x32_f16 v[32:35], v[160:163], v[188:191], v[32:35]
	v_mfma_f32_16x16x32_f16 v[24:27], v[152:155], v[196:199], v[24:27]
	v_mfma_f32_16x16x32_f16 v[16:19], v[160:163], v[196:199], v[16:19]
	v_mfma_f32_16x16x32_f16 v[8:11], v[152:155], v[208:211], v[8:11]
	v_mfma_f32_16x16x32_f16 v[4:7], v[160:163], v[208:211], v[4:7]
	v_mfma_f32_16x16x32_f16 v[56:59], v[156:159], v[180:183], v[56:59]
	v_mfma_f32_16x16x32_f16 v[48:51], v[164:167], v[180:183], v[48:51]
	v_mfma_f32_16x16x32_f16 v[40:43], v[156:159], v[192:195], v[40:43]
	v_mfma_f32_16x16x32_f16 v[32:35], v[164:167], v[192:195], v[32:35]
	v_mfma_f32_16x16x32_f16 v[24:27], v[156:159], v[200:203], v[24:27]
	v_mfma_f32_16x16x32_f16 v[16:19], v[164:167], v[200:203], v[16:19]
	v_mfma_f32_16x16x32_f16 v[8:11], v[156:159], v[212:215], v[8:11]
	v_mfma_f32_16x16x32_f16 v[4:7], v[164:167], v[212:215], v[4:7]
	s_nop 0
	s_barrier
	s_add_u32 s60, s60, 0x100
	s_addc_u32 s61, s61, 0
	s_add_i32 s13, s13, 2
	s_cmp_gt_u32 s13, 29
	s_cbranch_scc1 .LBB0_1129

; #define G_STAGE(bufoff, gbase, voff) do { _Pragma("unroll") for (int _i = 0; _i < 2; ++_i) \
;         __builtin_amdgcn_global_load_lds((const unsigned*)((const char*)(gbase) + (voff)[_i]), (LAS unsigned*)(lds + (bufoff) + ldsw + _i * 8192), 16, 0, 0); } while (0)
; #define G_LDA(dst, b, h) do { _Pragma("unroll") for (int m = 0; m < 4; ++m) { const i32x4 _p0 = *(const LAS i32x4*)(lds + G_SA(b, h) + aoff + m * 2048), _p1 = *(const LAS i32x4*)(lds + G_SA(b, h) + aoff + m * 2048 + 1024); \
;         dst[m] = __builtin_shufflevector(_p0, _p1, 0, 1, 2, 3, 4, 5, 6, 7); } } while (0)
; #define G_LDB(dst, b, h) do { _Pragma("unroll") for (int n = 0; n < 2; ++n) { const i32x4 _p0 = *(const LAS i32x4*)(lds + G_SB(b, h) + boff + n * 2048), _p1 = *(const LAS i32x4*)(lds + G_SB(b, h) + boff + n * 2048 + 1024); \
;         dst[n] = __builtin_shufflevector(_p0, _p1, 0, 1, 2, 3, 4, 5, 6, 7); } } while (0)
; #define G_WAIT_V(n) asm volatile("s_waitcnt vmcnt(" #n ")" ::: "memory")
; #define G_WAIT_L(n) asm volatile("s_waitcnt lgkmcnt(" #n ")" ::: "memory")
; #define G_BAR __builtin_amdgcn_s_barrier()
; #define G_SCHED __builtin_amdgcn_sched_barrier(0)
; template <int NS, int MODE  , class Epi>
; __device__ __forceinline__ void gemm_phase(LAS unsigned char* lds, const Gemm g, const StaticOrder& S, const Epi& E) {
;     ...
;             if (G_SP2) {
;             G_LDB(B0, 0, 0); G_LDB(B1, 0, 1); G_SCHED; G_LDA(At, 0, 0); G_STAGE(G_SA(1, 1), a1 + hstep, voffA);
;             G_WAIT_V(8); G_WAIT_L(0); G_BAR; G_MMA(0, 0, At, B0); G_MMA(0, 1, At, B1); G_BAR; G_SCHED;
;             G_LDA(At, 0, 1); G_STAGE(G_SB(0, 0), b2, voffB); G_STAGE(G_SB(0, 1), b2 + hstep, voffB); G_STAGE(G_SA(0, 0), a2, voffA);
;             G_WAIT_V(8); G_WAIT_L(0); G_BAR; G_MMA(1, 0, At, B0); G_MMA(1, 1, At, B1); G_BAR; G_SCHED;
.LBB0_1276:
	s_add_i32 s21, 0, 0x10000
	s_add_i32 s30, 0, 0x14000
	v_add_u32_e32 v132, s21, v190
	v_add_u32_e32 v136, s30, v190
	ds_read_b128 v[160:163], v132
	ds_read_b128 v[148:151], v132 offset:1024
	ds_read_b128 v[156:159], v132 offset:2048
	ds_read_b128 v[152:155], v132 offset:3072
	ds_read_b128 v[144:147], v136
	ds_read_b128 v[132:135], v136 offset:1024
	ds_read_b128 v[140:143], v136 offset:2048
	ds_read_b128 v[136:139], v136 offset:3072
	v_lshl_add_u64 v[226:227], v[174:175], 0, s[60:61]
	s_add_i32 m0, s19, 0xc000
	ds_read_b128 v[176:179], v194
	ds_read_b128 v[180:183], v194 offset:1024
	ds_read_b128 v[202:205], v194 offset:2048
	ds_read_b128 v[206:209], v194 offset:3072
	ds_read_b128 v[210:213], v194 offset:4096
	ds_read_b128 v[214:217], v194 offset:5120
	ds_read_b128 v[218:221], v194 offset:6144
	ds_read_b128 v[222:225], v194 offset:7168
	global_load_lds_dwordx4 v[226:227], off
	v_lshl_add_u64 v[226:227], v[186:187], 0, s[60:61]
	s_add_i32 m0, s19, 0xe000
	s_nop 0
	global_load_lds_dwordx4 v[226:227], off
	s_waitcnt vmcnt(8)
	s_waitcnt lgkmcnt(0)
	s_barrier
	s_nop 0
	s_waitcnt lgkmcnt(0)
	v_mfma_i32_16x16x64_i8 v[128:131], v[160:163], v[176:179], v[128:131]
	v_mfma_i32_16x16x64_i8 v[120:123], v[156:159], v[176:179], v[120:123]
	v_mfma_i32_16x16x64_i8 v[112:115], v[160:163], v[202:205], v[112:115]
	v_mfma_i32_16x16x64_i8 v[104:107], v[156:159], v[202:205], v[104:107]
	v_mfma_i32_16x16x64_i8 v[96:99], v[160:163], v[210:213], v[96:99]
	v_mfma_i32_16x16x64_i8 v[88:91], v[156:159], v[210:213], v[88:91]
	v_mfma_i32_16x16x64_i8 v[80:83], v[160:163], v[218:221], v[80:83]
	v_mfma_i32_16x16x64_i8 v[72:75], v[156:159], v[218:221], v[72:75]
	s_nop 0
	v_mfma_i32_16x16x64_i8 v[128:131], v[148:151], v[180:183], v[128:131]
	v_mfma_i32_16x16x64_i8 v[120:123], v[152:155], v[180:183], v[120:123]
	v_mfma_i32_16x16x64_i8 v[112:115], v[148:151], v[206:209], v[112:115]
	v_mfma_i32_16x16x64_i8 v[104:107], v[152:155], v[206:209], v[104:107]
	v_mfma_i32_16x16x64_i8 v[96:99], v[148:151], v[214:217], v[96:99]
	v_mfma_i32_16x16x64_i8 v[88:91], v[152:155], v[214:217], v[88:91]
	v_mfma_i32_16x16x64_i8 v[80:83], v[148:151], v[222:225], v[80:83]
	v_mfma_i32_16x16x64_i8 v[72:75], v[152:155], v[222:225], v[72:75]
	s_nop 0
	s_nop 0
	v_mfma_i32_16x16x64_i8 v[124:127], v[144:147], v[176:179], v[124:127]
	v_mfma_i32_16x16x64_i8 v[116:119], v[140:143], v[176:179], v[116:119]
	v_mfma_i32_16x16x64_i8 v[108:111], v[144:147], v[202:205], v[108:111]
	v_mfma_i32_16x16x64_i8 v[100:103], v[140:143], v[202:205], v[100:103]
	v_mfma_i32_16x16x64_i8 v[92:95], v[144:147], v[210:213], v[92:95]
	v_mfma_i32_16x16x64_i8 v[84:87], v[140:143], v[210:213], v[84:87]
	v_mfma_i32_16x16x64_i8 v[76:79], v[144:147], v[218:221], v[76:79]
	v_mfma_i32_16x16x64_i8 v[68:71], v[140:143], v[218:221], v[68:71]
	s_nop 0
	v_mfma_i32_16x16x64_i8 v[124:127], v[132:135], v[180:183], v[124:127]
	v_mfma_i32_16x16x64_i8 v[116:119], v[136:139], v[180:183], v[116:119]
	v_mfma_i32_16x16x64_i8 v[108:111], v[132:135], v[206:209], v[108:111]
	v_mfma_i32_16x16x64_i8 v[100:103], v[136:139], v[206:209], v[100:103]
	v_mfma_i32_16x16x64_i8 v[92:95], v[132:135], v[214:217], v[92:95]
	v_mfma_i32_16x16x64_i8 v[84:87], v[136:139], v[214:217], v[84:87]
	v_mfma_i32_16x16x64_i8 v[76:79], v[132:135], v[222:225], v[76:79]
	v_mfma_i32_16x16x64_i8 v[68:71], v[136:139], v[222:225], v[68:71]
	s_nop 0
	s_barrier
	s_add_i32 s21, s21, s18
	v_lshl_add_u64 v[226:227], s[68:69], 0, v[2:3]
	s_mov_b32 m0, s21
	ds_read_b128 v[176:179], v194 offset:16384
	ds_read_b128 v[180:183], v194 offset:17408
	ds_read_b128 v[202:205], v194 offset:18432
	ds_read_b128 v[206:209], v194 offset:19456
	ds_read_b128 v[210:213], v194 offset:20480
	ds_read_b128 v[214:217], v194 offset:21504
	ds_read_b128 v[218:221], v194 offset:22528
	ds_read_b128 v[222:225], v194 offset:23552
	global_load_lds_dwordx4 v[226:227], off
	s_add_i32 m0, s21, 0x2000
	s_add_u32 s24, s68, 0x40000
	v_lshl_add_u64 v[226:227], s[68:69], 0, v[164:165]
	s_addc_u32 s25, s69, 0
	s_add_i32 s21, s30, s18
	global_load_lds_dwordx4 v[226:227], off
	v_lshl_add_u64 v[226:227], s[24:25], 0, v[2:3]
	s_mov_b32 m0, s21
	s_nop 0
	global_load_lds_dwordx4 v[226:227], off
	v_lshl_add_u64 v[226:227], s[24:25], 0, v[164:165]
	s_add_i32 m0, s21, 0x2000
	s_nop 0
	global_load_lds_dwordx4 v[226:227], off
	v_lshl_add_u64 v[226:227], s[66:67], 0, v[168:169]
	s_mov_b32 m0, s19
	s_nop 0
	global_load_lds_dwordx4 v[226:227], off
	v_lshl_add_u64 v[226:227], s[66:67], 0, v[166:167]
	s_mov_b32 m0, s29
	s_nop 0
	global_load_lds_dwordx4 v[226:227], off
	s_waitcnt vmcnt(8)
	s_waitcnt lgkmcnt(0)
	s_barrier
; #define G_STAGE(bufoff, gbase, voff) do { _Pragma("unroll") for (int _i = 0; _i < 2; ++_i) \
;         __builtin_amdgcn_global_load_lds((const unsigned*)((const char*)(gbase) + (voff)[_i]), (LAS unsigned*)(lds + (bufoff) + ldsw + _i * 8192), 16, 0, 0); } while (0)
; #define G_LDA(dst, b, h) do { _Pragma("unroll") for (int m = 0; m < 4; ++m) { const i32x4 _p0 = *(const LAS i32x4*)(lds + G_SA(b, h) + aoff + m * 2048), _p1 = *(const LAS i32x4*)(lds + G_SA(b, h) + aoff + m * 2048 + 1024); \
;         dst[m] = __builtin_shufflevector(_p0, _p1, 0, 1, 2, 3, 4, 5, 6, 7); } } while (0)
; #define G_LDB(dst, b, h) do { _Pragma("unroll") for (int n = 0; n < 2; ++n) { const i32x4 _p0 = *(const LAS i32x4*)(lds + G_SB(b, h) + boff + n * 2048), _p1 = *(const LAS i32x4*)(lds + G_SB(b, h) + boff + n * 2048 + 1024); \
;         dst[n] = __builtin_shufflevector(_p0, _p1, 0, 1, 2, 3, 4, 5, 6, 7); } } while (0)
; #define G_WAIT_V(n) asm volatile("s_waitcnt vmcnt(" #n ")" ::: "memory")
; #define G_WAIT_L(n) asm volatile("s_waitcnt lgkmcnt(" #n ")" ::: "memory")
; #define G_BAR __builtin_amdgcn_s_barrier()
; #define G_SCHED __builtin_amdgcn_sched_barrier(0)
; template <int NS, int MODE  , class Epi>
; __device__ __forceinline__ void gemm_phase(LAS unsigned char* lds, const Gemm g, const StaticOrder& S, const Epi& E) {
;     ...
;             G_WAIT_V(8); G_WAIT_L(0); G_BAR; G_MMA(1, 0, At, B0); G_MMA(1, 1, At, B1); G_BAR; G_SCHED;
;             G_LDB(B0, 1, 0); G_LDB(B1, 1, 1); G_SCHED; G_LDA(At, 1, 0); G_STAGE(G_SA(0, 1), a2 + hstep, voffA);
;             G_WAIT_V(8); G_WAIT_L(0); G_BAR; G_MMA(0, 0, At, B0); G_MMA(0, 1, At, B1); G_BAR; G_SCHED;
;             G_LDA(At, 1, 1); G_STAGE(G_SB(1, 0), b3, voffB); G_STAGE(G_SB(1, 1), b3 + hstep, voffB); G_STAGE(G_SA(1, 0), a3, voffA);
	s_nop 0
	s_waitcnt lgkmcnt(0)
	v_mfma_i32_16x16x64_i8 v[64:67], v[160:163], v[176:179], v[64:67]
	v_mfma_i32_16x16x64_i8 v[56:59], v[156:159], v[176:179], v[56:59]
	v_mfma_i32_16x16x64_i8 v[48:51], v[160:163], v[202:205], v[48:51]
	v_mfma_i32_16x16x64_i8 v[40:43], v[156:159], v[202:205], v[40:43]
	v_mfma_i32_16x16x64_i8 v[32:35], v[160:163], v[210:213], v[32:35]
	v_mfma_i32_16x16x64_i8 v[24:27], v[156:159], v[210:213], v[24:27]
	v_mfma_i32_16x16x64_i8 v[16:19], v[160:163], v[218:221], v[16:19]
	v_mfma_i32_16x16x64_i8 v[8:11], v[156:159], v[218:221], v[8:11]
	s_nop 0
	v_mfma_i32_16x16x64_i8 v[64:67], v[148:151], v[180:183], v[64:67]
	v_mfma_i32_16x16x64_i8 v[56:59], v[152:155], v[180:183], v[56:59]
	v_mfma_i32_16x16x64_i8 v[48:51], v[148:151], v[206:209], v[48:51]
	v_mfma_i32_16x16x64_i8 v[40:43], v[152:155], v[206:209], v[40:43]
	v_mfma_i32_16x16x64_i8 v[32:35], v[148:151], v[214:217], v[32:35]
	v_mfma_i32_16x16x64_i8 v[24:27], v[152:155], v[214:217], v[24:27]
	v_mfma_i32_16x16x64_i8 v[16:19], v[148:151], v[222:225], v[16:19]
	v_mfma_i32_16x16x64_i8 v[8:11], v[152:155], v[222:225], v[8:11]
	s_nop 0
	s_nop 0
	v_mfma_i32_16x16x64_i8 v[60:63], v[144:147], v[176:179], v[60:63]
	v_mfma_i32_16x16x64_i8 v[52:55], v[140:143], v[176:179], v[52:55]
	v_mfma_i32_16x16x64_i8 v[44:47], v[144:147], v[202:205], v[44:47]
	v_mfma_i32_16x16x64_i8 v[36:39], v[140:143], v[202:205], v[36:39]
	v_mfma_i32_16x16x64_i8 v[28:31], v[144:147], v[210:213], v[28:31]
	v_mfma_i32_16x16x64_i8 v[20:23], v[140:143], v[210:213], v[20:23]
	v_mfma_i32_16x16x64_i8 v[12:15], v[144:147], v[218:221], v[12:15]
	v_mfma_i32_16x16x64_i8 v[4:7], v[140:143], v[218:221], v[4:7]
	s_nop 0
	v_mfma_i32_16x16x64_i8 v[60:63], v[132:135], v[180:183], v[60:63]
	v_mfma_i32_16x16x64_i8 v[52:55], v[136:139], v[180:183], v[52:55]
	v_mfma_i32_16x16x64_i8 v[44:47], v[132:135], v[206:209], v[44:47]
	v_mfma_i32_16x16x64_i8 v[36:39], v[136:139], v[206:209], v[36:39]
	v_mfma_i32_16x16x64_i8 v[28:31], v[132:135], v[214:217], v[28:31]
	v_mfma_i32_16x16x64_i8 v[20:23], v[136:139], v[214:217], v[20:23]
	v_mfma_i32_16x16x64_i8 v[12:15], v[132:135], v[222:225], v[12:15]
	v_mfma_i32_16x16x64_i8 v[4:7], v[136:139], v[222:225], v[4:7]
	s_nop 0
	s_barrier
	s_add_i32 s21, 0, 0x18000
	s_add_i32 s30, 0, 0x1c000
	v_add_u32_e32 v144, s21, v190
	v_add_u32_e32 v160, s30, v190
	ds_read_b128 v[132:135], v144
	ds_read_b128 v[136:139], v144 offset:1024
	ds_read_b128 v[140:143], v144 offset:2048
	ds_read_b128 v[144:147], v144 offset:3072
	ds_read_b128 v[148:151], v160
	ds_read_b128 v[152:155], v160 offset:1024
	ds_read_b128 v[156:159], v160 offset:2048
	ds_read_b128 v[160:163], v160 offset:3072
	s_add_u32 s24, s66, 0x40000
	s_addc_u32 s25, s67, 0
	s_mov_b32 m0, s56
	v_lshl_add_u64 v[226:227], s[24:25], 0, v[168:169]
	ds_read_b128 v[176:179], v194 offset:32768
	ds_read_b128 v[180:183], v194 offset:33792
	ds_read_b128 v[202:205], v194 offset:34816
	ds_read_b128 v[206:209], v194 offset:35840
	ds_read_b128 v[210:213], v194 offset:36864
	ds_read_b128 v[214:217], v194 offset:37888
	ds_read_b128 v[218:221], v194 offset:38912
	ds_read_b128 v[222:225], v194 offset:39936
	global_load_lds_dwordx4 v[226:227], off
	v_lshl_add_u64 v[226:227], s[24:25], 0, v[166:167]
	s_mov_b32 m0, s70
	s_nop 0
	global_load_lds_dwordx4 v[226:227], off
	s_waitcnt vmcnt(8)
	s_waitcnt lgkmcnt(0)
	s_barrier
	s_nop 0
	s_waitcnt lgkmcnt(0)
	v_mfma_i32_16x16x64_i8 v[128:131], v[132:135], v[176:179], v[128:131]
	v_mfma_i32_16x16x64_i8 v[120:123], v[140:143], v[176:179], v[120:123]
	v_mfma_i32_16x16x64_i8 v[112:115], v[132:135], v[202:205], v[112:115]
	v_mfma_i32_16x16x64_i8 v[104:107], v[140:143], v[202:205], v[104:107]
	v_mfma_i32_16x16x64_i8 v[96:99], v[132:135], v[210:213], v[96:99]
	v_mfma_i32_16x16x64_i8 v[88:91], v[140:143], v[210:213], v[88:91]
	v_mfma_i32_16x16x64_i8 v[80:83], v[132:135], v[218:221], v[80:83]
	v_mfma_i32_16x16x64_i8 v[72:75], v[140:143], v[218:221], v[72:75]
	s_nop 0
	v_mfma_i32_16x16x64_i8 v[128:131], v[136:139], v[180:183], v[128:131]
	v_mfma_i32_16x16x64_i8 v[120:123], v[144:147], v[180:183], v[120:123]
	v_mfma_i32_16x16x64_i8 v[112:115], v[136:139], v[206:209], v[112:115]
	v_mfma_i32_16x16x64_i8 v[104:107], v[144:147], v[206:209], v[104:107]
	v_mfma_i32_16x16x64_i8 v[96:99], v[136:139], v[214:217], v[96:99]
	v_mfma_i32_16x16x64_i8 v[88:91], v[144:147], v[214:217], v[88:91]
	v_mfma_i32_16x16x64_i8 v[80:83], v[136:139], v[222:225], v[80:83]
	v_mfma_i32_16x16x64_i8 v[72:75], v[144:147], v[222:225], v[72:75]
	s_nop 0
	s_nop 0
	v_mfma_i32_16x16x64_i8 v[124:127], v[148:151], v[176:179], v[124:127]
	v_mfma_i32_16x16x64_i8 v[116:119], v[156:159], v[176:179], v[116:119]
	v_mfma_i32_16x16x64_i8 v[108:111], v[148:151], v[202:205], v[108:111]
	v_mfma_i32_16x16x64_i8 v[100:103], v[156:159], v[202:205], v[100:103]
	v_mfma_i32_16x16x64_i8 v[92:95], v[148:151], v[210:213], v[92:95]
	v_mfma_i32_16x16x64_i8 v[84:87], v[156:159], v[210:213], v[84:87]
	v_mfma_i32_16x16x64_i8 v[76:79], v[148:151], v[218:221], v[76:79]
	v_mfma_i32_16x16x64_i8 v[68:71], v[156:159], v[218:221], v[68:71]
	s_nop 0
	v_mfma_i32_16x16x64_i8 v[124:127], v[152:155], v[180:183], v[124:127]
	v_mfma_i32_16x16x64_i8 v[116:119], v[160:163], v[180:183], v[116:119]
	v_mfma_i32_16x16x64_i8 v[108:111], v[152:155], v[206:209], v[108:111]
	v_mfma_i32_16x16x64_i8 v[100:103], v[160:163], v[206:209], v[100:103]
	v_mfma_i32_16x16x64_i8 v[92:95], v[152:155], v[214:217], v[92:95]
	v_mfma_i32_16x16x64_i8 v[84:87], v[160:163], v[214:217], v[84:87]
	v_mfma_i32_16x16x64_i8 v[76:79], v[152:155], v[222:225], v[76:79]
	v_mfma_i32_16x16x64_i8 v[68:71], v[160:163], v[222:225], v[68:71]
	s_nop 0
	s_barrier
; #define G_STAGE(bufoff, gbase, voff) do { _Pragma("unroll") for (int _i = 0; _i < 2; ++_i) \
;         __builtin_amdgcn_global_load_lds((const unsigned*)((const char*)(gbase) + (voff)[_i]), (LAS unsigned*)(lds + (bufoff) + ldsw + _i * 8192), 16, 0, 0); } while (0)
; #define G_LDA(dst, b, h) do { _Pragma("unroll") for (int m = 0; m < 4; ++m) { const i32x4 _p0 = *(const LAS i32x4*)(lds + G_SA(b, h) + aoff + m * 2048), _p1 = *(const LAS i32x4*)(lds + G_SA(b, h) + aoff + m * 2048 + 1024); \
;         dst[m] = __builtin_shufflevector(_p0, _p1, 0, 1, 2, 3, 4, 5, 6, 7); } } while (0)
; #define G_WAIT_V(n) asm volatile("s_waitcnt vmcnt(" #n ")" ::: "memory")
; #define G_WAIT_L(n) asm volatile("s_waitcnt lgkmcnt(" #n ")" ::: "memory")
; #define G_BAR __builtin_amdgcn_s_barrier()
; #define G_SCHED __builtin_amdgcn_sched_barrier(0)
; template <int NS, int MODE  , class Epi>
; __device__ __forceinline__ void gemm_phase(LAS unsigned char* lds, const Gemm g, const StaticOrder& S, const Epi& E) {
;     ...
;             G_LDA(At, 1, 1); G_STAGE(G_SB(1, 0), b3, voffB); G_STAGE(G_SB(1, 1), b3 + hstep, voffB); G_STAGE(G_SA(1, 0), a3, voffA);
;             G_WAIT_V(8); G_WAIT_L(0); G_BAR; G_MMA(1, 0, At, B0); G_MMA(1, 1, At, B1); G_BAR; G_SCHED;
	s_add_i32 s21, s21, s18
	v_lshl_add_u64 v[226:227], s[64:65], 0, v[2:3]
	s_mov_b32 m0, s21
	ds_read_b128 v[176:179], v194 offset:49152
	ds_read_b128 v[180:183], v194 offset:50176
	ds_read_b128 v[202:205], v194 offset:51200
	ds_read_b128 v[206:209], v194 offset:52224
	ds_read_b128 v[210:213], v194 offset:53248
	ds_read_b128 v[214:217], v194 offset:54272
	ds_read_b128 v[218:221], v194 offset:55296
	ds_read_b128 v[222:225], v194 offset:56320
	global_load_lds_dwordx4 v[226:227], off
	s_add_i32 m0, s21, 0x2000
	s_add_u32 s24, s64, 0x40000
	v_lshl_add_u64 v[226:227], s[64:65], 0, v[164:165]
	s_addc_u32 s25, s65, 0
	s_add_i32 s21, s30, s18
	global_load_lds_dwordx4 v[226:227], off
	v_lshl_add_u64 v[226:227], s[24:25], 0, v[2:3]
	s_mov_b32 m0, s21
	s_nop 0
	global_load_lds_dwordx4 v[226:227], off
	v_lshl_add_u64 v[226:227], s[24:25], 0, v[164:165]
	s_add_i32 m0, s21, 0x2000
	s_nop 0
	global_load_lds_dwordx4 v[226:227], off
	v_lshl_add_u64 v[226:227], s[62:63], 0, v[168:169]
	s_mov_b32 m0, s71
	s_nop 0
	global_load_lds_dwordx4 v[226:227], off
	v_lshl_add_u64 v[226:227], s[62:63], 0, v[166:167]
	s_mov_b32 m0, s72
	s_nop 0
	global_load_lds_dwordx4 v[226:227], off
	s_waitcnt vmcnt(8)
	s_waitcnt lgkmcnt(0)
	s_barrier
	s_nop 0
	s_waitcnt lgkmcnt(0)
	v_mfma_i32_16x16x64_i8 v[64:67], v[132:135], v[176:179], v[64:67]
	v_mfma_i32_16x16x64_i8 v[56:59], v[140:143], v[176:179], v[56:59]
	v_mfma_i32_16x16x64_i8 v[48:51], v[132:135], v[202:205], v[48:51]
	v_mfma_i32_16x16x64_i8 v[40:43], v[140:143], v[202:205], v[40:43]
	v_mfma_i32_16x16x64_i8 v[32:35], v[132:135], v[210:213], v[32:35]
	v_mfma_i32_16x16x64_i8 v[24:27], v[140:143], v[210:213], v[24:27]
	v_mfma_i32_16x16x64_i8 v[16:19], v[132:135], v[218:221], v[16:19]
	v_mfma_i32_16x16x64_i8 v[8:11], v[140:143], v[218:221], v[8:11]
	s_nop 0
	v_mfma_i32_16x16x64_i8 v[64:67], v[136:139], v[180:183], v[64:67]
	v_mfma_i32_16x16x64_i8 v[56:59], v[144:147], v[180:183], v[56:59]
	v_mfma_i32_16x16x64_i8 v[48:51], v[136:139], v[206:209], v[48:51]
	v_mfma_i32_16x16x64_i8 v[40:43], v[144:147], v[206:209], v[40:43]
	v_mfma_i32_16x16x64_i8 v[32:35], v[136:139], v[214:217], v[32:35]
	v_mfma_i32_16x16x64_i8 v[24:27], v[144:147], v[214:217], v[24:27]
	v_mfma_i32_16x16x64_i8 v[16:19], v[136:139], v[222:225], v[16:19]
	v_mfma_i32_16x16x64_i8 v[8:11], v[144:147], v[222:225], v[8:11]
	s_nop 0
	s_nop 0
	v_mfma_i32_16x16x64_i8 v[60:63], v[148:151], v[176:179], v[60:63]
	v_mfma_i32_16x16x64_i8 v[52:55], v[156:159], v[176:179], v[52:55]
	v_mfma_i32_16x16x64_i8 v[44:47], v[148:151], v[202:205], v[44:47]
	v_mfma_i32_16x16x64_i8 v[36:39], v[156:159], v[202:205], v[36:39]
	v_mfma_i32_16x16x64_i8 v[28:31], v[148:151], v[210:213], v[28:31]
	v_mfma_i32_16x16x64_i8 v[20:23], v[156:159], v[210:213], v[20:23]
	v_mfma_i32_16x16x64_i8 v[12:15], v[148:151], v[218:221], v[12:15]
	v_mfma_i32_16x16x64_i8 v[4:7], v[156:159], v[218:221], v[4:7]
	s_nop 0
	v_mfma_i32_16x16x64_i8 v[60:63], v[152:155], v[180:183], v[60:63]
	v_mfma_i32_16x16x64_i8 v[52:55], v[160:163], v[180:183], v[52:55]
	v_mfma_i32_16x16x64_i8 v[44:47], v[152:155], v[206:209], v[44:47]
	v_mfma_i32_16x16x64_i8 v[36:39], v[160:163], v[206:209], v[36:39]
	v_mfma_i32_16x16x64_i8 v[28:31], v[152:155], v[214:217], v[28:31]
	v_mfma_i32_16x16x64_i8 v[20:23], v[160:163], v[214:217], v[20:23]
	v_mfma_i32_16x16x64_i8 v[12:15], v[152:155], v[222:225], v[12:15]
	v_mfma_i32_16x16x64_i8 v[4:7], v[160:163], v[222:225], v[4:7]
	s_nop 0
	s_barrier
	s_add_i32 s13, s13, 2
	s_add_u32 s60, s60, 0x100
	s_addc_u32 s61, s61, 0
	s_cmp_gt_u32 s13, 13
	s_cbranch_scc1 .LBB0_1279

;     __device__ __forceinline__ void operator()(const f32x4 (&acc)[2][2][4][2], const Unit& u, int wr, int wc, int fr, int fq, const float (&pre)[8]) const {
;         const int row0 = u.pm * BM + wr * 64 + fr, col0 = u.pn * 128 + wc * 32 + 8 * fq;
; #pragma unroll
;         for (int ai = 0; ai < 2; ++ai)
; #pragma unroll
;             for (int m = 0; m < 4; ++m) {
;                 const size_t off = (size_t)(row0 + ai * HALF + m * 16) * DFF + col0;
;                 const float rsc = pre[ai * 4 + m];
;                 const float ka = us * rsc * (1.0f / KREP), ke = ka * -1.4426950408889634f, K = ka * ka * (h8 ? SH8 : SA);
;                 f32x2 hv[4];
; #pragma unroll
;                 for (int n = 0; n < 2; ++n)
; #pragma unroll
;                     for (int jp = 0; jp < 2; ++jp) {
;                         const float fa0 = acc[ai][0][m][n][2 * jp], fa1 = acc[ai][0][m][n][2 * jp + 1], fb0 = acc[ai][1][m][n][2 * jp], fb1 = acc[ai][1][m][n][2 * jp + 1];
;                         const f32x2 A = iacc ? (f32x2){(float)__float_as_int(fa0), (float)__float_as_int(fa1)} : (f32x2){fa0, fa1};
;                         const f32x2 B = iacc ? (f32x2){(float)__float_as_int(fb0), (float)__float_as_int(fb1)} : (f32x2){fb0, fb1};
;                         const f32x2 X = A * ke;
;                         const f32x2 D = (f32x2){__builtin_amdgcn_exp2f(X[0]), __builtin_amdgcn_exp2f(X[1])} + 1.0f;
;                         const f32x2 R = {__builtin_amdgcn_rcpf(D[0]), __builtin_amdgcn_rcpf(D[1])};
;                         hv[n * 2 + jp] = ((A * B) * R) * K;
;                     }
;                 f16x8 hi, lo;
;                 if (h8) {
;                     int p0 = __builtin_amdgcn_cvt_pk_fp8_f32(hv[0][0], hv[0][1], 0, false); p0 = __builtin_amdgcn_cvt_pk_fp8_f32(hv[1][0], hv[1][1], p0, true);
;                     int p1 = __builtin_amdgcn_cvt_pk_fp8_f32(hv[2][0], hv[2][1], 0, false); p1 = __builtin_amdgcn_cvt_pk_fp8_f32(hv[3][0], hv[3][1], p1, true);
;                     *(u32x2v*)((unsigned char*)Hh + off) = (u32x2v){(unsigned)p0, (unsigned)p1}; }
; template <int NS, int MODE  , class Epi>
; __device__ __forceinline__ void gemm_phase(LAS unsigned char* lds, const Gemm g, const StaticOrder& S, const Epi& E) {
;     ...
;         if constexpr (MODE != 0) asm volatile("s_nop 7\n\ts_nop 7\n\ts_nop 7" ::: "memory");
.LBB0_1281:
	v_cvt_f32_i32_e32 v129, v129
	v_cvt_f32_i32_e32 v128, v128
	v_cvt_f32_i32_e32 v125, v125
	v_cvt_f32_i32_e32 v124, v124
	v_cvt_f32_i32_e32 v131, v131
	v_cvt_f32_i32_e32 v130, v130
	s_waitcnt vmcnt(8)
	v_mul_f32_e32 v135, v188, v200
	v_mul_f32_e32 v136, 0xbfb8aa3b, v135
	v_pk_mul_f32 v[138:139], v[136:137], v[128:129] op_sel_hi:[0,1]
	v_pk_mul_f32 v[124:125], v[128:129], v[124:125]
	v_pk_mul_f32 v[128:129], v[136:137], v[130:131] op_sel_hi:[0,1]
	v_exp_f32_e32 v128, v128
	v_exp_f32_e32 v129, v129
	v_cvt_f32_i32_e32 v127, v127
	v_cvt_f32_i32_e32 v126, v126
	v_cvt_f32_i32_e32 v121, v121
	v_cvt_f32_i32_e32 v120, v120
	v_pk_add_f32 v[128:129], v[128:129], 1.0 op_sel_hi:[1,0]
	v_pk_mul_f32 v[126:127], v[130:131], v[126:127]
	v_cvt_f32_i32_e32 v117, v117
	v_pk_mul_f32 v[130:131], v[136:137], v[120:121] op_sel_hi:[0,1]
	v_cvt_f32_i32_e32 v116, v116
	v_cvt_f32_i32_e32 v123, v123
	v_cvt_f32_i32_e32 v122, v122
	v_exp_f32_e32 v138, v138
	v_exp_f32_e32 v139, v139
	v_rcp_f32_e32 v128, v128
	v_rcp_f32_e32 v129, v129
	v_exp_f32_e32 v130, v130
	v_exp_f32_e32 v131, v131
	v_pk_mul_f32 v[116:117], v[120:121], v[116:117]
	v_pk_mul_f32 v[120:121], v[136:137], v[122:123] op_sel_hi:[0,1]
	v_pk_add_f32 v[138:139], v[138:139], 1.0 op_sel_hi:[1,0]
	v_pk_mul_f32 v[126:127], v[128:129], v[126:127]
	v_pk_add_f32 v[128:129], v[130:131], 1.0 op_sel_hi:[1,0]
	v_exp_f32_e32 v120, v120
	v_exp_f32_e32 v121, v121
	v_rcp_f32_e32 v138, v138
	v_rcp_f32_e32 v139, v139
	v_rcp_f32_e32 v128, v128
	v_rcp_f32_e32 v129, v129
	v_cvt_f32_i32_e32 v119, v119
	v_cvt_f32_i32_e32 v118, v118
	v_mul_f32_e32 v135, v135, v135
	v_pk_add_f32 v[120:121], v[120:121], 1.0 op_sel_hi:[1,0]
	v_mul_f32_e32 v140, 4.0, v135
	v_pk_mul_f32 v[124:125], v[138:139], v[124:125]
	v_pk_mul_f32 v[116:117], v[128:129], v[116:117]
	v_rcp_f32_e32 v120, v120
	v_rcp_f32_e32 v121, v121
	v_pk_mul_f32 v[124:125], v[140:141], v[124:125] op_sel_hi:[0,1]
	v_pk_mul_f32 v[116:117], v[140:141], v[116:117] op_sel_hi:[0,1]
	v_pk_mul_f32 v[118:119], v[122:123], v[118:119]
	v_mov_b32_e32 v122, v3
	v_mov_b32_e32 v123, v3
	v_cvt_pk_fp8_f32 v122, v124, v125
	v_cvt_pk_fp8_f32 v123, v116, v117
	v_pk_mul_f32 v[116:117], v[120:121], v[118:119]
	v_pk_mul_f32 v[126:127], v[140:141], v[126:127] op_sel_hi:[0,1]
	v_pk_mul_f32 v[116:117], v[140:141], v[116:117] op_sel_hi:[0,1]
	v_cvt_pk_fp8_f32 v122, v126, v127 op_sel:[0,0,1]
	v_cvt_pk_fp8_f32 v123, v116, v117 op_sel:[0,0,1]
	v_lshl_add_u32 v134, s3, 8, v189
	v_lshl_or_b32 v132, s2, 7, v193
	v_mov_b64_e32 v[116:117], s[6:7]
	s_movk_i32 s4, 0x1600
	v_ashrrev_i32_e32 v133, 31, v132
	v_mad_i64_i32 v[118:119], s[2:3], v134, s4, v[116:117]
	v_cvt_f32_i32_e32 v113, v113
	v_cvt_f32_i32_e32 v112, v112
	v_cvt_f32_i32_e32 v109, v109
	v_cvt_f32_i32_e32 v108, v108
	v_cvt_f32_i32_e32 v115, v115
	v_cvt_f32_i32_e32 v114, v114
	v_lshl_add_u64 v[118:119], v[118:119], 0, v[132:133]
	s_nop 7
	s_nop 7
	s_nop 7
	global_store_dwordx2 v[118:119], v[122:123], off
	v_mul_f32_e32 v122, v188, v199
	v_or_b32_e32 v119, 16, v134
	v_mul_f32_e32 v118, 0xbfb8aa3b, v122
	v_pk_mul_f32 v[120:121], v[118:119], v[112:113] op_sel_hi:[0,1]
	v_pk_mul_f32 v[108:109], v[112:113], v[108:109]
	v_pk_mul_f32 v[112:113], v[118:119], v[114:115] op_sel_hi:[0,1]
	v_exp_f32_e32 v112, v112
	v_exp_f32_e32 v113, v113
	v_cvt_f32_i32_e32 v111, v111
	v_cvt_f32_i32_e32 v110, v110
	v_cvt_f32_i32_e32 v105, v105
	v_cvt_f32_i32_e32 v104, v104
	v_pk_add_f32 v[112:113], v[112:113], 1.0 op_sel_hi:[1,0]
	v_pk_mul_f32 v[110:111], v[114:115], v[110:111]
	v_cvt_f32_i32_e32 v101, v101
	v_pk_mul_f32 v[114:115], v[118:119], v[104:105] op_sel_hi:[0,1]
	v_cvt_f32_i32_e32 v100, v100
	v_cvt_f32_i32_e32 v107, v107
	v_cvt_f32_i32_e32 v106, v106
	v_exp_f32_e32 v120, v120
	v_exp_f32_e32 v121, v121
	v_rcp_f32_e32 v112, v112
	v_rcp_f32_e32 v113, v113
	v_exp_f32_e32 v114, v114
	v_exp_f32_e32 v115, v115
	v_pk_mul_f32 v[100:101], v[104:105], v[100:101]
	v_pk_mul_f32 v[104:105], v[118:119], v[106:107] op_sel_hi:[0,1]
	v_pk_add_f32 v[120:121], v[120:121], 1.0 op_sel_hi:[1,0]
	v_pk_mul_f32 v[110:111], v[112:113], v[110:111]
	v_pk_add_f32 v[112:113], v[114:115], 1.0 op_sel_hi:[1,0]
	v_exp_f32_e32 v104, v104
	v_exp_f32_e32 v105, v105
	v_rcp_f32_e32 v120, v120
	v_rcp_f32_e32 v121, v121
	v_rcp_f32_e32 v112, v112
	v_rcp_f32_e32 v113, v113
	v_cvt_f32_i32_e32 v103, v103
	v_cvt_f32_i32_e32 v102, v102
	v_mul_f32_e32 v122, v122, v122
	v_pk_add_f32 v[104:105], v[104:105], 1.0 op_sel_hi:[1,0]
	v_mul_f32_e32 v122, 4.0, v122
	v_pk_mul_f32 v[108:109], v[120:121], v[108:109]
	v_pk_mul_f32 v[100:101], v[112:113], v[100:101]
	v_rcp_f32_e32 v104, v104
	v_rcp_f32_e32 v105, v105
	v_pk_mul_f32 v[108:109], v[122:123], v[108:109] op_sel_hi:[0,1]
	v_pk_mul_f32 v[100:101], v[122:123], v[100:101] op_sel_hi:[0,1]
	v_pk_mul_f32 v[102:103], v[106:107], v[102:103]
	v_mov_b32_e32 v106, v3
	v_mov_b32_e32 v107, v3
	v_cvt_pk_fp8_f32 v106, v108, v109
	v_cvt_pk_fp8_f32 v107, v100, v101
	v_pk_mul_f32 v[100:101], v[104:105], v[102:103]
	v_pk_mul_f32 v[110:111], v[122:123], v[110:111] op_sel_hi:[0,1]
	v_pk_mul_f32 v[100:101], v[122:123], v[100:101] op_sel_hi:[0,1]
	v_cvt_pk_fp8_f32 v106, v110, v111 op_sel:[0,0,1]
	v_cvt_pk_fp8_f32 v107, v100, v101 op_sel:[0,0,1]
	v_cvt_f32_i32_e32 v97, v97
	v_cvt_f32_i32_e32 v96, v96
	v_cvt_f32_i32_e32 v93, v93
	v_cvt_f32_i32_e32 v92, v92
	v_cvt_f32_i32_e32 v99, v99
	v_cvt_f32_i32_e32 v98, v98
	v_mad_i64_i32 v[100:101], s[2:3], v119, s4, v[116:117]
	v_lshl_add_u64 v[100:101], v[100:101], 0, v[132:133]
	v_mul_f32_e32 v104, v188, v198
	global_store_dwordx2 v[100:101], v[106:107], off
	v_or_b32_e32 v101, 32, v134
	v_mul_f32_e32 v100, 0xbfb8aa3b, v104
;     __device__ __forceinline__ void operator()(const f32x4 (&acc)[2][2][4][2], const Unit& u, int wr, int wc, int fr, int fq, const float (&pre)[8]) const {
;     ...
;                         const float fa0 = acc[ai][0][m][n][2 * jp], fa1 = acc[ai][0][m][n][2 * jp + 1], fb0 = acc[ai][1][m][n][2 * jp], fb1 = acc[ai][1][m][n][2 * jp + 1];
;                         const f32x2 A = iacc ? (f32x2){(float)__float_as_int(fa0), (float)__float_as_int(fa1)} : (f32x2){fa0, fa1};
;                         const f32x2 B = iacc ? (f32x2){(float)__float_as_int(fb0), (float)__float_as_int(fb1)} : (f32x2){fb0, fb1};
;                         const f32x2 X = A * ke;
;                         const f32x2 D = (f32x2){__builtin_amdgcn_exp2f(X[0]), __builtin_amdgcn_exp2f(X[1])} + 1.0f;
;                         const f32x2 R = {__builtin_amdgcn_rcpf(D[0]), __builtin_amdgcn_rcpf(D[1])};
;                         hv[n * 2 + jp] = ((A * B) * R) * K;
;                     }
;                 f16x8 hi, lo;
;                 if (h8) {
;                     int p0 = __builtin_amdgcn_cvt_pk_fp8_f32(hv[0][0], hv[0][1], 0, false); p0 = __builtin_amdgcn_cvt_pk_fp8_f32(hv[1][0], hv[1][1], p0, true);
;                     int p1 = __builtin_amdgcn_cvt_pk_fp8_f32(hv[2][0], hv[2][1], 0, false); p1 = __builtin_amdgcn_cvt_pk_fp8_f32(hv[3][0], hv[3][1], p1, true);
;                     *(u32x2v*)((unsigned char*)Hh + off) = (u32x2v){(unsigned)p0, (unsigned)p1}; }
	v_pk_mul_f32 v[102:103], v[100:101], v[96:97] op_sel_hi:[0,1]
	v_pk_mul_f32 v[92:93], v[96:97], v[92:93]
	v_pk_mul_f32 v[96:97], v[100:101], v[98:99] op_sel_hi:[0,1]
	v_exp_f32_e32 v96, v96
	v_exp_f32_e32 v97, v97
	v_cvt_f32_i32_e32 v95, v95
	v_cvt_f32_i32_e32 v94, v94
	v_cvt_f32_i32_e32 v89, v89
	v_cvt_f32_i32_e32 v88, v88
	v_pk_add_f32 v[96:97], v[96:97], 1.0 op_sel_hi:[1,0]
	v_pk_mul_f32 v[94:95], v[98:99], v[94:95]
	v_cvt_f32_i32_e32 v85, v85
	v_pk_mul_f32 v[98:99], v[100:101], v[88:89] op_sel_hi:[0,1]
	v_cvt_f32_i32_e32 v84, v84
	v_cvt_f32_i32_e32 v91, v91
	v_cvt_f32_i32_e32 v90, v90
	v_exp_f32_e32 v102, v102
	v_exp_f32_e32 v103, v103
	v_rcp_f32_e32 v96, v96
	v_rcp_f32_e32 v97, v97
	v_exp_f32_e32 v98, v98
	v_exp_f32_e32 v99, v99
	v_pk_mul_f32 v[84:85], v[88:89], v[84:85]
	v_pk_mul_f32 v[88:89], v[100:101], v[90:91] op_sel_hi:[0,1]
	v_pk_add_f32 v[102:103], v[102:103], 1.0 op_sel_hi:[1,0]
	v_pk_mul_f32 v[94:95], v[96:97], v[94:95]
	v_pk_add_f32 v[96:97], v[98:99], 1.0 op_sel_hi:[1,0]
	v_exp_f32_e32 v88, v88
	v_exp_f32_e32 v89, v89
	v_rcp_f32_e32 v102, v102
	v_rcp_f32_e32 v103, v103
	v_rcp_f32_e32 v96, v96
	v_rcp_f32_e32 v97, v97
	v_cvt_f32_i32_e32 v87, v87
	v_cvt_f32_i32_e32 v86, v86
	v_mul_f32_e32 v104, v104, v104
	v_pk_add_f32 v[88:89], v[88:89], 1.0 op_sel_hi:[1,0]
	v_mul_f32_e32 v104, 4.0, v104
	v_pk_mul_f32 v[92:93], v[102:103], v[92:93]
	v_pk_mul_f32 v[84:85], v[96:97], v[84:85]
	v_rcp_f32_e32 v88, v88
	v_rcp_f32_e32 v89, v89
	v_pk_mul_f32 v[92:93], v[104:105], v[92:93] op_sel_hi:[0,1]
	v_pk_mul_f32 v[84:85], v[104:105], v[84:85] op_sel_hi:[0,1]
	v_pk_mul_f32 v[86:87], v[90:91], v[86:87]
	v_mov_b32_e32 v90, v3
	v_mov_b32_e32 v91, v3
	v_cvt_pk_fp8_f32 v90, v92, v93
	v_cvt_pk_fp8_f32 v91, v84, v85
	v_pk_mul_f32 v[84:85], v[88:89], v[86:87]
	v_pk_mul_f32 v[94:95], v[104:105], v[94:95] op_sel_hi:[0,1]
	v_pk_mul_f32 v[84:85], v[104:105], v[84:85] op_sel_hi:[0,1]
	v_cvt_pk_fp8_f32 v90, v94, v95 op_sel:[0,0,1]
	v_cvt_pk_fp8_f32 v91, v84, v85 op_sel:[0,0,1]
	v_cvt_f32_i32_e32 v81, v81
	v_cvt_f32_i32_e32 v80, v80
	v_cvt_f32_i32_e32 v77, v77
	v_cvt_f32_i32_e32 v76, v76
	v_cvt_f32_i32_e32 v83, v83
	v_cvt_f32_i32_e32 v82, v82
	v_mad_i64_i32 v[84:85], s[2:3], v101, s4, v[116:117]
	v_lshl_add_u64 v[84:85], v[84:85], 0, v[132:133]
	v_mul_f32_e32 v88, v188, v197
	global_store_dwordx2 v[84:85], v[90:91], off
	v_or_b32_e32 v85, 48, v134
	v_mul_f32_e32 v84, 0xbfb8aa3b, v88
	v_pk_mul_f32 v[86:87], v[84:85], v[80:81] op_sel_hi:[0,1]
	v_pk_mul_f32 v[76:77], v[80:81], v[76:77]
	v_pk_mul_f32 v[80:81], v[84:85], v[82:83] op_sel_hi:[0,1]
	v_exp_f32_e32 v80, v80
	v_exp_f32_e32 v81, v81
	v_cvt_f32_i32_e32 v79, v79
	v_cvt_f32_i32_e32 v78, v78
	v_cvt_f32_i32_e32 v73, v73
	v_cvt_f32_i32_e32 v72, v72
	v_pk_add_f32 v[80:81], v[80:81], 1.0 op_sel_hi:[1,0]
	v_pk_mul_f32 v[78:79], v[82:83], v[78:79]
	v_cvt_f32_i32_e32 v69, v69
	v_pk_mul_f32 v[82:83], v[84:85], v[72:73] op_sel_hi:[0,1]
	v_cvt_f32_i32_e32 v68, v68
	v_cvt_f32_i32_e32 v75, v75
	v_cvt_f32_i32_e32 v74, v74
	v_exp_f32_e32 v86, v86
	v_exp_f32_e32 v87, v87
	v_rcp_f32_e32 v80, v80
	v_rcp_f32_e32 v81, v81
	v_exp_f32_e32 v82, v82
	v_exp_f32_e32 v83, v83
	v_pk_mul_f32 v[68:69], v[72:73], v[68:69]
	v_pk_mul_f32 v[72:73], v[84:85], v[74:75] op_sel_hi:[0,1]
	v_pk_add_f32 v[86:87], v[86:87], 1.0 op_sel_hi:[1,0]
	v_pk_mul_f32 v[78:79], v[80:81], v[78:79]
	v_pk_add_f32 v[80:81], v[82:83], 1.0 op_sel_hi:[1,0]
	v_exp_f32_e32 v72, v72
	v_exp_f32_e32 v73, v73
	v_rcp_f32_e32 v86, v86
	v_rcp_f32_e32 v87, v87
	v_rcp_f32_e32 v80, v80
	v_rcp_f32_e32 v81, v81
	v_cvt_f32_i32_e32 v71, v71
	v_cvt_f32_i32_e32 v70, v70
	v_mul_f32_e32 v88, v88, v88
	v_pk_add_f32 v[72:73], v[72:73], 1.0 op_sel_hi:[1,0]
	v_mul_f32_e32 v88, 4.0, v88
	v_pk_mul_f32 v[76:77], v[86:87], v[76:77]
	v_pk_mul_f32 v[68:69], v[80:81], v[68:69]
	v_rcp_f32_e32 v72, v72
	v_rcp_f32_e32 v73, v73
	v_pk_mul_f32 v[76:77], v[88:89], v[76:77] op_sel_hi:[0,1]
	v_pk_mul_f32 v[68:69], v[88:89], v[68:69] op_sel_hi:[0,1]
	v_pk_mul_f32 v[70:71], v[74:75], v[70:71]
	v_mov_b32_e32 v74, v3
	v_mov_b32_e32 v75, v3
	v_cvt_pk_fp8_f32 v74, v76, v77
	v_cvt_pk_fp8_f32 v75, v68, v69
	v_pk_mul_f32 v[68:69], v[72:73], v[70:71]
	v_pk_mul_f32 v[78:79], v[88:89], v[78:79] op_sel_hi:[0,1]
	v_pk_mul_f32 v[68:69], v[88:89], v[68:69] op_sel_hi:[0,1]
	v_cvt_pk_fp8_f32 v74, v78, v79 op_sel:[0,0,1]
	v_cvt_pk_fp8_f32 v75, v68, v69 op_sel:[0,0,1]
	v_cvt_f32_i32_e32 v65, v65
	v_cvt_f32_i32_e32 v64, v64
	v_cvt_f32_i32_e32 v61, v61
	v_cvt_f32_i32_e32 v60, v60
	v_cvt_f32_i32_e32 v67, v67
	v_cvt_f32_i32_e32 v66, v66
	v_mad_i64_i32 v[68:69], s[2:3], v85, s4, v[116:117]
	v_lshl_add_u64 v[68:69], v[68:69], 0, v[132:133]
	v_mul_f32_e32 v72, v188, v196
	global_store_dwordx2 v[68:69], v[74:75], off
	v_add_u32_e32 v69, 0x80, v134
	v_mul_f32_e32 v68, 0xbfb8aa3b, v72
	v_pk_mul_f32 v[70:71], v[68:69], v[64:65] op_sel_hi:[0,1]
	v_pk_mul_f32 v[60:61], v[64:65], v[60:61]
	v_pk_mul_f32 v[64:65], v[68:69], v[66:67] op_sel_hi:[0,1]
	v_exp_f32_e32 v64, v64
	v_exp_f32_e32 v65, v65
	v_cvt_f32_i32_e32 v63, v63
	v_cvt_f32_i32_e32 v62, v62
	v_cvt_f32_i32_e32 v57, v57
	v_cvt_f32_i32_e32 v56, v56
	v_pk_add_f32 v[64:65], v[64:65], 1.0 op_sel_hi:[1,0]
	v_pk_mul_f32 v[62:63], v[66:67], v[62:63]
	v_cvt_f32_i32_e32 v53, v53
	v_pk_mul_f32 v[66:67], v[68:69], v[56:57] op_sel_hi:[0,1]
	v_cvt_f32_i32_e32 v52, v52
	v_cvt_f32_i32_e32 v59, v59
	v_cvt_f32_i32_e32 v58, v58
	v_exp_f32_e32 v70, v70
	v_exp_f32_e32 v71, v71
	v_rcp_f32_e32 v64, v64
	v_rcp_f32_e32 v65, v65
	v_exp_f32_e32 v66, v66
	v_exp_f32_e32 v67, v67
	v_pk_mul_f32 v[52:53], v[56:57], v[52:53]
	v_pk_mul_f32 v[56:57], v[68:69], v[58:59] op_sel_hi:[0,1]
;     __device__ __forceinline__ void operator()(const f32x4 (&acc)[2][2][4][2], const Unit& u, int wr, int wc, int fr, int fq, const float (&pre)[8]) const {
;     ...
;             for (int m = 0; m < 4; ++m) {
;                 const size_t off = (size_t)(row0 + ai * HALF + m * 16) * DFF + col0;
;                 const float rsc = pre[ai * 4 + m];
;                 const float ka = us * rsc * (1.0f / KREP), ke = ka * -1.4426950408889634f, K = ka * ka * (h8 ? SH8 : SA);
;                 f32x2 hv[4];
; #pragma unroll
;                 for (int n = 0; n < 2; ++n)
; #pragma unroll
;                     for (int jp = 0; jp < 2; ++jp) {
;                         const float fa0 = acc[ai][0][m][n][2 * jp], fa1 = acc[ai][0][m][n][2 * jp + 1], fb0 = acc[ai][1][m][n][2 * jp], fb1 = acc[ai][1][m][n][2 * jp + 1];
;                         const f32x2 A = iacc ? (f32x2){(float)__float_as_int(fa0), (float)__float_as_int(fa1)} : (f32x2){fa0, fa1};
;                         const f32x2 B = iacc ? (f32x2){(float)__float_as_int(fb0), (float)__float_as_int(fb1)} : (f32x2){fb0, fb1};
;                         const f32x2 X = A * ke;
;                         const f32x2 D = (f32x2){__builtin_amdgcn_exp2f(X[0]), __builtin_amdgcn_exp2f(X[1])} + 1.0f;
;                         const f32x2 R = {__builtin_amdgcn_rcpf(D[0]), __builtin_amdgcn_rcpf(D[1])};
;                         hv[n * 2 + jp] = ((A * B) * R) * K;
;                     }
;                 f16x8 hi, lo;
;                 if (h8) {
;                     int p0 = __builtin_amdgcn_cvt_pk_fp8_f32(hv[0][0], hv[0][1], 0, false); p0 = __builtin_amdgcn_cvt_pk_fp8_f32(hv[1][0], hv[1][1], p0, true);
;                     int p1 = __builtin_amdgcn_cvt_pk_fp8_f32(hv[2][0], hv[2][1], 0, false); p1 = __builtin_amdgcn_cvt_pk_fp8_f32(hv[3][0], hv[3][1], p1, true);
;                     *(u32x2v*)((unsigned char*)Hh + off) = (u32x2v){(unsigned)p0, (unsigned)p1}; }
	v_pk_add_f32 v[70:71], v[70:71], 1.0 op_sel_hi:[1,0]
	v_pk_mul_f32 v[62:63], v[64:65], v[62:63]
	v_pk_add_f32 v[64:65], v[66:67], 1.0 op_sel_hi:[1,0]
	v_exp_f32_e32 v56, v56
	v_exp_f32_e32 v57, v57
	v_rcp_f32_e32 v70, v70
	v_rcp_f32_e32 v71, v71
	v_rcp_f32_e32 v64, v64
	v_rcp_f32_e32 v65, v65
	v_cvt_f32_i32_e32 v55, v55
	v_cvt_f32_i32_e32 v54, v54
	v_mul_f32_e32 v72, v72, v72
	v_pk_add_f32 v[56:57], v[56:57], 1.0 op_sel_hi:[1,0]
	v_mul_f32_e32 v72, 4.0, v72
	v_pk_mul_f32 v[60:61], v[70:71], v[60:61]
	v_pk_mul_f32 v[52:53], v[64:65], v[52:53]
	v_rcp_f32_e32 v56, v56
	v_rcp_f32_e32 v57, v57
	v_pk_mul_f32 v[60:61], v[72:73], v[60:61] op_sel_hi:[0,1]
	v_pk_mul_f32 v[52:53], v[72:73], v[52:53] op_sel_hi:[0,1]
	v_pk_mul_f32 v[54:55], v[58:59], v[54:55]
	v_mov_b32_e32 v58, v3
	v_mov_b32_e32 v59, v3
	v_cvt_pk_fp8_f32 v58, v60, v61
	v_cvt_pk_fp8_f32 v59, v52, v53
	v_pk_mul_f32 v[52:53], v[56:57], v[54:55]
	v_pk_mul_f32 v[62:63], v[72:73], v[62:63] op_sel_hi:[0,1]
	v_pk_mul_f32 v[52:53], v[72:73], v[52:53] op_sel_hi:[0,1]
	v_cvt_pk_fp8_f32 v58, v62, v63 op_sel:[0,0,1]
	v_cvt_pk_fp8_f32 v59, v52, v53 op_sel:[0,0,1]
	v_cvt_f32_i32_e32 v49, v49
	v_cvt_f32_i32_e32 v48, v48
	v_cvt_f32_i32_e32 v45, v45
	v_cvt_f32_i32_e32 v44, v44
	v_cvt_f32_i32_e32 v51, v51
	v_cvt_f32_i32_e32 v50, v50
	v_mad_i64_i32 v[52:53], s[2:3], v69, s4, v[116:117]
	v_lshl_add_u64 v[52:53], v[52:53], 0, v[132:133]
	v_mul_f32_e32 v56, v188, v195
	global_store_dwordx2 v[52:53], v[58:59], off
	v_add_u32_e32 v53, 0x90, v134
	v_mul_f32_e32 v52, 0xbfb8aa3b, v56
	v_pk_mul_f32 v[54:55], v[52:53], v[48:49] op_sel_hi:[0,1]
	v_pk_mul_f32 v[44:45], v[48:49], v[44:45]
	v_pk_mul_f32 v[48:49], v[52:53], v[50:51] op_sel_hi:[0,1]
	v_exp_f32_e32 v48, v48
	v_exp_f32_e32 v49, v49
	v_cvt_f32_i32_e32 v47, v47
	v_cvt_f32_i32_e32 v46, v46
	v_cvt_f32_i32_e32 v41, v41
	v_cvt_f32_i32_e32 v40, v40
	v_pk_add_f32 v[48:49], v[48:49], 1.0 op_sel_hi:[1,0]
	v_pk_mul_f32 v[46:47], v[50:51], v[46:47]
	v_cvt_f32_i32_e32 v37, v37
	v_pk_mul_f32 v[50:51], v[52:53], v[40:41] op_sel_hi:[0,1]
	v_cvt_f32_i32_e32 v36, v36
	v_cvt_f32_i32_e32 v43, v43
	v_cvt_f32_i32_e32 v42, v42
	v_exp_f32_e32 v54, v54
	v_exp_f32_e32 v55, v55
	v_rcp_f32_e32 v48, v48
	v_rcp_f32_e32 v49, v49
	v_exp_f32_e32 v50, v50
	v_exp_f32_e32 v51, v51
	v_pk_mul_f32 v[36:37], v[40:41], v[36:37]
	v_pk_mul_f32 v[40:41], v[52:53], v[42:43] op_sel_hi:[0,1]
	v_pk_add_f32 v[54:55], v[54:55], 1.0 op_sel_hi:[1,0]
	v_pk_mul_f32 v[46:47], v[48:49], v[46:47]
	v_pk_add_f32 v[48:49], v[50:51], 1.0 op_sel_hi:[1,0]
	v_exp_f32_e32 v40, v40
	v_exp_f32_e32 v41, v41
	v_rcp_f32_e32 v54, v54
	v_rcp_f32_e32 v55, v55
	v_rcp_f32_e32 v48, v48
	v_rcp_f32_e32 v49, v49
	v_cvt_f32_i32_e32 v39, v39
	v_cvt_f32_i32_e32 v38, v38
	v_mul_f32_e32 v56, v56, v56
	v_pk_add_f32 v[40:41], v[40:41], 1.0 op_sel_hi:[1,0]
	v_mul_f32_e32 v56, 4.0, v56
	v_pk_mul_f32 v[44:45], v[54:55], v[44:45]
	v_pk_mul_f32 v[36:37], v[48:49], v[36:37]
	v_rcp_f32_e32 v40, v40
	v_rcp_f32_e32 v41, v41
	v_pk_mul_f32 v[44:45], v[56:57], v[44:45] op_sel_hi:[0,1]
	v_pk_mul_f32 v[36:37], v[56:57], v[36:37] op_sel_hi:[0,1]
	v_pk_mul_f32 v[38:39], v[42:43], v[38:39]
	v_mov_b32_e32 v42, v3
	v_mov_b32_e32 v43, v3
	v_cvt_pk_fp8_f32 v42, v44, v45
	v_cvt_pk_fp8_f32 v43, v36, v37
	v_pk_mul_f32 v[36:37], v[40:41], v[38:39]
	v_pk_mul_f32 v[46:47], v[56:57], v[46:47] op_sel_hi:[0,1]
	v_pk_mul_f32 v[36:37], v[56:57], v[36:37] op_sel_hi:[0,1]
	v_cvt_pk_fp8_f32 v42, v46, v47 op_sel:[0,0,1]
	v_cvt_pk_fp8_f32 v43, v36, v37 op_sel:[0,0,1]
	v_cvt_f32_i32_e32 v33, v33
	v_cvt_f32_i32_e32 v32, v32
	v_cvt_f32_i32_e32 v29, v29
	v_cvt_f32_i32_e32 v28, v28
	v_cvt_f32_i32_e32 v35, v35
	v_cvt_f32_i32_e32 v34, v34
	v_mad_i64_i32 v[36:37], s[2:3], v53, s4, v[116:117]
	v_lshl_add_u64 v[36:37], v[36:37], 0, v[132:133]
	v_mul_f32_e32 v40, v188, v192
	global_store_dwordx2 v[36:37], v[42:43], off
	v_add_u32_e32 v37, 0xa0, v134
	v_mul_f32_e32 v36, 0xbfb8aa3b, v40
	v_pk_mul_f32 v[38:39], v[36:37], v[32:33] op_sel_hi:[0,1]
	v_pk_mul_f32 v[28:29], v[32:33], v[28:29]
	v_pk_mul_f32 v[32:33], v[36:37], v[34:35] op_sel_hi:[0,1]
	v_exp_f32_e32 v32, v32
	v_exp_f32_e32 v33, v33
	v_cvt_f32_i32_e32 v31, v31
	v_cvt_f32_i32_e32 v30, v30
	v_cvt_f32_i32_e32 v25, v25
	v_cvt_f32_i32_e32 v24, v24
	v_pk_add_f32 v[32:33], v[32:33], 1.0 op_sel_hi:[1,0]
	v_pk_mul_f32 v[30:31], v[34:35], v[30:31]
	v_cvt_f32_i32_e32 v21, v21
	v_pk_mul_f32 v[34:35], v[36:37], v[24:25] op_sel_hi:[0,1]
	v_cvt_f32_i32_e32 v20, v20
	v_cvt_f32_i32_e32 v27, v27
	v_cvt_f32_i32_e32 v26, v26
;     __device__ __forceinline__ void preload(float (&pre)[8], const Unit& u, int wr, int fr) const {
;         const int row0 = u.pm * BM + wr * 64 + fr;
; #pragma unroll
;         for (int ai = 0; ai < 2; ++ai)
; #pragma unroll
;             for (int m = 0; m < 4; ++m) pre[ai * 4 + m] = rs ? rs[row0 + ai * HALF + m * 16] : 1.0f;
;     }
;     __device__ __forceinline__ void operator()(const f32x4 (&acc)[2][2][4][2], const Unit& u, int wr, int wc, int fr, int fq, const float (&pre)[8]) const {
;     ...
;             for (int m = 0; m < 4; ++m) {
;                 const size_t off = (size_t)(row0 + ai * HALF + m * 16) * DFF + col0;
;                 const float rsc = pre[ai * 4 + m];
;                 const float ka = us * rsc * (1.0f / KREP), ke = ka * -1.4426950408889634f, K = ka * ka * (h8 ? SH8 : SA);
;                 f32x2 hv[4];
; #pragma unroll
;                 for (int n = 0; n < 2; ++n)
; #pragma unroll
;                     for (int jp = 0; jp < 2; ++jp) {
;                         const float fa0 = acc[ai][0][m][n][2 * jp], fa1 = acc[ai][0][m][n][2 * jp + 1], fb0 = acc[ai][1][m][n][2 * jp], fb1 = acc[ai][1][m][n][2 * jp + 1];
;                         const f32x2 A = iacc ? (f32x2){(float)__float_as_int(fa0), (float)__float_as_int(fa1)} : (f32x2){fa0, fa1};
;                         const f32x2 B = iacc ? (f32x2){(float)__float_as_int(fb0), (float)__float_as_int(fb1)} : (f32x2){fb0, fb1};
;                         const f32x2 X = A * ke;
;                         const f32x2 D = (f32x2){__builtin_amdgcn_exp2f(X[0]), __builtin_amdgcn_exp2f(X[1])} + 1.0f;
;                         const f32x2 R = {__builtin_amdgcn_rcpf(D[0]), __builtin_amdgcn_rcpf(D[1])};
;                         hv[n * 2 + jp] = ((A * B) * R) * K;
;                     }
;                 f16x8 hi, lo;
;                 if (h8) {
;                     int p0 = __builtin_amdgcn_cvt_pk_fp8_f32(hv[0][0], hv[0][1], 0, false); p0 = __builtin_amdgcn_cvt_pk_fp8_f32(hv[1][0], hv[1][1], p0, true);
;                     int p1 = __builtin_amdgcn_cvt_pk_fp8_f32(hv[2][0], hv[2][1], 0, false); p1 = __builtin_amdgcn_cvt_pk_fp8_f32(hv[3][0], hv[3][1], p1, true);
;                     *(u32x2v*)((unsigned char*)Hh + off) = (u32x2v){(unsigned)p0, (unsigned)p1}; }
	v_exp_f32_e32 v38, v38
	v_exp_f32_e32 v39, v39
	v_rcp_f32_e32 v32, v32
	v_rcp_f32_e32 v33, v33
	v_exp_f32_e32 v34, v34
	v_exp_f32_e32 v35, v35
	v_pk_mul_f32 v[20:21], v[24:25], v[20:21]
	v_pk_mul_f32 v[24:25], v[36:37], v[26:27] op_sel_hi:[0,1]
	v_pk_add_f32 v[38:39], v[38:39], 1.0 op_sel_hi:[1,0]
	v_pk_mul_f32 v[30:31], v[32:33], v[30:31]
	v_pk_add_f32 v[32:33], v[34:35], 1.0 op_sel_hi:[1,0]
	v_exp_f32_e32 v24, v24
	v_exp_f32_e32 v25, v25
	v_rcp_f32_e32 v38, v38
	v_rcp_f32_e32 v39, v39
	v_rcp_f32_e32 v32, v32
	v_rcp_f32_e32 v33, v33
	v_cvt_f32_i32_e32 v23, v23
	v_cvt_f32_i32_e32 v22, v22
	v_mul_f32_e32 v40, v40, v40
	v_pk_add_f32 v[24:25], v[24:25], 1.0 op_sel_hi:[1,0]
	v_mul_f32_e32 v40, 4.0, v40
	v_pk_mul_f32 v[28:29], v[38:39], v[28:29]
	v_pk_mul_f32 v[20:21], v[32:33], v[20:21]
	v_rcp_f32_e32 v24, v24
	v_rcp_f32_e32 v25, v25
	v_pk_mul_f32 v[28:29], v[40:41], v[28:29] op_sel_hi:[0,1]
	v_pk_mul_f32 v[20:21], v[40:41], v[20:21] op_sel_hi:[0,1]
	v_pk_mul_f32 v[22:23], v[26:27], v[22:23]
	v_mov_b32_e32 v26, v3
	v_mov_b32_e32 v27, v3
	v_cvt_pk_fp8_f32 v26, v28, v29
	v_cvt_pk_fp8_f32 v27, v20, v21
	v_pk_mul_f32 v[20:21], v[24:25], v[22:23]
	v_pk_mul_f32 v[30:31], v[40:41], v[30:31] op_sel_hi:[0,1]
	v_pk_mul_f32 v[20:21], v[40:41], v[20:21] op_sel_hi:[0,1]
	v_cvt_pk_fp8_f32 v26, v30, v31 op_sel:[0,0,1]
	v_cvt_pk_fp8_f32 v27, v20, v21 op_sel:[0,0,1]
	v_cvt_f32_i32_e32 v17, v17
	v_cvt_f32_i32_e32 v16, v16
	v_cvt_f32_i32_e32 v13, v13
	v_cvt_f32_i32_e32 v12, v12
	v_cvt_f32_i32_e32 v19, v19
	v_cvt_f32_i32_e32 v18, v18
	v_mad_i64_i32 v[20:21], s[2:3], v37, s4, v[116:117]
	v_lshl_add_u64 v[20:21], v[20:21], 0, v[132:133]
	v_mul_f32_e32 v24, v188, v191
	global_store_dwordx2 v[20:21], v[26:27], off
	v_add_u32_e32 v21, 0xb0, v134
	v_mul_f32_e32 v20, 0xbfb8aa3b, v24
	v_pk_mul_f32 v[22:23], v[20:21], v[16:17] op_sel_hi:[0,1]
	v_pk_mul_f32 v[12:13], v[16:17], v[12:13]
	v_pk_mul_f32 v[16:17], v[20:21], v[18:19] op_sel_hi:[0,1]
	v_exp_f32_e32 v16, v16
	v_exp_f32_e32 v17, v17
	v_cvt_f32_i32_e32 v15, v15
	v_cvt_f32_i32_e32 v14, v14
	v_cvt_f32_i32_e32 v9, v9
	v_cvt_f32_i32_e32 v8, v8
	v_pk_add_f32 v[16:17], v[16:17], 1.0 op_sel_hi:[1,0]
	v_pk_mul_f32 v[14:15], v[18:19], v[14:15]
	v_cvt_f32_i32_e32 v5, v5
	v_pk_mul_f32 v[18:19], v[20:21], v[8:9] op_sel_hi:[0,1]
	v_cvt_f32_i32_e32 v4, v4
	v_cvt_f32_i32_e32 v11, v11
	v_cvt_f32_i32_e32 v10, v10
	v_exp_f32_e32 v22, v22
	v_exp_f32_e32 v23, v23
	v_rcp_f32_e32 v16, v16
	v_rcp_f32_e32 v17, v17
	v_exp_f32_e32 v18, v18
	v_exp_f32_e32 v19, v19
	v_pk_mul_f32 v[4:5], v[8:9], v[4:5]
	v_pk_mul_f32 v[8:9], v[20:21], v[10:11] op_sel_hi:[0,1]
	v_pk_add_f32 v[22:23], v[22:23], 1.0 op_sel_hi:[1,0]
	v_pk_mul_f32 v[14:15], v[16:17], v[14:15]
	v_pk_add_f32 v[16:17], v[18:19], 1.0 op_sel_hi:[1,0]
	v_exp_f32_e32 v8, v8
	v_exp_f32_e32 v9, v9
	v_rcp_f32_e32 v22, v22
	v_rcp_f32_e32 v23, v23
	v_rcp_f32_e32 v16, v16
	v_rcp_f32_e32 v17, v17
	v_cvt_f32_i32_e32 v7, v7
	v_cvt_f32_i32_e32 v6, v6
	v_mul_f32_e32 v24, v24, v24
	v_pk_add_f32 v[8:9], v[8:9], 1.0 op_sel_hi:[1,0]
	v_mul_f32_e32 v24, 4.0, v24
	v_pk_mul_f32 v[12:13], v[22:23], v[12:13]
	v_pk_mul_f32 v[4:5], v[16:17], v[4:5]
	v_rcp_f32_e32 v8, v8
	v_rcp_f32_e32 v9, v9
	v_pk_mul_f32 v[12:13], v[24:25], v[12:13] op_sel_hi:[0,1]
	v_pk_mul_f32 v[4:5], v[24:25], v[4:5] op_sel_hi:[0,1]
	v_pk_mul_f32 v[6:7], v[10:11], v[6:7]
	v_mov_b32_e32 v10, v3
	v_mov_b32_e32 v11, v3
	v_cvt_pk_fp8_f32 v10, v12, v13
	v_cvt_pk_fp8_f32 v11, v4, v5
	v_pk_mul_f32 v[4:5], v[8:9], v[6:7]
	v_pk_mul_f32 v[14:15], v[24:25], v[14:15] op_sel_hi:[0,1]
	v_pk_mul_f32 v[4:5], v[24:25], v[4:5] op_sel_hi:[0,1]
	v_cvt_pk_fp8_f32 v10, v14, v15 op_sel:[0,0,1]
	v_cvt_pk_fp8_f32 v11, v4, v5 op_sel:[0,0,1]
	v_mad_i64_i32 v[4:5], s[2:3], v21, s4, v[116:117]
	v_lshl_add_u64 v[4:5], v[4:5], 0, v[132:133]
	s_andn2_b64 vcc, exec, s[42:43]
	s_mov_b64 s[42:43], -1
	global_store_dwordx2 v[4:5], v[10:11], off
	s_cbranch_vccnz .LBB0_1272
	v_lshl_add_u32 v4, s20, 8, v189
	v_ashrrev_i32_e32 v5, 31, v4
	v_lshl_add_u64 v[4:5], v[4:5], 2, s[16:17]
	global_load_dword v200, v[4:5], off
	global_load_dword v199, v[4:5], off offset:64
	global_load_dword v198, v[4:5], off offset:128
	global_load_dword v197, v[4:5], off offset:192
	global_load_dword v196, v[4:5], off offset:512
	global_load_dword v195, v[4:5], off offset:576
	global_load_dword v192, v[4:5], off offset:640
	global_load_dword v191, v[4:5], off offset:704
	s_andn2_b64 vcc, exec, s[0:1]
	s_cbranch_vccnz .LBB0_1271
	s_barrier
	s_branch .LBB0_1271

; #define G_STAGE(bufoff, gbase, voff) do { _Pragma("unroll") for (int _i = 0; _i < 2; ++_i) \
;         __builtin_amdgcn_global_load_lds((const unsigned*)((const char*)(gbase) + (voff)[_i]), (LAS unsigned*)(lds + (bufoff) + ldsw + _i * 8192), 16, 0, 0); } while (0)
; #define G_LDA(dst, b, h) do { _Pragma("unroll") for (int m = 0; m < 4; ++m) { const i32x4 _p0 = *(const LAS i32x4*)(lds + G_SA(b, h) + aoff + m * 2048), _p1 = *(const LAS i32x4*)(lds + G_SA(b, h) + aoff + m * 2048 + 1024); \
;         dst[m] = __builtin_shufflevector(_p0, _p1, 0, 1, 2, 3, 4, 5, 6, 7); } } while (0)
; #define G_LDB(dst, b, h) do { _Pragma("unroll") for (int n = 0; n < 2; ++n) { const i32x4 _p0 = *(const LAS i32x4*)(lds + G_SB(b, h) + boff + n * 2048), _p1 = *(const LAS i32x4*)(lds + G_SB(b, h) + boff + n * 2048 + 1024); \
;         dst[n] = __builtin_shufflevector(_p0, _p1, 0, 1, 2, 3, 4, 5, 6, 7); } } while (0)
; #define G_WAIT_V(n) asm volatile("s_waitcnt vmcnt(" #n ")" ::: "memory")
; #define G_WAIT_L(n) asm volatile("s_waitcnt lgkmcnt(" #n ")" ::: "memory")
; #define G_BAR __builtin_amdgcn_s_barrier()
; #define G_SCHED __builtin_amdgcn_sched_barrier(0)
; template <int NS, int MODE  , class Epi>
; __device__ __forceinline__ void gemm_phase(LAS unsigned char* lds, const Gemm g, const StaticOrder& S, const Epi& E) {
;     ...
;             G_LDB(B0, 0, 0); G_LDB(B1, 0, 1); G_SCHED; G_LDA(At, 0, 0); G_STAGE(G_SA(1, 1), a1 + hstep, voffA);
;             G_WAIT_V(8); G_WAIT_L(0); G_BAR; G_MMA(0, 0, At, B0); G_MMA(0, 1, At, B1); G_BAR; G_SCHED;
;             G_LDA(At, 0, 1); G_STAGE(G_SB(0, 0), b2, voffB); G_STAGE(G_SB(0, 1), b2 + hstep, voffB); G_STAGE(G_SA(0, 0), a2, voffA);
;             G_WAIT_V(8); G_WAIT_L(0); G_BAR; G_MMA(1, 0, At, B0); G_MMA(1, 1, At, B1); G_BAR; G_SCHED;
.LBB0_1357:
	s_add_i32 s25, 0, 0x10000
	s_add_i32 s30, 0, 0x14000
	v_add_u32_e32 v4, s25, v214
	v_add_u32_e32 v16, s30, v214
	ds_read_b128 v[20:23], v4
	ds_read_b128 v[24:27], v4 offset:1024
	ds_read_b128 v[28:31], v4 offset:2048
	ds_read_b128 v[32:35], v4 offset:3072
	ds_read_b128 v[4:7], v16
	ds_read_b128 v[8:11], v16 offset:1024
	ds_read_b128 v[12:15], v16 offset:2048
	ds_read_b128 v[16:19], v16 offset:3072
	v_lshl_add_u64 v[176:177], v[164:165], 0, s[48:49]
	s_add_i32 m0, s19, 0xc000
	ds_read_b128 v[188:191], v216
	ds_read_b128 v[192:195], v216 offset:1024
	ds_read_b128 v[196:199], v216 offset:2048
	ds_read_b128 v[200:203], v216 offset:3072
	ds_read_b128 v[204:207], v216 offset:4096
	ds_read_b128 v[208:211], v216 offset:5120
	ds_read_b128 v[218:221], v216 offset:6144
	ds_read_b128 v[222:225], v216 offset:7168
	global_load_lds_dwordx4 v[176:177], off
	v_lshl_add_u64 v[176:177], v[166:167], 0, s[48:49]
	s_add_i32 m0, s19, 0xe000
	s_nop 0
	global_load_lds_dwordx4 v[176:177], off
	s_waitcnt vmcnt(8)
	s_waitcnt lgkmcnt(0)
	s_barrier
	s_nop 0
	s_waitcnt lgkmcnt(0)
	v_mfma_scale_f32_16x16x128_f8f6f4 v[160:163], v[20:27], v[188:195], v[160:163], v212, v212 op_sel_hi:[0,0,0]
	v_mfma_scale_f32_16x16x128_f8f6f4 v[156:159], v[28:35], v[188:195], v[156:159], v212, v212 op_sel_hi:[0,0,0]
	v_mfma_scale_f32_16x16x128_f8f6f4 v[144:147], v[20:27], v[196:203], v[144:147], v212, v212 op_sel_hi:[0,0,0]
	v_mfma_scale_f32_16x16x128_f8f6f4 v[140:143], v[28:35], v[196:203], v[140:143], v212, v212 op_sel_hi:[0,0,0]
	v_mfma_scale_f32_16x16x128_f8f6f4 v[128:131], v[20:27], v[204:211], v[128:131], v212, v212 op_sel_hi:[0,0,0]
	v_mfma_scale_f32_16x16x128_f8f6f4 v[124:127], v[28:35], v[204:211], v[124:127], v212, v212 op_sel_hi:[0,0,0]
	v_mfma_scale_f32_16x16x128_f8f6f4 v[112:115], v[20:27], v[218:225], v[112:115], v212, v212 op_sel_hi:[0,0,0]
	v_mfma_scale_f32_16x16x128_f8f6f4 v[108:111], v[28:35], v[218:225], v[108:111], v212, v212 op_sel_hi:[0,0,0]
	s_nop 0
	s_nop 0
	v_mfma_scale_f32_16x16x128_f8f6f4 v[152:155], v[4:11], v[188:195], v[152:155], v212, v212 op_sel_hi:[0,0,0]
	v_mfma_scale_f32_16x16x128_f8f6f4 v[148:151], v[12:19], v[188:195], v[148:151], v212, v212 op_sel_hi:[0,0,0]
	v_mfma_scale_f32_16x16x128_f8f6f4 v[136:139], v[4:11], v[196:203], v[136:139], v212, v212 op_sel_hi:[0,0,0]
	v_mfma_scale_f32_16x16x128_f8f6f4 v[132:135], v[12:19], v[196:203], v[132:135], v212, v212 op_sel_hi:[0,0,0]
	v_mfma_scale_f32_16x16x128_f8f6f4 v[120:123], v[4:11], v[204:211], v[120:123], v212, v212 op_sel_hi:[0,0,0]
	v_mfma_scale_f32_16x16x128_f8f6f4 v[116:119], v[12:19], v[204:211], v[116:119], v212, v212 op_sel_hi:[0,0,0]
	v_mfma_scale_f32_16x16x128_f8f6f4 v[104:107], v[4:11], v[218:225], v[104:107], v212, v212 op_sel_hi:[0,0,0]
	v_mfma_scale_f32_16x16x128_f8f6f4 v[100:103], v[12:19], v[218:225], v[100:103], v212, v212 op_sel_hi:[0,0,0]
	s_nop 0
	s_barrier
	s_add_i32 s25, s25, s18
	v_lshl_add_u64 v[176:177], s[60:61], 0, v[2:3]
	s_mov_b32 m0, s25
	ds_read_b128 v[188:191], v216 offset:16384
	ds_read_b128 v[192:195], v216 offset:17408
	ds_read_b128 v[196:199], v216 offset:18432
	ds_read_b128 v[200:203], v216 offset:19456
	ds_read_b128 v[204:207], v216 offset:20480
	ds_read_b128 v[208:211], v216 offset:21504
	ds_read_b128 v[218:221], v216 offset:22528
	ds_read_b128 v[222:225], v216 offset:23552
	global_load_lds_dwordx4 v[176:177], off
	s_add_i32 m0, s25, 0x2000
	v_lshl_add_u64 v[176:177], s[60:61], 0, v[172:173]
	s_add_u32 s60, s60, 0xb0000
	s_addc_u32 s61, s61, 0
	s_add_i32 s25, s30, s18
	global_load_lds_dwordx4 v[176:177], off
	v_lshl_add_u64 v[176:177], s[60:61], 0, v[2:3]
	s_mov_b32 m0, s25
	s_nop 0
	global_load_lds_dwordx4 v[176:177], off
	v_lshl_add_u64 v[176:177], s[60:61], 0, v[172:173]
	s_add_i32 m0, s25, 0x2000
	s_nop 0
	global_load_lds_dwordx4 v[176:177], off
	v_lshl_add_u64 v[176:177], s[58:59], 0, v[168:169]
	s_mov_b32 m0, s19
	s_nop 0
	global_load_lds_dwordx4 v[176:177], off
	v_lshl_add_u64 v[176:177], s[58:59], 0, v[170:171]
	s_mov_b32 m0, s29
	s_nop 0
	global_load_lds_dwordx4 v[176:177], off
	s_waitcnt vmcnt(8)
	s_waitcnt lgkmcnt(0)
	s_barrier
	s_nop 0
	s_waitcnt lgkmcnt(0)
	v_mfma_scale_f32_16x16x128_f8f6f4 v[96:99], v[20:27], v[188:195], v[96:99], v212, v212 op_sel_hi:[0,0,0]
	v_mfma_scale_f32_16x16x128_f8f6f4 v[92:95], v[28:35], v[188:195], v[92:95], v212, v212 op_sel_hi:[0,0,0]
	v_mfma_scale_f32_16x16x128_f8f6f4 v[80:83], v[20:27], v[196:203], v[80:83], v212, v212 op_sel_hi:[0,0,0]
	v_mfma_scale_f32_16x16x128_f8f6f4 v[76:79], v[28:35], v[196:203], v[76:79], v212, v212 op_sel_hi:[0,0,0]
	v_mfma_scale_f32_16x16x128_f8f6f4 v[64:67], v[20:27], v[204:211], v[64:67], v212, v212 op_sel_hi:[0,0,0]
	v_mfma_scale_f32_16x16x128_f8f6f4 v[60:63], v[28:35], v[204:211], v[60:63], v212, v212 op_sel_hi:[0,0,0]
	v_mfma_scale_f32_16x16x128_f8f6f4 v[48:51], v[20:27], v[218:225], v[48:51], v212, v212 op_sel_hi:[0,0,0]
	v_mfma_scale_f32_16x16x128_f8f6f4 v[44:47], v[28:35], v[218:225], v[44:47], v212, v212 op_sel_hi:[0,0,0]
	s_nop 0
	s_nop 0
	v_mfma_scale_f32_16x16x128_f8f6f4 v[88:91], v[4:11], v[188:195], v[88:91], v212, v212 op_sel_hi:[0,0,0]
	v_mfma_scale_f32_16x16x128_f8f6f4 v[84:87], v[12:19], v[188:195], v[84:87], v212, v212 op_sel_hi:[0,0,0]
	v_mfma_scale_f32_16x16x128_f8f6f4 v[72:75], v[4:11], v[196:203], v[72:75], v212, v212 op_sel_hi:[0,0,0]
	v_mfma_scale_f32_16x16x128_f8f6f4 v[68:71], v[12:19], v[196:203], v[68:71], v212, v212 op_sel_hi:[0,0,0]
	v_mfma_scale_f32_16x16x128_f8f6f4 v[56:59], v[4:11], v[204:211], v[56:59], v212, v212 op_sel_hi:[0,0,0]
	v_mfma_scale_f32_16x16x128_f8f6f4 v[52:55], v[12:19], v[204:211], v[52:55], v212, v212 op_sel_hi:[0,0,0]
	v_mfma_scale_f32_16x16x128_f8f6f4 v[40:43], v[4:11], v[218:225], v[40:43], v212, v212 op_sel_hi:[0,0,0]
	v_mfma_scale_f32_16x16x128_f8f6f4 v[36:39], v[12:19], v[218:225], v[36:39], v212, v212 op_sel_hi:[0,0,0]
	s_nop 0
	s_barrier
; #define G_STAGE(bufoff, gbase, voff) do { _Pragma("unroll") for (int _i = 0; _i < 2; ++_i) \
;         __builtin_amdgcn_global_load_lds((const unsigned*)((const char*)(gbase) + (voff)[_i]), (LAS unsigned*)(lds + (bufoff) + ldsw + _i * 8192), 16, 0, 0); } while (0)
; #define G_LDA(dst, b, h) do { _Pragma("unroll") for (int m = 0; m < 4; ++m) { const i32x4 _p0 = *(const LAS i32x4*)(lds + G_SA(b, h) + aoff + m * 2048), _p1 = *(const LAS i32x4*)(lds + G_SA(b, h) + aoff + m * 2048 + 1024); \
;         dst[m] = __builtin_shufflevector(_p0, _p1, 0, 1, 2, 3, 4, 5, 6, 7); } } while (0)
; #define G_LDB(dst, b, h) do { _Pragma("unroll") for (int n = 0; n < 2; ++n) { const i32x4 _p0 = *(const LAS i32x4*)(lds + G_SB(b, h) + boff + n * 2048), _p1 = *(const LAS i32x4*)(lds + G_SB(b, h) + boff + n * 2048 + 1024); \
;         dst[n] = __builtin_shufflevector(_p0, _p1, 0, 1, 2, 3, 4, 5, 6, 7); } } while (0)
; #define G_WAIT_V(n) asm volatile("s_waitcnt vmcnt(" #n ")" ::: "memory")
; #define G_WAIT_L(n) asm volatile("s_waitcnt lgkmcnt(" #n ")" ::: "memory")
; #define G_BAR __builtin_amdgcn_s_barrier()
; #define G_SCHED __builtin_amdgcn_sched_barrier(0)
; template <int NS, int MODE  , class Epi>
; __device__ __forceinline__ void gemm_phase(LAS unsigned char* lds, const Gemm g, const StaticOrder& S, const Epi& E) {
;     ...
;             G_LDB(B0, 1, 0); G_LDB(B1, 1, 1); G_SCHED; G_LDA(At, 1, 0); G_STAGE(G_SA(0, 1), a2 + hstep, voffA);
;             G_WAIT_V(8); G_WAIT_L(0); G_BAR; G_MMA(0, 0, At, B0); G_MMA(0, 1, At, B1); G_BAR; G_SCHED;
;             G_LDA(At, 1, 1); G_STAGE(G_SB(1, 0), b3, voffB); G_STAGE(G_SB(1, 1), b3 + hstep, voffB); G_STAGE(G_SA(1, 0), a3, voffA);
;             G_WAIT_V(8); G_WAIT_L(0); G_BAR; G_MMA(1, 0, At, B0); G_MMA(1, 1, At, B1); G_BAR; G_SCHED;
	s_add_i32 s25, 0, 0x18000
	s_add_i32 s35, 0, 0x1c000
	v_add_u32_e32 v16, s25, v214
	v_add_u32_e32 v32, s35, v214
	ds_read_b128 v[4:7], v16
	ds_read_b128 v[8:11], v16 offset:1024
	ds_read_b128 v[12:15], v16 offset:2048
	ds_read_b128 v[16:19], v16 offset:3072
	ds_read_b128 v[20:23], v32
	ds_read_b128 v[24:27], v32 offset:1024
	ds_read_b128 v[28:31], v32 offset:2048
	ds_read_b128 v[32:35], v32 offset:3072
	s_add_u32 s30, s58, 0xb0000
	s_addc_u32 s31, s59, 0
	s_mov_b32 m0, s56
	v_lshl_add_u64 v[176:177], s[30:31], 0, v[168:169]
	ds_read_b128 v[188:191], v216 offset:32768
	ds_read_b128 v[192:195], v216 offset:33792
	ds_read_b128 v[196:199], v216 offset:34816
	ds_read_b128 v[200:203], v216 offset:35840
	ds_read_b128 v[204:207], v216 offset:36864
	ds_read_b128 v[208:211], v216 offset:37888
	ds_read_b128 v[218:221], v216 offset:38912
	ds_read_b128 v[222:225], v216 offset:39936
	global_load_lds_dwordx4 v[176:177], off
	v_lshl_add_u64 v[176:177], s[30:31], 0, v[170:171]
	s_mov_b32 m0, s62
	s_nop 0
	global_load_lds_dwordx4 v[176:177], off
	s_waitcnt vmcnt(8)
	s_waitcnt lgkmcnt(0)
	s_barrier
	s_nop 0
	s_waitcnt lgkmcnt(0)
	v_mfma_scale_f32_16x16x128_f8f6f4 v[160:163], v[4:11], v[188:195], v[160:163], v212, v212 op_sel_hi:[0,0,0]
	v_mfma_scale_f32_16x16x128_f8f6f4 v[156:159], v[12:19], v[188:195], v[156:159], v212, v212 op_sel_hi:[0,0,0]
	v_mfma_scale_f32_16x16x128_f8f6f4 v[144:147], v[4:11], v[196:203], v[144:147], v212, v212 op_sel_hi:[0,0,0]
	v_mfma_scale_f32_16x16x128_f8f6f4 v[140:143], v[12:19], v[196:203], v[140:143], v212, v212 op_sel_hi:[0,0,0]
	v_mfma_scale_f32_16x16x128_f8f6f4 v[128:131], v[4:11], v[204:211], v[128:131], v212, v212 op_sel_hi:[0,0,0]
	v_mfma_scale_f32_16x16x128_f8f6f4 v[124:127], v[12:19], v[204:211], v[124:127], v212, v212 op_sel_hi:[0,0,0]
	v_mfma_scale_f32_16x16x128_f8f6f4 v[112:115], v[4:11], v[218:225], v[112:115], v212, v212 op_sel_hi:[0,0,0]
	v_mfma_scale_f32_16x16x128_f8f6f4 v[108:111], v[12:19], v[218:225], v[108:111], v212, v212 op_sel_hi:[0,0,0]
	s_nop 0
	s_nop 0
	v_mfma_scale_f32_16x16x128_f8f6f4 v[152:155], v[20:27], v[188:195], v[152:155], v212, v212 op_sel_hi:[0,0,0]
	v_mfma_scale_f32_16x16x128_f8f6f4 v[148:151], v[28:35], v[188:195], v[148:151], v212, v212 op_sel_hi:[0,0,0]
	v_mfma_scale_f32_16x16x128_f8f6f4 v[136:139], v[20:27], v[196:203], v[136:139], v212, v212 op_sel_hi:[0,0,0]
	v_mfma_scale_f32_16x16x128_f8f6f4 v[132:135], v[28:35], v[196:203], v[132:135], v212, v212 op_sel_hi:[0,0,0]
	v_mfma_scale_f32_16x16x128_f8f6f4 v[120:123], v[20:27], v[204:211], v[120:123], v212, v212 op_sel_hi:[0,0,0]
	v_mfma_scale_f32_16x16x128_f8f6f4 v[116:119], v[28:35], v[204:211], v[116:119], v212, v212 op_sel_hi:[0,0,0]
	v_mfma_scale_f32_16x16x128_f8f6f4 v[104:107], v[20:27], v[218:225], v[104:107], v212, v212 op_sel_hi:[0,0,0]
	v_mfma_scale_f32_16x16x128_f8f6f4 v[100:103], v[28:35], v[218:225], v[100:103], v212, v212 op_sel_hi:[0,0,0]
	s_nop 0
	s_barrier
	s_add_i32 s25, s25, s18
	v_lshl_add_u64 v[176:177], s[54:55], 0, v[2:3]
	s_mov_b32 m0, s25
	ds_read_b128 v[188:191], v216 offset:49152
	ds_read_b128 v[192:195], v216 offset:50176
	ds_read_b128 v[196:199], v216 offset:51200
	ds_read_b128 v[200:203], v216 offset:52224
	ds_read_b128 v[204:207], v216 offset:53248
	ds_read_b128 v[208:211], v216 offset:54272
	ds_read_b128 v[218:221], v216 offset:55296
	ds_read_b128 v[222:225], v216 offset:56320
	global_load_lds_dwordx4 v[176:177], off
	s_add_i32 m0, s25, 0x2000
	s_add_u32 s30, s54, 0xb0000
	v_lshl_add_u64 v[176:177], s[54:55], 0, v[172:173]
	s_addc_u32 s31, s55, 0
	s_add_i32 s25, s35, s18
	global_load_lds_dwordx4 v[176:177], off
	v_lshl_add_u64 v[176:177], s[30:31], 0, v[2:3]
	s_mov_b32 m0, s25
	s_nop 0
	global_load_lds_dwordx4 v[176:177], off
	v_lshl_add_u64 v[176:177], s[30:31], 0, v[172:173]
	s_add_i32 m0, s25, 0x2000
	s_nop 0
	global_load_lds_dwordx4 v[176:177], off
	v_lshl_add_u64 v[176:177], s[52:53], 0, v[168:169]
	s_mov_b32 m0, s65
	s_nop 0
	global_load_lds_dwordx4 v[176:177], off
	v_lshl_add_u64 v[176:177], s[52:53], 0, v[170:171]
	s_mov_b32 m0, s66
	s_nop 0
	global_load_lds_dwordx4 v[176:177], off
	s_waitcnt vmcnt(8)
	s_waitcnt lgkmcnt(0)
	s_barrier
	s_nop 0
	s_waitcnt lgkmcnt(0)
	v_mfma_scale_f32_16x16x128_f8f6f4 v[96:99], v[4:11], v[188:195], v[96:99], v212, v212 op_sel_hi:[0,0,0]
	v_mfma_scale_f32_16x16x128_f8f6f4 v[92:95], v[12:19], v[188:195], v[92:95], v212, v212 op_sel_hi:[0,0,0]
	v_mfma_scale_f32_16x16x128_f8f6f4 v[80:83], v[4:11], v[196:203], v[80:83], v212, v212 op_sel_hi:[0,0,0]
	v_mfma_scale_f32_16x16x128_f8f6f4 v[76:79], v[12:19], v[196:203], v[76:79], v212, v212 op_sel_hi:[0,0,0]
	v_mfma_scale_f32_16x16x128_f8f6f4 v[64:67], v[4:11], v[204:211], v[64:67], v212, v212 op_sel_hi:[0,0,0]
	v_mfma_scale_f32_16x16x128_f8f6f4 v[60:63], v[12:19], v[204:211], v[60:63], v212, v212 op_sel_hi:[0,0,0]
	v_mfma_scale_f32_16x16x128_f8f6f4 v[48:51], v[4:11], v[218:225], v[48:51], v212, v212 op_sel_hi:[0,0,0]
	v_mfma_scale_f32_16x16x128_f8f6f4 v[44:47], v[12:19], v[218:225], v[44:47], v212, v212 op_sel_hi:[0,0,0]
	s_nop 0
	s_nop 0
	v_mfma_scale_f32_16x16x128_f8f6f4 v[88:91], v[20:27], v[188:195], v[88:91], v212, v212 op_sel_hi:[0,0,0]
	v_mfma_scale_f32_16x16x128_f8f6f4 v[84:87], v[28:35], v[188:195], v[84:87], v212, v212 op_sel_hi:[0,0,0]
	v_mfma_scale_f32_16x16x128_f8f6f4 v[72:75], v[20:27], v[196:203], v[72:75], v212, v212 op_sel_hi:[0,0,0]
	v_mfma_scale_f32_16x16x128_f8f6f4 v[68:71], v[28:35], v[196:203], v[68:71], v212, v212 op_sel_hi:[0,0,0]
	v_mfma_scale_f32_16x16x128_f8f6f4 v[56:59], v[20:27], v[204:211], v[56:59], v212, v212 op_sel_hi:[0,0,0]
	v_mfma_scale_f32_16x16x128_f8f6f4 v[52:55], v[28:35], v[204:211], v[52:55], v212, v212 op_sel_hi:[0,0,0]
	v_mfma_scale_f32_16x16x128_f8f6f4 v[40:43], v[20:27], v[218:225], v[40:43], v212, v212 op_sel_hi:[0,0,0]
	v_mfma_scale_f32_16x16x128_f8f6f4 v[36:39], v[28:35], v[218:225], v[36:39], v212, v212 op_sel_hi:[0,0,0]
	s_nop 0
	s_barrier
	s_add_i32 s24, s24, 2
	s_add_u32 s48, s48, 0x100
	s_addc_u32 s49, s49, 0
	s_cmp_gt_u32 s24, 41
	s_cbranch_scc1 .LBB0_1360
